# k9 plus: back-to-back s_setprio 0/1 pair between the two MFMA blocks of each segment removed
# baseline (speedup 1.0000x reference)
; #define PG8_STAGE(bufoff, gbase, voff) do { _Pragma("unroll") for (int _i = 0; _i < 2; ++_i) \
;         { unsigned _vo = (voff)[_i]; asm volatile("" : "+v"(_vo));     \
;         __builtin_amdgcn_global_load_lds((const unsigned*)((const char*)(gbase) + _vo), (PG8_LAS unsigned*)(lds + (bufoff) + ldsw + _i * 8192), 16, 0, 0); } } while (0)
; #define PG8_LDA(dst, b, h) do { _Pragma("unroll") for (int m = 0; m < 4; ++m) _Pragma("unroll") for (int k = 0; k < 2; ++k) dst[m][k] = *(const PG8_LAS bf16x8*)(lds + PG8_SA(b, h) + aoff + m * 2048 + k * 1024); } while (0)
; #define PG8_LDB(dst, b, h) do { _Pragma("unroll") for (int n = 0; n < 2; ++n) _Pragma("unroll") for (int k = 0; k < 2; ++k) dst[n][k] = *(const PG8_LAS bf16x8*)(lds + PG8_SB(b, h) + boff + n * 2048 + k * 1024); } while (0)
; #define PG8_WAIT_V(n) asm volatile("s_waitcnt vmcnt(" #n ")" ::: "memory")
; #define PG8_WAIT_L(n) asm volatile("s_waitcnt lgkmcnt(" #n ")" ::: "memory")
; #define PG8_BAR __builtin_amdgcn_s_barrier()
; #define PG8_SCHED __builtin_amdgcn_sched_barrier(0)
; template <class Epi, class Sched, bool ALIGN_EPI = false, bool SP2 = false, bool ABLK = false, bool F8 = false>
; __device__ __forceinline__ void gemm_phase(PG8_LAS unsigned char* lds, const Gemm g, const Sched& S, const Epi& E, const int wave_s) {
;     ...
;             const bool last = (t == nt - 2);
;             const char* a1 = cA + (size_t)(t + 1) * kstepA;
;             const char* a2 = last ? nA : cA + (size_t)(t + 2) * kstepA; const char* b2 = last ? nB : cB + (size_t)(t + 2) * kstep;
;             const char* a3 = a2 + kstepA; const char* b3 = b2 + kstep;
;             if (last && has_next) { S.a_ready(nxt); if constexpr (Epi::PREF) E.prefetch(nxt, wid, lane); }
;             if constexpr (SP2) {
;             PG8_LDB(B0, 0, 0); PG8_LDB(B1, 0, 1); PG8_SCHED; PG8_LDA(At, 0, 0); PG8_STAGE(PG8_SA(1, 1), a1 + hstepA, voffA);
;             PG8_WAIT_V(8); PG8_WAIT_L(0); PG8_BAR; PG8_MMA(0, 0, At, B0); PG8_MMA(0, 1, At, B1); PG8_BAR; PG8_SCHED;
;             PG8_LDA(At, 0, 1); PG8_STAGE(PG8_SB(0, 0), b2, voffB); PG8_STAGE(PG8_SB(0, 1), b2 + hstep, voffB); PG8_STAGE(PG8_SA(0, 0), a2, voffA);
;             PG8_WAIT_V(8); PG8_WAIT_L(0); PG8_BAR; PG8_MMA(1, 0, At, B0); PG8_MMA(1, 1, At, B1); PG8_BAR; PG8_SCHED;
.LBB0_223:
	v_add_u32_e32 v128, s64, v160
	ds_read_b128 v[166:169], v128
	ds_read_b128 v[170:173], v128 offset:1024
	ds_read_b128 v[174:177], v128 offset:2048
	ds_read_b128 v[178:181], v128 offset:3072
	v_add_u32_e32 v128, s65, v160
	ds_read_b128 v[182:185], v128
	ds_read_b128 v[186:189], v128 offset:1024
	ds_read_b128 v[190:193], v128 offset:2048
	ds_read_b128 v[194:197], v128 offset:3072
	s_add_u32 s62, s58, 0xfff80080
	s_addc_u32 s63, s59, -1
	s_and_b64 s[60:61], s[60:61], exec
	s_cselect_b32 s61, s63, s49
	s_cselect_b32 s60, s62, s77
	s_cselect_b32 s63, s80, s17
	s_cselect_b32 s62, s79, s78
	ds_read_b128 v[198:201], v163
	ds_read_b128 v[202:205], v163 offset:1024
	ds_read_b128 v[206:209], v163 offset:2048
	ds_read_b128 v[210:213], v163 offset:3072
	ds_read_b128 v[214:217], v163 offset:4096
	ds_read_b128 v[218:221], v163 offset:5120
	ds_read_b128 v[222:225], v163 offset:6144
	ds_read_b128 v[230:233], v163 offset:7168
	s_add_i32 m0, s22, 0xc000
	s_nop 0
	global_load_lds_dwordx4 v156, s[58:59]
	s_add_i32 m0, s22, 0xe000
	s_nop 0
	global_load_lds_dwordx4 v158, s[58:59]
	s_waitcnt vmcnt(8)
	s_waitcnt lgkmcnt(0)
	s_barrier
	s_setprio 1
	s_waitcnt lgkmcnt(0)
	v_mfma_f32_16x16x32_bf16 v[124:127], v[166:169], v[198:201], v[124:127]
	v_mfma_f32_16x16x32_bf16 v[116:119], v[174:177], v[198:201], v[116:119]
	v_mfma_f32_16x16x32_bf16 v[108:111], v[166:169], v[206:209], v[108:111]
	v_mfma_f32_16x16x32_bf16 v[100:103], v[174:177], v[206:209], v[100:103]
	v_mfma_f32_16x16x32_bf16 v[92:95], v[166:169], v[214:217], v[92:95]
	v_mfma_f32_16x16x32_bf16 v[84:87], v[174:177], v[214:217], v[84:87]
	v_mfma_f32_16x16x32_bf16 v[76:79], v[166:169], v[222:225], v[76:79]
	v_mfma_f32_16x16x32_bf16 v[68:71], v[174:177], v[222:225], v[68:71]
	v_mfma_f32_16x16x32_bf16 v[124:127], v[170:173], v[202:205], v[124:127]
	v_mfma_f32_16x16x32_bf16 v[116:119], v[178:181], v[202:205], v[116:119]
	v_mfma_f32_16x16x32_bf16 v[108:111], v[170:173], v[210:213], v[108:111]
	v_mfma_f32_16x16x32_bf16 v[100:103], v[178:181], v[210:213], v[100:103]
	v_mfma_f32_16x16x32_bf16 v[92:95], v[170:173], v[218:221], v[92:95]
	v_mfma_f32_16x16x32_bf16 v[84:87], v[178:181], v[218:221], v[84:87]
	v_mfma_f32_16x16x32_bf16 v[76:79], v[170:173], v[230:233], v[76:79]
	v_mfma_f32_16x16x32_bf16 v[68:71], v[178:181], v[230:233], v[68:71]
	v_mfma_f32_16x16x32_bf16 v[120:123], v[182:185], v[198:201], v[120:123]
	v_mfma_f32_16x16x32_bf16 v[112:115], v[190:193], v[198:201], v[112:115]
	v_mfma_f32_16x16x32_bf16 v[104:107], v[182:185], v[206:209], v[104:107]
	v_mfma_f32_16x16x32_bf16 v[96:99], v[190:193], v[206:209], v[96:99]
	v_mfma_f32_16x16x32_bf16 v[88:91], v[182:185], v[214:217], v[88:91]
	v_mfma_f32_16x16x32_bf16 v[80:83], v[190:193], v[214:217], v[80:83]
	v_mfma_f32_16x16x32_bf16 v[72:75], v[182:185], v[222:225], v[72:75]
	v_mfma_f32_16x16x32_bf16 v[64:67], v[190:193], v[222:225], v[64:67]
	v_mfma_f32_16x16x32_bf16 v[120:123], v[186:189], v[202:205], v[120:123]
	v_mfma_f32_16x16x32_bf16 v[112:115], v[194:197], v[202:205], v[112:115]
	v_mfma_f32_16x16x32_bf16 v[104:107], v[186:189], v[210:213], v[104:107]
	v_mfma_f32_16x16x32_bf16 v[96:99], v[194:197], v[210:213], v[96:99]
	v_mfma_f32_16x16x32_bf16 v[88:91], v[186:189], v[218:221], v[88:91]
	v_mfma_f32_16x16x32_bf16 v[80:83], v[194:197], v[218:221], v[80:83]
	v_mfma_f32_16x16x32_bf16 v[72:75], v[186:189], v[230:233], v[72:75]
	v_mfma_f32_16x16x32_bf16 v[64:67], v[194:197], v[230:233], v[64:67]
	s_setprio 0
	s_barrier
	s_add_i32 s72, s64, s3
	ds_read_b128 v[198:201], v163 offset:16384
	ds_read_b128 v[202:205], v163 offset:17408
	ds_read_b128 v[206:209], v163 offset:18432
	ds_read_b128 v[210:213], v163 offset:19456
	ds_read_b128 v[214:217], v163 offset:20480
	ds_read_b128 v[218:221], v163 offset:21504
	ds_read_b128 v[222:225], v163 offset:22528
	ds_read_b128 v[230:233], v163 offset:23552
	s_mov_b32 m0, s72
	s_nop 0
	global_load_lds_dwordx4 v157, s[62:63]
	s_add_i32 m0, s72, 0x2000
	s_add_u32 s72, s62, 0x80000
	global_load_lds_dwordx4 v159, s[62:63]
	s_addc_u32 s73, s63, 0
	s_add_i32 s83, s65, s3
	s_mov_b32 m0, s83
	s_nop 0
	global_load_lds_dwordx4 v157, s[72:73]
	s_add_i32 m0, s83, 0x2000
	s_nop 0
	global_load_lds_dwordx4 v159, s[72:73]
	s_mov_b32 m0, s22
	s_nop 0
	global_load_lds_dwordx4 v156, s[60:61]
	s_mov_b32 m0, s23
	s_nop 0
	global_load_lds_dwordx4 v158, s[60:61]
	s_waitcnt vmcnt(8)
	s_waitcnt lgkmcnt(0)
	s_barrier
	s_setprio 1
	s_waitcnt lgkmcnt(0)
	v_mfma_f32_16x16x32_bf16 v[60:63], v[166:169], v[198:201], v[60:63]
	v_mfma_f32_16x16x32_bf16 v[52:55], v[174:177], v[198:201], v[52:55]
	v_mfma_f32_16x16x32_bf16 v[44:47], v[166:169], v[206:209], v[44:47]
	v_mfma_f32_16x16x32_bf16 v[36:39], v[174:177], v[206:209], v[36:39]
	v_mfma_f32_16x16x32_bf16 v[28:31], v[166:169], v[214:217], v[28:31]
	v_mfma_f32_16x16x32_bf16 v[20:23], v[174:177], v[214:217], v[20:23]
	v_mfma_f32_16x16x32_bf16 v[12:15], v[166:169], v[222:225], v[12:15]
	v_mfma_f32_16x16x32_bf16 v[4:7], v[174:177], v[222:225], v[4:7]
	v_mfma_f32_16x16x32_bf16 v[60:63], v[170:173], v[202:205], v[60:63]
	v_mfma_f32_16x16x32_bf16 v[52:55], v[178:181], v[202:205], v[52:55]
	v_mfma_f32_16x16x32_bf16 v[44:47], v[170:173], v[210:213], v[44:47]
	v_mfma_f32_16x16x32_bf16 v[36:39], v[178:181], v[210:213], v[36:39]
	v_mfma_f32_16x16x32_bf16 v[28:31], v[170:173], v[218:221], v[28:31]
	v_mfma_f32_16x16x32_bf16 v[20:23], v[178:181], v[218:221], v[20:23]
	v_mfma_f32_16x16x32_bf16 v[12:15], v[170:173], v[230:233], v[12:15]
	v_mfma_f32_16x16x32_bf16 v[4:7], v[178:181], v[230:233], v[4:7]
	v_mfma_f32_16x16x32_bf16 v[56:59], v[182:185], v[198:201], v[56:59]
	v_mfma_f32_16x16x32_bf16 v[48:51], v[190:193], v[198:201], v[48:51]
	v_mfma_f32_16x16x32_bf16 v[40:43], v[182:185], v[206:209], v[40:43]
	v_mfma_f32_16x16x32_bf16 v[32:35], v[190:193], v[206:209], v[32:35]
	v_mfma_f32_16x16x32_bf16 v[24:27], v[182:185], v[214:217], v[24:27]
	v_mfma_f32_16x16x32_bf16 v[16:19], v[190:193], v[214:217], v[16:19]
	v_mfma_f32_16x16x32_bf16 v[8:11], v[182:185], v[222:225], v[8:11]
	v_mfma_f32_16x16x32_bf16 v[0:3], v[190:193], v[222:225], v[0:3]
	v_mfma_f32_16x16x32_bf16 v[56:59], v[186:189], v[202:205], v[56:59]
	v_mfma_f32_16x16x32_bf16 v[48:51], v[194:197], v[202:205], v[48:51]
	v_mfma_f32_16x16x32_bf16 v[40:43], v[186:189], v[210:213], v[40:43]
	v_mfma_f32_16x16x32_bf16 v[32:35], v[194:197], v[210:213], v[32:35]
	v_mfma_f32_16x16x32_bf16 v[24:27], v[186:189], v[218:221], v[24:27]
	v_mfma_f32_16x16x32_bf16 v[16:19], v[194:197], v[218:221], v[16:19]
	v_mfma_f32_16x16x32_bf16 v[8:11], v[186:189], v[230:233], v[8:11]
	v_mfma_f32_16x16x32_bf16 v[0:3], v[194:197], v[230:233], v[0:3]
	s_setprio 0
	s_barrier
; #define PG8_STAGE(bufoff, gbase, voff) do { _Pragma("unroll") for (int _i = 0; _i < 2; ++_i) \
;         { unsigned _vo = (voff)[_i]; asm volatile("" : "+v"(_vo));     \
;         __builtin_amdgcn_global_load_lds((const unsigned*)((const char*)(gbase) + _vo), (PG8_LAS unsigned*)(lds + (bufoff) + ldsw + _i * 8192), 16, 0, 0); } } while (0)
; #define PG8_LDA(dst, b, h) do { _Pragma("unroll") for (int m = 0; m < 4; ++m) _Pragma("unroll") for (int k = 0; k < 2; ++k) dst[m][k] = *(const PG8_LAS bf16x8*)(lds + PG8_SA(b, h) + aoff + m * 2048 + k * 1024); } while (0)
; #define PG8_LDB(dst, b, h) do { _Pragma("unroll") for (int n = 0; n < 2; ++n) _Pragma("unroll") for (int k = 0; k < 2; ++k) dst[n][k] = *(const PG8_LAS bf16x8*)(lds + PG8_SB(b, h) + boff + n * 2048 + k * 1024); } while (0)
; #define PG8_WAIT_V(n) asm volatile("s_waitcnt vmcnt(" #n ")" ::: "memory")
; #define PG8_WAIT_L(n) asm volatile("s_waitcnt lgkmcnt(" #n ")" ::: "memory")
; #define PG8_BAR __builtin_amdgcn_s_barrier()
; #define PG8_SCHED __builtin_amdgcn_sched_barrier(0)
; template <class Epi, class Sched, bool ALIGN_EPI = false, bool SP2 = false, bool ABLK = false, bool F8 = false>
; __device__ __forceinline__ void gemm_phase(PG8_LAS unsigned char* lds, const Gemm g, const Sched& S, const Epi& E, const int wave_s) {
;     ...
;             PG8_LDB(B0, 1, 0); PG8_LDB(B1, 1, 1); PG8_SCHED; PG8_LDA(At, 1, 0); PG8_STAGE(PG8_SA(0, 1), a2 + hstepA, voffA);
;             PG8_WAIT_V(8); PG8_WAIT_L(0); PG8_BAR; PG8_MMA(0, 0, At, B0); PG8_MMA(0, 1, At, B1); PG8_BAR; PG8_SCHED;
;             PG8_LDA(At, 1, 1); PG8_STAGE(PG8_SB(1, 0), b3, voffB); PG8_STAGE(PG8_SB(1, 1), b3 + hstep, voffB); PG8_STAGE(PG8_SA(1, 0), a3, voffA);
;             PG8_WAIT_V(8); PG8_WAIT_L(0); PG8_BAR; PG8_MMA(1, 0, At, B0); PG8_MMA(1, 1, At, B1); PG8_BAR; PG8_SCHED;
	s_add_i32 s83, 0, 0x18000
	v_add_u32_e32 v128, s83, v160
	s_add_i32 s84, 0, 0x1c000
	ds_read_b128 v[166:169], v128
	ds_read_b128 v[170:173], v128 offset:1024
	ds_read_b128 v[174:177], v128 offset:2048
	ds_read_b128 v[178:181], v128 offset:3072
	v_add_u32_e32 v128, s84, v160
	ds_read_b128 v[182:185], v128
	ds_read_b128 v[186:189], v128 offset:1024
	ds_read_b128 v[190:193], v128 offset:2048
	ds_read_b128 v[194:197], v128 offset:3072
	s_add_u32 s72, s60, 0x80000
	s_mov_b32 m0, s46
	ds_read_b128 v[198:201], v163 offset:32768
	ds_read_b128 v[202:205], v163 offset:33792
	ds_read_b128 v[206:209], v163 offset:34816
	ds_read_b128 v[210:213], v163 offset:35840
	ds_read_b128 v[214:217], v163 offset:36864
	ds_read_b128 v[218:221], v163 offset:37888
	ds_read_b128 v[222:225], v163 offset:38912
	ds_read_b128 v[230:233], v163 offset:39936
	s_addc_u32 s73, s61, 0
	s_nop 0
	global_load_lds_dwordx4 v156, s[72:73]
	s_mov_b32 m0, s47
	s_nop 0
	global_load_lds_dwordx4 v158, s[72:73]
	s_waitcnt vmcnt(8)
	s_waitcnt lgkmcnt(0)
	s_barrier
	s_setprio 1
	s_waitcnt lgkmcnt(0)
	v_mfma_f32_16x16x32_bf16 v[124:127], v[166:169], v[198:201], v[124:127]
	v_mfma_f32_16x16x32_bf16 v[116:119], v[174:177], v[198:201], v[116:119]
	v_mfma_f32_16x16x32_bf16 v[108:111], v[166:169], v[206:209], v[108:111]
	v_mfma_f32_16x16x32_bf16 v[100:103], v[174:177], v[206:209], v[100:103]
	v_mfma_f32_16x16x32_bf16 v[92:95], v[166:169], v[214:217], v[92:95]
	v_mfma_f32_16x16x32_bf16 v[84:87], v[174:177], v[214:217], v[84:87]
	v_mfma_f32_16x16x32_bf16 v[76:79], v[166:169], v[222:225], v[76:79]
	v_mfma_f32_16x16x32_bf16 v[68:71], v[174:177], v[222:225], v[68:71]
	v_mfma_f32_16x16x32_bf16 v[124:127], v[170:173], v[202:205], v[124:127]
	v_mfma_f32_16x16x32_bf16 v[116:119], v[178:181], v[202:205], v[116:119]
	v_mfma_f32_16x16x32_bf16 v[108:111], v[170:173], v[210:213], v[108:111]
	v_mfma_f32_16x16x32_bf16 v[100:103], v[178:181], v[210:213], v[100:103]
	v_mfma_f32_16x16x32_bf16 v[92:95], v[170:173], v[218:221], v[92:95]
	v_mfma_f32_16x16x32_bf16 v[84:87], v[178:181], v[218:221], v[84:87]
	v_mfma_f32_16x16x32_bf16 v[76:79], v[170:173], v[230:233], v[76:79]
	v_mfma_f32_16x16x32_bf16 v[68:71], v[178:181], v[230:233], v[68:71]
	v_mfma_f32_16x16x32_bf16 v[120:123], v[182:185], v[198:201], v[120:123]
	v_mfma_f32_16x16x32_bf16 v[112:115], v[190:193], v[198:201], v[112:115]
	v_mfma_f32_16x16x32_bf16 v[104:107], v[182:185], v[206:209], v[104:107]
	v_mfma_f32_16x16x32_bf16 v[96:99], v[190:193], v[206:209], v[96:99]
	v_mfma_f32_16x16x32_bf16 v[88:91], v[182:185], v[214:217], v[88:91]
	v_mfma_f32_16x16x32_bf16 v[80:83], v[190:193], v[214:217], v[80:83]
	v_mfma_f32_16x16x32_bf16 v[72:75], v[182:185], v[222:225], v[72:75]
	v_mfma_f32_16x16x32_bf16 v[64:67], v[190:193], v[222:225], v[64:67]
	v_mfma_f32_16x16x32_bf16 v[120:123], v[186:189], v[202:205], v[120:123]
	v_mfma_f32_16x16x32_bf16 v[112:115], v[194:197], v[202:205], v[112:115]
	v_mfma_f32_16x16x32_bf16 v[104:107], v[186:189], v[210:213], v[104:107]
	v_mfma_f32_16x16x32_bf16 v[96:99], v[194:197], v[210:213], v[96:99]
	v_mfma_f32_16x16x32_bf16 v[88:91], v[186:189], v[218:221], v[88:91]
	v_mfma_f32_16x16x32_bf16 v[80:83], v[194:197], v[218:221], v[80:83]
	v_mfma_f32_16x16x32_bf16 v[72:75], v[186:189], v[230:233], v[72:75]
	v_mfma_f32_16x16x32_bf16 v[64:67], v[194:197], v[230:233], v[64:67]
	s_setprio 0
	s_barrier
	ds_read_b128 v[198:201], v163 offset:49152
	ds_read_b128 v[202:205], v163 offset:50176
	ds_read_b128 v[206:209], v163 offset:51200
	ds_read_b128 v[210:213], v163 offset:52224
	ds_read_b128 v[214:217], v163 offset:53248
	ds_read_b128 v[218:221], v163 offset:54272
	ds_read_b128 v[222:225], v163 offset:55296
	ds_read_b128 v[230:233], v163 offset:56320
	s_add_i32 s72, s83, s3
	s_add_u32 vcc_lo, s62, s14
	s_addc_u32 vcc_hi, s63, s15
	s_mov_b32 m0, s72
	s_nop 0
	global_load_lds_dwordx4 v157, vcc
	s_add_i32 m0, s72, 0x2000
	s_nop 0
	s_add_u32 vcc_lo, s62, s14
	s_addc_u32 vcc_hi, s63, s15
	s_add_u32 s62, s62, 0x80080
	s_addc_u32 s63, s63, 0
	s_add_i32 s72, s84, s3
	global_load_lds_dwordx4 v159, vcc
	s_mov_b32 m0, s72
	s_nop 0
	global_load_lds_dwordx4 v157, s[62:63]
	s_add_i32 m0, s72, 0x2000
	s_nop 0
	global_load_lds_dwordx4 v159, s[62:63]
	s_mov_b32 m0, s55
	s_add_u32 vcc_lo, s60, s14
	s_addc_u32 vcc_hi, s61, s15
	v_mov_b32_e32 v128, v158
	global_load_lds_dwordx4 v156, vcc
	s_mov_b32 m0, s57
	s_add_u32 vcc_lo, s60, s14
	s_addc_u32 vcc_hi, s61, s15
	global_load_lds_dwordx4 v158, vcc
	s_waitcnt vmcnt(8)
	s_waitcnt lgkmcnt(0)
	s_barrier
	s_setprio 1
	s_waitcnt lgkmcnt(0)
	v_mfma_f32_16x16x32_bf16 v[60:63], v[166:169], v[198:201], v[60:63]
	v_mfma_f32_16x16x32_bf16 v[52:55], v[174:177], v[198:201], v[52:55]
	v_mfma_f32_16x16x32_bf16 v[44:47], v[166:169], v[206:209], v[44:47]
	v_mfma_f32_16x16x32_bf16 v[36:39], v[174:177], v[206:209], v[36:39]
	v_mfma_f32_16x16x32_bf16 v[28:31], v[166:169], v[214:217], v[28:31]
	v_mfma_f32_16x16x32_bf16 v[20:23], v[174:177], v[214:217], v[20:23]
	v_mfma_f32_16x16x32_bf16 v[12:15], v[166:169], v[222:225], v[12:15]
	v_mfma_f32_16x16x32_bf16 v[4:7], v[174:177], v[222:225], v[4:7]
	v_mfma_f32_16x16x32_bf16 v[60:63], v[170:173], v[202:205], v[60:63]
	v_mfma_f32_16x16x32_bf16 v[52:55], v[178:181], v[202:205], v[52:55]
	v_mfma_f32_16x16x32_bf16 v[44:47], v[170:173], v[210:213], v[44:47]
	v_mfma_f32_16x16x32_bf16 v[36:39], v[178:181], v[210:213], v[36:39]
	v_mfma_f32_16x16x32_bf16 v[28:31], v[170:173], v[218:221], v[28:31]
	v_mfma_f32_16x16x32_bf16 v[20:23], v[178:181], v[218:221], v[20:23]
	v_mfma_f32_16x16x32_bf16 v[12:15], v[170:173], v[230:233], v[12:15]
	v_mfma_f32_16x16x32_bf16 v[4:7], v[178:181], v[230:233], v[4:7]
	v_mfma_f32_16x16x32_bf16 v[56:59], v[182:185], v[198:201], v[56:59]
	v_mfma_f32_16x16x32_bf16 v[48:51], v[190:193], v[198:201], v[48:51]
	v_mfma_f32_16x16x32_bf16 v[40:43], v[182:185], v[206:209], v[40:43]
	v_mfma_f32_16x16x32_bf16 v[32:35], v[190:193], v[206:209], v[32:35]
	v_mfma_f32_16x16x32_bf16 v[24:27], v[182:185], v[214:217], v[24:27]
	v_mfma_f32_16x16x32_bf16 v[16:19], v[190:193], v[214:217], v[16:19]
	v_mfma_f32_16x16x32_bf16 v[8:11], v[182:185], v[222:225], v[8:11]
	v_mfma_f32_16x16x32_bf16 v[0:3], v[190:193], v[222:225], v[0:3]
	v_mfma_f32_16x16x32_bf16 v[56:59], v[186:189], v[202:205], v[56:59]
	v_mfma_f32_16x16x32_bf16 v[48:51], v[194:197], v[202:205], v[48:51]
	v_mfma_f32_16x16x32_bf16 v[40:43], v[186:189], v[210:213], v[40:43]
	v_mfma_f32_16x16x32_bf16 v[32:35], v[194:197], v[210:213], v[32:35]
	v_mfma_f32_16x16x32_bf16 v[24:27], v[186:189], v[218:221], v[24:27]
	v_mfma_f32_16x16x32_bf16 v[16:19], v[194:197], v[218:221], v[16:19]
	v_mfma_f32_16x16x32_bf16 v[8:11], v[186:189], v[230:233], v[8:11]
	v_mfma_f32_16x16x32_bf16 v[0:3], v[194:197], v[230:233], v[0:3]
	s_setprio 0
	s_barrier
	s_add_i32 s81, s81, 2
	s_add_u32 s58, s58, 0x100
	s_addc_u32 s59, s59, 0
	s_add_u32 s79, s79, 0x100
	s_addc_u32 s80, s80, 0
	s_cmp_gt_u32 s81, 29
	s_cbranch_scc1 .LBB0_226

; #define PG8_STAGE(bufoff, gbase, voff) do { _Pragma("unroll") for (int _i = 0; _i < 2; ++_i) \
;         { unsigned _vo = (voff)[_i]; asm volatile("" : "+v"(_vo));     \
;         __builtin_amdgcn_global_load_lds((const unsigned*)((const char*)(gbase) + _vo), (PG8_LAS unsigned*)(lds + (bufoff) + ldsw + _i * 8192), 16, 0, 0); } } while (0)
; #define PG8_LDA(dst, b, h) do { _Pragma("unroll") for (int m = 0; m < 4; ++m) _Pragma("unroll") for (int k = 0; k < 2; ++k) dst[m][k] = *(const PG8_LAS bf16x8*)(lds + PG8_SA(b, h) + aoff + m * 2048 + k * 1024); } while (0)
; #define PG8_LDB(dst, b, h) do { _Pragma("unroll") for (int n = 0; n < 2; ++n) _Pragma("unroll") for (int k = 0; k < 2; ++k) dst[n][k] = *(const PG8_LAS bf16x8*)(lds + PG8_SB(b, h) + boff + n * 2048 + k * 1024); } while (0)
; #define PG8_WAIT_V(n) asm volatile("s_waitcnt vmcnt(" #n ")" ::: "memory")
; #define PG8_WAIT_L(n) asm volatile("s_waitcnt lgkmcnt(" #n ")" ::: "memory")
; #define PG8_BAR __builtin_amdgcn_s_barrier()
; #define PG8_SCHED __builtin_amdgcn_sched_barrier(0)
; template <class Epi, class Sched, bool ALIGN_EPI = false, bool SP2 = false, bool ABLK = false, bool F8 = false>
; __device__ __forceinline__ void gemm_phase(PG8_LAS unsigned char* lds, const Gemm g, const Sched& S, const Epi& E, const int wave_s) {
;     ...
;             const bool last = (t == nt - 2);
;             const char* a1 = cA + (size_t)(t + 1) * kstepA;
;             const char* a2 = last ? nA : cA + (size_t)(t + 2) * kstepA; const char* b2 = last ? nB : cB + (size_t)(t + 2) * kstep;
;             const char* a3 = a2 + kstepA; const char* b3 = b2 + kstep;
;             if (last && has_next) { S.a_ready(nxt); if constexpr (Epi::PREF) E.prefetch(nxt, wid, lane); }
;             if constexpr (SP2) {
;             PG8_LDB(B0, 0, 0); PG8_LDB(B1, 0, 1); PG8_SCHED; PG8_LDA(At, 0, 0); PG8_STAGE(PG8_SA(1, 1), a1 + hstepA, voffA);
;             PG8_WAIT_V(8); PG8_WAIT_L(0); PG8_BAR; PG8_MMA(0, 0, At, B0); PG8_MMA(0, 1, At, B1); PG8_BAR; PG8_SCHED;
;             PG8_LDA(At, 0, 1); PG8_STAGE(PG8_SB(0, 0), b2, voffB); PG8_STAGE(PG8_SB(0, 1), b2 + hstep, voffB); PG8_STAGE(PG8_SA(0, 0), a2, voffA);
;             PG8_WAIT_V(8); PG8_WAIT_L(0); PG8_BAR; PG8_MMA(1, 0, At, B0); PG8_MMA(1, 1, At, B1); PG8_BAR; PG8_SCHED;
.LBB0_304:
	ds_read_b128 v[104:107], v230
	ds_read_b128 v[116:119], v230 offset:1024
	ds_read_b128 v[128:131], v230 offset:2048
	ds_read_b128 v[140:143], v230 offset:3072
	ds_read_b128 v[144:147], v231
	ds_read_b128 v[148:151], v231 offset:1024
	ds_read_b128 v[152:155], v231 offset:2048
	ds_read_b128 v[156:159], v231 offset:3072
	s_add_u32 s52, s50, 0x4000
	s_addc_u32 s53, s51, 0
	s_cmpk_eq_i32 s77, 0x54
	s_cselect_b32 s56, s12, s52
	s_cselect_b32 s57, s13, s53
	s_cselect_b32 s54, s48, s67
	s_cselect_b32 s55, s49, s76
	s_add_u32 s52, s56, 0x8000
	s_addc_u32 s53, s57, 0
	ds_read_b128 v[160:163], v232
	ds_read_b128 v[164:167], v232 offset:1024
	ds_read_b128 v[168:171], v232 offset:2048
	ds_read_b128 v[172:175], v232 offset:3072
	ds_read_b128 v[176:179], v232 offset:4096
	ds_read_b128 v[180:183], v232 offset:5120
	ds_read_b128 v[190:193], v232 offset:6144
	ds_read_b128 v[194:197], v232 offset:7168
	s_add_i32 m0, s22, 0xc000
	s_nop 0
	global_load_lds_dwordx4 v222, s[50:51]
	s_add_i32 m0, s22, 0xe000
	s_nop 0
	global_load_lds_dwordx4 v224, s[50:51]
	s_waitcnt vmcnt(8)
	s_waitcnt lgkmcnt(0)
	s_barrier
	s_setprio 1
	s_waitcnt lgkmcnt(0)
	v_mfma_f32_16x16x32_bf16 v[136:139], v[104:107], v[160:163], v[136:139]
	v_mfma_f32_16x16x32_bf16 v[132:135], v[128:131], v[160:163], v[132:135]
	v_mfma_f32_16x16x32_bf16 v[112:115], v[104:107], v[168:171], v[112:115]
	v_mfma_f32_16x16x32_bf16 v[108:111], v[128:131], v[168:171], v[108:111]
	v_mfma_f32_16x16x32_bf16 v[92:95], v[104:107], v[176:179], v[92:95]
	v_mfma_f32_16x16x32_bf16 v[88:91], v[128:131], v[176:179], v[88:91]
	v_mfma_f32_16x16x32_bf16 v[76:79], v[104:107], v[190:193], v[76:79]
	v_mfma_f32_16x16x32_bf16 v[72:75], v[128:131], v[190:193], v[72:75]
	v_mfma_f32_16x16x32_bf16 v[136:139], v[116:119], v[164:167], v[136:139]
	v_mfma_f32_16x16x32_bf16 v[132:135], v[140:143], v[164:167], v[132:135]
	v_mfma_f32_16x16x32_bf16 v[112:115], v[116:119], v[172:175], v[112:115]
	v_mfma_f32_16x16x32_bf16 v[108:111], v[140:143], v[172:175], v[108:111]
	v_mfma_f32_16x16x32_bf16 v[92:95], v[116:119], v[180:183], v[92:95]
	v_mfma_f32_16x16x32_bf16 v[88:91], v[140:143], v[180:183], v[88:91]
	v_mfma_f32_16x16x32_bf16 v[76:79], v[116:119], v[194:197], v[76:79]
	v_mfma_f32_16x16x32_bf16 v[72:75], v[140:143], v[194:197], v[72:75]
	v_mfma_f32_16x16x32_bf16 v[124:127], v[144:147], v[160:163], v[124:127]
	v_mfma_f32_16x16x32_bf16 v[120:123], v[152:155], v[160:163], v[120:123]
	v_mfma_f32_16x16x32_bf16 v[100:103], v[144:147], v[168:171], v[100:103]
	v_mfma_f32_16x16x32_bf16 v[96:99], v[152:155], v[168:171], v[96:99]
	v_mfma_f32_16x16x32_bf16 v[84:87], v[144:147], v[176:179], v[84:87]
	v_mfma_f32_16x16x32_bf16 v[80:83], v[152:155], v[176:179], v[80:83]
	v_mfma_f32_16x16x32_bf16 v[68:71], v[144:147], v[190:193], v[68:71]
	v_mfma_f32_16x16x32_bf16 v[64:67], v[152:155], v[190:193], v[64:67]
	v_mfma_f32_16x16x32_bf16 v[124:127], v[148:151], v[164:167], v[124:127]
	v_mfma_f32_16x16x32_bf16 v[120:123], v[156:159], v[164:167], v[120:123]
	v_mfma_f32_16x16x32_bf16 v[100:103], v[148:151], v[172:175], v[100:103]
	v_mfma_f32_16x16x32_bf16 v[96:99], v[156:159], v[172:175], v[96:99]
	v_mfma_f32_16x16x32_bf16 v[84:87], v[148:151], v[180:183], v[84:87]
	v_mfma_f32_16x16x32_bf16 v[80:83], v[156:159], v[180:183], v[80:83]
	v_mfma_f32_16x16x32_bf16 v[68:71], v[148:151], v[194:197], v[68:71]
	v_mfma_f32_16x16x32_bf16 v[64:67], v[156:159], v[194:197], v[64:67]
	s_setprio 0
	s_barrier
	s_add_i32 s72, s61, s3
	ds_read_b128 v[160:163], v232 offset:16384
	ds_read_b128 v[164:167], v232 offset:17408
	ds_read_b128 v[168:171], v232 offset:18432
	ds_read_b128 v[172:175], v232 offset:19456
	ds_read_b128 v[176:179], v232 offset:20480
	ds_read_b128 v[180:183], v232 offset:21504
	ds_read_b128 v[190:193], v232 offset:22528
	ds_read_b128 v[194:197], v232 offset:23552
	s_mov_b32 m0, s72
	s_nop 0
	global_load_lds_dwordx4 v223, s[54:55]
	s_add_i32 m0, s72, 0x2000
	s_add_u32 s72, s54, 0x160000
	global_load_lds_dwordx4 v225, s[54:55]
	s_addc_u32 s73, s55, 0
	s_add_i32 s78, s62, s3
	s_mov_b32 m0, s78
	s_nop 0
	global_load_lds_dwordx4 v223, s[72:73]
	s_add_i32 m0, s78, 0x2000
	s_nop 0
	global_load_lds_dwordx4 v225, s[72:73]
	s_mov_b32 m0, s22
	s_nop 0
	global_load_lds_dwordx4 v222, s[56:57]
	s_mov_b32 m0, s23
	s_nop 0
	global_load_lds_dwordx4 v224, s[56:57]
	s_waitcnt vmcnt(8)
	s_waitcnt lgkmcnt(0)
	s_barrier
	s_setprio 1
	s_waitcnt lgkmcnt(0)
	v_mfma_f32_16x16x32_bf16 v[60:63], v[104:107], v[160:163], v[60:63]
	v_mfma_f32_16x16x32_bf16 v[56:59], v[128:131], v[160:163], v[56:59]
	v_mfma_f32_16x16x32_bf16 v[44:47], v[104:107], v[168:171], v[44:47]
	v_mfma_f32_16x16x32_bf16 v[40:43], v[128:131], v[168:171], v[40:43]
	v_mfma_f32_16x16x32_bf16 v[28:31], v[104:107], v[176:179], v[28:31]
	v_mfma_f32_16x16x32_bf16 v[24:27], v[128:131], v[176:179], v[24:27]
	v_mfma_f32_16x16x32_bf16 v[12:15], v[104:107], v[190:193], v[12:15]
	v_mfma_f32_16x16x32_bf16 v[8:11], v[128:131], v[190:193], v[8:11]
	v_mfma_f32_16x16x32_bf16 v[60:63], v[116:119], v[164:167], v[60:63]
	v_mfma_f32_16x16x32_bf16 v[56:59], v[140:143], v[164:167], v[56:59]
	v_mfma_f32_16x16x32_bf16 v[44:47], v[116:119], v[172:175], v[44:47]
	v_mfma_f32_16x16x32_bf16 v[40:43], v[140:143], v[172:175], v[40:43]
	v_mfma_f32_16x16x32_bf16 v[28:31], v[116:119], v[180:183], v[28:31]
	v_mfma_f32_16x16x32_bf16 v[24:27], v[140:143], v[180:183], v[24:27]
	v_mfma_f32_16x16x32_bf16 v[12:15], v[116:119], v[194:197], v[12:15]
	v_mfma_f32_16x16x32_bf16 v[8:11], v[140:143], v[194:197], v[8:11]
	v_mfma_f32_16x16x32_bf16 v[52:55], v[144:147], v[160:163], v[52:55]
	v_mfma_f32_16x16x32_bf16 v[48:51], v[152:155], v[160:163], v[48:51]
	v_mfma_f32_16x16x32_bf16 v[36:39], v[144:147], v[168:171], v[36:39]
	v_mfma_f32_16x16x32_bf16 v[32:35], v[152:155], v[168:171], v[32:35]
	v_mfma_f32_16x16x32_bf16 v[20:23], v[144:147], v[176:179], v[20:23]
	v_mfma_f32_16x16x32_bf16 v[16:19], v[152:155], v[176:179], v[16:19]
	v_mfma_f32_16x16x32_bf16 v[4:7], v[144:147], v[190:193], v[4:7]
	v_mfma_f32_16x16x32_bf16 v[0:3], v[152:155], v[190:193], v[0:3]
	v_mfma_f32_16x16x32_bf16 v[52:55], v[148:151], v[164:167], v[52:55]
	v_mfma_f32_16x16x32_bf16 v[48:51], v[156:159], v[164:167], v[48:51]
	v_mfma_f32_16x16x32_bf16 v[36:39], v[148:151], v[172:175], v[36:39]
	v_mfma_f32_16x16x32_bf16 v[32:35], v[156:159], v[172:175], v[32:35]
	v_mfma_f32_16x16x32_bf16 v[20:23], v[148:151], v[180:183], v[20:23]
	v_mfma_f32_16x16x32_bf16 v[16:19], v[156:159], v[180:183], v[16:19]
	v_mfma_f32_16x16x32_bf16 v[4:7], v[148:151], v[194:197], v[4:7]
	v_mfma_f32_16x16x32_bf16 v[0:3], v[156:159], v[194:197], v[0:3]
	s_setprio 0
	s_barrier
; #define PG8_STAGE(bufoff, gbase, voff) do { _Pragma("unroll") for (int _i = 0; _i < 2; ++_i) \
;         { unsigned _vo = (voff)[_i]; asm volatile("" : "+v"(_vo));     \
;         __builtin_amdgcn_global_load_lds((const unsigned*)((const char*)(gbase) + _vo), (PG8_LAS unsigned*)(lds + (bufoff) + ldsw + _i * 8192), 16, 0, 0); } } while (0)
; #define PG8_LDA(dst, b, h) do { _Pragma("unroll") for (int m = 0; m < 4; ++m) _Pragma("unroll") for (int k = 0; k < 2; ++k) dst[m][k] = *(const PG8_LAS bf16x8*)(lds + PG8_SA(b, h) + aoff + m * 2048 + k * 1024); } while (0)
; #define PG8_LDB(dst, b, h) do { _Pragma("unroll") for (int n = 0; n < 2; ++n) _Pragma("unroll") for (int k = 0; k < 2; ++k) dst[n][k] = *(const PG8_LAS bf16x8*)(lds + PG8_SB(b, h) + boff + n * 2048 + k * 1024); } while (0)
; #define PG8_WAIT_V(n) asm volatile("s_waitcnt vmcnt(" #n ")" ::: "memory")
; #define PG8_WAIT_L(n) asm volatile("s_waitcnt lgkmcnt(" #n ")" ::: "memory")
; #define PG8_BAR __builtin_amdgcn_s_barrier()
; #define PG8_SCHED __builtin_amdgcn_sched_barrier(0)
; template <class Epi, class Sched, bool ALIGN_EPI = false, bool SP2 = false, bool ABLK = false, bool F8 = false>
; __device__ __forceinline__ void gemm_phase(PG8_LAS unsigned char* lds, const Gemm g, const Sched& S, const Epi& E, const int wave_s) {
;     ...
;             PG8_LDB(B0, 1, 0); PG8_LDB(B1, 1, 1); PG8_SCHED; PG8_LDA(At, 1, 0); PG8_STAGE(PG8_SA(0, 1), a2 + hstepA, voffA);
;             PG8_WAIT_V(8); PG8_WAIT_L(0); PG8_BAR; PG8_MMA(0, 0, At, B0); PG8_MMA(0, 1, At, B1); PG8_BAR; PG8_SCHED;
;             PG8_LDA(At, 1, 1); PG8_STAGE(PG8_SB(1, 0), b3, voffB); PG8_STAGE(PG8_SB(1, 1), b3 + hstep, voffB); PG8_STAGE(PG8_SA(1, 0), a3, voffA);
;             PG8_WAIT_V(8); PG8_WAIT_L(0); PG8_BAR; PG8_MMA(1, 0, At, B0); PG8_MMA(1, 1, At, B1); PG8_BAR; PG8_SCHED;
;     ...
;         if constexpr (ALIGN_EPI) { if (wr == 0) PG8_BAR; }
	s_add_i32 s72, 0, 0x18000
	s_add_i32 s73, 0, 0x1c000
	v_add_u32_e32 v140, s72, v227
	v_add_u32_e32 v156, s73, v227
	ds_read_b128 v[104:107], v140
	ds_read_b128 v[116:119], v140 offset:1024
	ds_read_b128 v[128:131], v140 offset:2048
	ds_read_b128 v[140:143], v140 offset:3072
	ds_read_b128 v[144:147], v156
	ds_read_b128 v[148:151], v156 offset:1024
	ds_read_b128 v[152:155], v156 offset:2048
	ds_read_b128 v[156:159], v156 offset:3072
	s_add_u32 s56, s56, 0x4000
	s_mov_b32 m0, s46
	ds_read_b128 v[160:163], v232 offset:32768
	ds_read_b128 v[164:167], v232 offset:33792
	ds_read_b128 v[168:171], v232 offset:34816
	ds_read_b128 v[172:175], v232 offset:35840
	ds_read_b128 v[176:179], v232 offset:36864
	ds_read_b128 v[180:183], v232 offset:37888
	ds_read_b128 v[190:193], v232 offset:38912
	ds_read_b128 v[194:197], v232 offset:39936
	s_addc_u32 s57, s57, 0
	s_nop 0
	global_load_lds_dwordx4 v222, s[56:57]
	s_mov_b32 m0, s47
	s_nop 0
	global_load_lds_dwordx4 v224, s[56:57]
	s_waitcnt vmcnt(8)
	s_waitcnt lgkmcnt(0)
	s_barrier
	s_setprio 1
	s_waitcnt lgkmcnt(0)
	v_mfma_f32_16x16x32_bf16 v[136:139], v[104:107], v[160:163], v[136:139]
	v_mfma_f32_16x16x32_bf16 v[132:135], v[128:131], v[160:163], v[132:135]
	v_mfma_f32_16x16x32_bf16 v[112:115], v[104:107], v[168:171], v[112:115]
	v_mfma_f32_16x16x32_bf16 v[108:111], v[128:131], v[168:171], v[108:111]
	v_mfma_f32_16x16x32_bf16 v[92:95], v[104:107], v[176:179], v[92:95]
	v_mfma_f32_16x16x32_bf16 v[88:91], v[128:131], v[176:179], v[88:91]
	v_mfma_f32_16x16x32_bf16 v[76:79], v[104:107], v[190:193], v[76:79]
	v_mfma_f32_16x16x32_bf16 v[72:75], v[128:131], v[190:193], v[72:75]
	v_mfma_f32_16x16x32_bf16 v[136:139], v[116:119], v[164:167], v[136:139]
	v_mfma_f32_16x16x32_bf16 v[132:135], v[140:143], v[164:167], v[132:135]
	v_mfma_f32_16x16x32_bf16 v[112:115], v[116:119], v[172:175], v[112:115]
	v_mfma_f32_16x16x32_bf16 v[108:111], v[140:143], v[172:175], v[108:111]
	v_mfma_f32_16x16x32_bf16 v[92:95], v[116:119], v[180:183], v[92:95]
	v_mfma_f32_16x16x32_bf16 v[88:91], v[140:143], v[180:183], v[88:91]
	v_mfma_f32_16x16x32_bf16 v[76:79], v[116:119], v[194:197], v[76:79]
	v_mfma_f32_16x16x32_bf16 v[72:75], v[140:143], v[194:197], v[72:75]
	v_mfma_f32_16x16x32_bf16 v[124:127], v[144:147], v[160:163], v[124:127]
	v_mfma_f32_16x16x32_bf16 v[120:123], v[152:155], v[160:163], v[120:123]
	v_mfma_f32_16x16x32_bf16 v[100:103], v[144:147], v[168:171], v[100:103]
	v_mfma_f32_16x16x32_bf16 v[96:99], v[152:155], v[168:171], v[96:99]
	v_mfma_f32_16x16x32_bf16 v[84:87], v[144:147], v[176:179], v[84:87]
	v_mfma_f32_16x16x32_bf16 v[80:83], v[152:155], v[176:179], v[80:83]
	v_mfma_f32_16x16x32_bf16 v[68:71], v[144:147], v[190:193], v[68:71]
	v_mfma_f32_16x16x32_bf16 v[64:67], v[152:155], v[190:193], v[64:67]
	v_mfma_f32_16x16x32_bf16 v[124:127], v[148:151], v[164:167], v[124:127]
	v_mfma_f32_16x16x32_bf16 v[120:123], v[156:159], v[164:167], v[120:123]
	v_mfma_f32_16x16x32_bf16 v[100:103], v[148:151], v[172:175], v[100:103]
	v_mfma_f32_16x16x32_bf16 v[96:99], v[156:159], v[172:175], v[96:99]
	v_mfma_f32_16x16x32_bf16 v[84:87], v[148:151], v[180:183], v[84:87]
	v_mfma_f32_16x16x32_bf16 v[80:83], v[156:159], v[180:183], v[80:83]
	v_mfma_f32_16x16x32_bf16 v[68:71], v[148:151], v[194:197], v[68:71]
	v_mfma_f32_16x16x32_bf16 v[64:67], v[156:159], v[194:197], v[64:67]
	s_setprio 0
	s_barrier
	ds_read_b128 v[160:163], v232 offset:49152
	ds_read_b128 v[164:167], v232 offset:50176
	ds_read_b128 v[168:171], v232 offset:51200
	ds_read_b128 v[172:175], v232 offset:52224
	ds_read_b128 v[176:179], v232 offset:53248
	ds_read_b128 v[180:183], v232 offset:54272
	ds_read_b128 v[190:193], v232 offset:55296
	ds_read_b128 v[194:197], v232 offset:56320
	s_add_i32 s56, s72, s3
	s_add_u32 vcc_lo, s54, s14
	s_addc_u32 vcc_hi, s55, s15
	s_mov_b32 m0, s56
	s_nop 0
	global_load_lds_dwordx4 v223, vcc
	s_add_i32 m0, s56, 0x2000
	s_nop 0
	s_add_u32 vcc_lo, s54, s14
	s_addc_u32 vcc_hi, s55, s15
	s_add_u32 s54, s54, 0x160080
	s_addc_u32 s55, s55, 0
	s_add_i32 s56, s73, s3
	global_load_lds_dwordx4 v225, vcc
	s_mov_b32 m0, s56
	s_nop 0
	global_load_lds_dwordx4 v223, s[54:55]
	s_add_i32 m0, s56, 0x2000
	s_nop 0
	global_load_lds_dwordx4 v225, s[54:55]
	s_mov_b32 m0, s59
	s_nop 0
	global_load_lds_dwordx4 v222, s[52:53]
	v_mov_b32_e32 v184, v224
	s_mov_b32 m0, s60
	s_nop 0
	global_load_lds_dwordx4 v224, s[52:53]
	s_waitcnt vmcnt(8)
	s_waitcnt lgkmcnt(0)
	s_barrier
	s_setprio 1
	s_waitcnt lgkmcnt(0)
	v_mfma_f32_16x16x32_bf16 v[60:63], v[104:107], v[160:163], v[60:63]
	v_mfma_f32_16x16x32_bf16 v[56:59], v[128:131], v[160:163], v[56:59]
	v_mfma_f32_16x16x32_bf16 v[44:47], v[104:107], v[168:171], v[44:47]
	v_mfma_f32_16x16x32_bf16 v[40:43], v[128:131], v[168:171], v[40:43]
	v_mfma_f32_16x16x32_bf16 v[28:31], v[104:107], v[176:179], v[28:31]
	v_mfma_f32_16x16x32_bf16 v[24:27], v[128:131], v[176:179], v[24:27]
	v_mfma_f32_16x16x32_bf16 v[12:15], v[104:107], v[190:193], v[12:15]
	v_mfma_f32_16x16x32_bf16 v[8:11], v[128:131], v[190:193], v[8:11]
	v_mfma_f32_16x16x32_bf16 v[60:63], v[116:119], v[164:167], v[60:63]
	v_mfma_f32_16x16x32_bf16 v[56:59], v[140:143], v[164:167], v[56:59]
	v_mfma_f32_16x16x32_bf16 v[44:47], v[116:119], v[172:175], v[44:47]
	v_mfma_f32_16x16x32_bf16 v[40:43], v[140:143], v[172:175], v[40:43]
	v_mfma_f32_16x16x32_bf16 v[28:31], v[116:119], v[180:183], v[28:31]
	v_mfma_f32_16x16x32_bf16 v[24:27], v[140:143], v[180:183], v[24:27]
	v_mfma_f32_16x16x32_bf16 v[12:15], v[116:119], v[194:197], v[12:15]
	v_mfma_f32_16x16x32_bf16 v[8:11], v[140:143], v[194:197], v[8:11]
	v_mfma_f32_16x16x32_bf16 v[52:55], v[144:147], v[160:163], v[52:55]
	v_mfma_f32_16x16x32_bf16 v[48:51], v[152:155], v[160:163], v[48:51]
	v_mfma_f32_16x16x32_bf16 v[36:39], v[144:147], v[168:171], v[36:39]
	v_mfma_f32_16x16x32_bf16 v[32:35], v[152:155], v[168:171], v[32:35]
	v_mfma_f32_16x16x32_bf16 v[20:23], v[144:147], v[176:179], v[20:23]
	v_mfma_f32_16x16x32_bf16 v[16:19], v[152:155], v[176:179], v[16:19]
	v_mfma_f32_16x16x32_bf16 v[4:7], v[144:147], v[190:193], v[4:7]
	v_mfma_f32_16x16x32_bf16 v[0:3], v[152:155], v[190:193], v[0:3]
	v_mfma_f32_16x16x32_bf16 v[52:55], v[148:151], v[164:167], v[52:55]
	v_mfma_f32_16x16x32_bf16 v[48:51], v[156:159], v[164:167], v[48:51]
	v_mfma_f32_16x16x32_bf16 v[36:39], v[148:151], v[172:175], v[36:39]
	v_mfma_f32_16x16x32_bf16 v[32:35], v[156:159], v[172:175], v[32:35]
	v_mfma_f32_16x16x32_bf16 v[20:23], v[148:151], v[180:183], v[20:23]
	v_mfma_f32_16x16x32_bf16 v[16:19], v[156:159], v[180:183], v[16:19]
	v_mfma_f32_16x16x32_bf16 v[4:7], v[148:151], v[194:197], v[4:7]
	v_mfma_f32_16x16x32_bf16 v[0:3], v[156:159], v[194:197], v[0:3]
	s_setprio 0
	s_barrier
	s_add_i32 s77, s77, 2
	s_add_u32 s67, s67, 0x100
	s_addc_u32 s76, s76, 0
	s_add_u32 s50, s50, 0x10000
	s_addc_u32 s51, s51, 0
	s_cmpk_gt_u32 s77, 0x55
	s_cbranch_scc0 .LBB0_304
	s_and_b64 vcc, exec, s[36:37]
	s_cbranch_vccz .LBB0_307
	s_barrier

; #define PG8_STAGE(bufoff, gbase, voff) do { _Pragma("unroll") for (int _i = 0; _i < 2; ++_i) \
;         { unsigned _vo = (voff)[_i]; asm volatile("" : "+v"(_vo));     \
;         __builtin_amdgcn_global_load_lds((const unsigned*)((const char*)(gbase) + _vo), (PG8_LAS unsigned*)(lds + (bufoff) + ldsw + _i * 8192), 16, 0, 0); } } while (0)
; #define PG8_LDA(dst, b, h) do { _Pragma("unroll") for (int m = 0; m < 4; ++m) _Pragma("unroll") for (int k = 0; k < 2; ++k) dst[m][k] = *(const PG8_LAS bf16x8*)(lds + PG8_SA(b, h) + aoff + m * 2048 + k * 1024); } while (0)
; #define PG8_LDB(dst, b, h) do { _Pragma("unroll") for (int n = 0; n < 2; ++n) _Pragma("unroll") for (int k = 0; k < 2; ++k) dst[n][k] = *(const PG8_LAS bf16x8*)(lds + PG8_SB(b, h) + boff + n * 2048 + k * 1024); } while (0)
; #define PG8_WAIT_V(n) asm volatile("s_waitcnt vmcnt(" #n ")" ::: "memory")
; #define PG8_WAIT_L(n) asm volatile("s_waitcnt lgkmcnt(" #n ")" ::: "memory")
; #define PG8_BAR __builtin_amdgcn_s_barrier()
; #define PG8_SCHED __builtin_amdgcn_sched_barrier(0)
; template <class Epi, class Sched, bool ALIGN_EPI = false, bool SP2 = false, bool ABLK = false, bool F8 = false>
; __device__ __forceinline__ void gemm_phase(PG8_LAS unsigned char* lds, const Gemm g, const Sched& S, const Epi& E, const int wave_s) {
;     ...
;             PG8_LDB(B0, 0, 0); PG8_LDB(B1, 0, 1); PG8_SCHED; PG8_LDA(At, 0, 0); PG8_STAGE(PG8_SA(1, 1), a1 + hstepA, voffA);
;             PG8_WAIT_V(8); PG8_WAIT_L(0); PG8_BAR; PG8_MMA(0, 0, At, B0); PG8_MMA(0, 1, At, B1); PG8_BAR; PG8_SCHED;
;             PG8_LDA(At, 0, 1); PG8_STAGE(PG8_SB(0, 0), b2, voffB); PG8_STAGE(PG8_SB(0, 1), b2 + hstep, voffB); PG8_STAGE(PG8_SA(0, 0), a2, voffA);
;             PG8_WAIT_V(8); PG8_WAIT_L(0); PG8_BAR; PG8_MMA(1, 0, At, B0); PG8_MMA(1, 1, At, B1); PG8_BAR; PG8_SCHED;
.LBB0_395:
	ds_read_b128 v[140:143], v176
	ds_read_b128 v[144:147], v176 offset:1024
	ds_read_b128 v[148:151], v176 offset:2048
	ds_read_b128 v[152:155], v176 offset:3072
	ds_read_b128 v[188:191], v177
	ds_read_b128 v[192:195], v177 offset:1024
	ds_read_b128 v[196:199], v177 offset:2048
	ds_read_b128 v[200:203], v177 offset:3072
	s_add_u32 s64, s62, 0xfff80080
	s_addc_u32 s65, s63, -1
	s_cmp_eq_u32 vcc_lo, 28
	s_cselect_b32 s65, s20, s65
	s_cselect_b32 s64, s23, s64
	s_cselect_b32 s67, s51, s61
	s_cselect_b32 s66, s53, s59
	ds_read_b128 v[204:207], v178
	ds_read_b128 v[208:211], v178 offset:1024
	ds_read_b128 v[212:215], v178 offset:2048
	ds_read_b128 v[216:219], v178 offset:3072
	ds_read_b128 v[220:223], v178 offset:4096
	ds_read_b128 v[224:227], v178 offset:5120
	ds_read_b128 v[230:233], v178 offset:6144
	ds_read_b128 v[234:237], v178 offset:7168
	s_add_i32 m0, s78, 0xc000
	s_nop 0
	global_load_lds_dwordx4 v158, s[62:63]
	s_add_i32 m0, s78, 0xe000
	s_nop 0
	global_load_lds_dwordx4 v160, s[62:63]
	s_waitcnt vmcnt(8)
	s_waitcnt lgkmcnt(0)
	s_barrier
	s_setprio 1
	s_waitcnt lgkmcnt(0)
	v_mfma_f32_16x16x32_bf16 v[124:127], v[140:143], v[204:207], v[124:127]
	v_mfma_f32_16x16x32_bf16 v[120:123], v[148:151], v[204:207], v[120:123]
	v_mfma_f32_16x16x32_bf16 v[108:111], v[140:143], v[212:215], v[108:111]
	v_mfma_f32_16x16x32_bf16 v[104:107], v[148:151], v[212:215], v[104:107]
	v_mfma_f32_16x16x32_bf16 v[92:95], v[140:143], v[220:223], v[92:95]
	v_mfma_f32_16x16x32_bf16 v[88:91], v[148:151], v[220:223], v[88:91]
	v_mfma_f32_16x16x32_bf16 v[76:79], v[140:143], v[230:233], v[76:79]
	v_mfma_f32_16x16x32_bf16 v[72:75], v[148:151], v[230:233], v[72:75]
	v_mfma_f32_16x16x32_bf16 v[124:127], v[144:147], v[208:211], v[124:127]
	v_mfma_f32_16x16x32_bf16 v[120:123], v[152:155], v[208:211], v[120:123]
	v_mfma_f32_16x16x32_bf16 v[108:111], v[144:147], v[216:219], v[108:111]
	v_mfma_f32_16x16x32_bf16 v[104:107], v[152:155], v[216:219], v[104:107]
	v_mfma_f32_16x16x32_bf16 v[92:95], v[144:147], v[224:227], v[92:95]
	v_mfma_f32_16x16x32_bf16 v[88:91], v[152:155], v[224:227], v[88:91]
	v_mfma_f32_16x16x32_bf16 v[76:79], v[144:147], v[234:237], v[76:79]
	v_mfma_f32_16x16x32_bf16 v[72:75], v[152:155], v[234:237], v[72:75]
	v_mfma_f32_16x16x32_bf16 v[116:119], v[188:191], v[204:207], v[116:119]
	v_mfma_f32_16x16x32_bf16 v[112:115], v[196:199], v[204:207], v[112:115]
	v_mfma_f32_16x16x32_bf16 v[100:103], v[188:191], v[212:215], v[100:103]
	v_mfma_f32_16x16x32_bf16 v[96:99], v[196:199], v[212:215], v[96:99]
	v_mfma_f32_16x16x32_bf16 v[84:87], v[188:191], v[220:223], v[84:87]
	v_mfma_f32_16x16x32_bf16 v[80:83], v[196:199], v[220:223], v[80:83]
	v_mfma_f32_16x16x32_bf16 v[68:71], v[188:191], v[230:233], v[68:71]
	v_mfma_f32_16x16x32_bf16 v[64:67], v[196:199], v[230:233], v[64:67]
	v_mfma_f32_16x16x32_bf16 v[116:119], v[192:195], v[208:211], v[116:119]
	v_mfma_f32_16x16x32_bf16 v[112:115], v[200:203], v[208:211], v[112:115]
	v_mfma_f32_16x16x32_bf16 v[100:103], v[192:195], v[216:219], v[100:103]
	v_mfma_f32_16x16x32_bf16 v[96:99], v[200:203], v[216:219], v[96:99]
	v_mfma_f32_16x16x32_bf16 v[84:87], v[192:195], v[224:227], v[84:87]
	v_mfma_f32_16x16x32_bf16 v[80:83], v[200:203], v[224:227], v[80:83]
	v_mfma_f32_16x16x32_bf16 v[68:71], v[192:195], v[234:237], v[68:71]
	v_mfma_f32_16x16x32_bf16 v[64:67], v[200:203], v[234:237], v[64:67]
	s_setprio 0
	s_barrier
	s_add_i32 s72, s21, s3
	ds_read_b128 v[204:207], v178 offset:16384
	ds_read_b128 v[208:211], v178 offset:17408
	ds_read_b128 v[212:215], v178 offset:18432
	ds_read_b128 v[216:219], v178 offset:19456
	ds_read_b128 v[220:223], v178 offset:20480
	ds_read_b128 v[224:227], v178 offset:21504
	ds_read_b128 v[230:233], v178 offset:22528
	ds_read_b128 v[234:237], v178 offset:23552
	s_mov_b32 m0, s72
	s_nop 0
	global_load_lds_dwordx4 v159, s[66:67]
	s_add_i32 m0, s72, 0x2000
	s_add_u32 s72, s66, 0x80000
	global_load_lds_dwordx4 v161, s[66:67]
	s_addc_u32 s73, s67, 0
	s_add_i32 s96, s22, s3
	s_mov_b32 m0, s96
	s_nop 0
	global_load_lds_dwordx4 v159, s[72:73]
	s_add_i32 m0, s96, 0x2000
	s_nop 0
	global_load_lds_dwordx4 v161, s[72:73]
	s_mov_b32 m0, s78
	s_nop 0
	global_load_lds_dwordx4 v158, s[64:65]
	s_mov_b32 m0, s79
	s_nop 0
	global_load_lds_dwordx4 v160, s[64:65]
	s_waitcnt vmcnt(8)
	s_waitcnt lgkmcnt(0)
	s_barrier
	s_setprio 1
	s_waitcnt lgkmcnt(0)
	v_mfma_f32_16x16x32_bf16 v[60:63], v[140:143], v[204:207], v[60:63]
	v_mfma_f32_16x16x32_bf16 v[56:59], v[148:151], v[204:207], v[56:59]
	v_mfma_f32_16x16x32_bf16 v[44:47], v[140:143], v[212:215], v[44:47]
	v_mfma_f32_16x16x32_bf16 v[40:43], v[148:151], v[212:215], v[40:43]
	v_mfma_f32_16x16x32_bf16 v[28:31], v[140:143], v[220:223], v[28:31]
	v_mfma_f32_16x16x32_bf16 v[24:27], v[148:151], v[220:223], v[24:27]
	v_mfma_f32_16x16x32_bf16 v[12:15], v[140:143], v[230:233], v[12:15]
	v_mfma_f32_16x16x32_bf16 v[8:11], v[148:151], v[230:233], v[8:11]
	v_mfma_f32_16x16x32_bf16 v[60:63], v[144:147], v[208:211], v[60:63]
	v_mfma_f32_16x16x32_bf16 v[56:59], v[152:155], v[208:211], v[56:59]
	v_mfma_f32_16x16x32_bf16 v[44:47], v[144:147], v[216:219], v[44:47]
	v_mfma_f32_16x16x32_bf16 v[40:43], v[152:155], v[216:219], v[40:43]
	v_mfma_f32_16x16x32_bf16 v[28:31], v[144:147], v[224:227], v[28:31]
	v_mfma_f32_16x16x32_bf16 v[24:27], v[152:155], v[224:227], v[24:27]
	v_mfma_f32_16x16x32_bf16 v[12:15], v[144:147], v[234:237], v[12:15]
	v_mfma_f32_16x16x32_bf16 v[8:11], v[152:155], v[234:237], v[8:11]
	v_mfma_f32_16x16x32_bf16 v[52:55], v[188:191], v[204:207], v[52:55]
	v_mfma_f32_16x16x32_bf16 v[48:51], v[196:199], v[204:207], v[48:51]
	v_mfma_f32_16x16x32_bf16 v[36:39], v[188:191], v[212:215], v[36:39]
	v_mfma_f32_16x16x32_bf16 v[32:35], v[196:199], v[212:215], v[32:35]
	v_mfma_f32_16x16x32_bf16 v[20:23], v[188:191], v[220:223], v[20:23]
	v_mfma_f32_16x16x32_bf16 v[16:19], v[196:199], v[220:223], v[16:19]
	v_mfma_f32_16x16x32_bf16 v[4:7], v[188:191], v[230:233], v[4:7]
	v_mfma_f32_16x16x32_bf16 v[0:3], v[196:199], v[230:233], v[0:3]
	v_mfma_f32_16x16x32_bf16 v[52:55], v[192:195], v[208:211], v[52:55]
	v_mfma_f32_16x16x32_bf16 v[48:51], v[200:203], v[208:211], v[48:51]
	v_mfma_f32_16x16x32_bf16 v[36:39], v[192:195], v[216:219], v[36:39]
	v_mfma_f32_16x16x32_bf16 v[32:35], v[200:203], v[216:219], v[32:35]
	v_mfma_f32_16x16x32_bf16 v[20:23], v[192:195], v[224:227], v[20:23]
	v_mfma_f32_16x16x32_bf16 v[16:19], v[200:203], v[224:227], v[16:19]
	v_mfma_f32_16x16x32_bf16 v[4:7], v[192:195], v[234:237], v[4:7]
	v_mfma_f32_16x16x32_bf16 v[0:3], v[200:203], v[234:237], v[0:3]
	s_setprio 0
	s_barrier
; #define PG8_STAGE(bufoff, gbase, voff) do { _Pragma("unroll") for (int _i = 0; _i < 2; ++_i) \
;         { unsigned _vo = (voff)[_i]; asm volatile("" : "+v"(_vo));     \
;         __builtin_amdgcn_global_load_lds((const unsigned*)((const char*)(gbase) + _vo), (PG8_LAS unsigned*)(lds + (bufoff) + ldsw + _i * 8192), 16, 0, 0); } } while (0)
; #define PG8_LDA(dst, b, h) do { _Pragma("unroll") for (int m = 0; m < 4; ++m) _Pragma("unroll") for (int k = 0; k < 2; ++k) dst[m][k] = *(const PG8_LAS bf16x8*)(lds + PG8_SA(b, h) + aoff + m * 2048 + k * 1024); } while (0)
; #define PG8_LDB(dst, b, h) do { _Pragma("unroll") for (int n = 0; n < 2; ++n) _Pragma("unroll") for (int k = 0; k < 2; ++k) dst[n][k] = *(const PG8_LAS bf16x8*)(lds + PG8_SB(b, h) + boff + n * 2048 + k * 1024); } while (0)
; #define PG8_WAIT_V(n) asm volatile("s_waitcnt vmcnt(" #n ")" ::: "memory")
; #define PG8_WAIT_L(n) asm volatile("s_waitcnt lgkmcnt(" #n ")" ::: "memory")
; #define PG8_BAR __builtin_amdgcn_s_barrier()
; #define PG8_SCHED __builtin_amdgcn_sched_barrier(0)
; template <class Epi, class Sched, bool ALIGN_EPI = false, bool SP2 = false, bool ABLK = false, bool F8 = false>
; __device__ __forceinline__ void gemm_phase(PG8_LAS unsigned char* lds, const Gemm g, const Sched& S, const Epi& E, const int wave_s) {
;     ...
;             PG8_LDB(B0, 1, 0); PG8_LDB(B1, 1, 1); PG8_SCHED; PG8_LDA(At, 1, 0); PG8_STAGE(PG8_SA(0, 1), a2 + hstepA, voffA);
;             PG8_WAIT_V(8); PG8_WAIT_L(0); PG8_BAR; PG8_MMA(0, 0, At, B0); PG8_MMA(0, 1, At, B1); PG8_BAR; PG8_SCHED;
	s_add_i32 s96, 0, 0x18000
	v_add_u32_e32 v128, s96, v165
	s_add_i32 vcc_hi, 0, 0x1c000
	ds_read_b128 v[140:143], v128
	ds_read_b128 v[144:147], v128 offset:1024
	ds_read_b128 v[148:151], v128 offset:2048
	ds_read_b128 v[152:155], v128 offset:3072
	v_add_u32_e32 v128, vcc_hi, v165
	ds_read_b128 v[188:191], v128
	ds_read_b128 v[192:195], v128 offset:1024
	ds_read_b128 v[196:199], v128 offset:2048
	ds_read_b128 v[200:203], v128 offset:3072
	s_add_u32 s72, s64, 0x80000
	s_mov_b32 m0, s80
	ds_read_b128 v[204:207], v178 offset:32768
	ds_read_b128 v[208:211], v178 offset:33792
	ds_read_b128 v[212:215], v178 offset:34816
	ds_read_b128 v[216:219], v178 offset:35840
	ds_read_b128 v[220:223], v178 offset:36864
	ds_read_b128 v[224:227], v178 offset:37888
	ds_read_b128 v[230:233], v178 offset:38912
	ds_read_b128 v[234:237], v178 offset:39936
	s_addc_u32 s73, s65, 0
	s_nop 0
	global_load_lds_dwordx4 v158, s[72:73]
	s_mov_b32 m0, s81
	s_nop 0
	global_load_lds_dwordx4 v160, s[72:73]
	s_waitcnt vmcnt(8)
	s_waitcnt lgkmcnt(0)
	s_barrier
	s_setprio 1
	s_waitcnt lgkmcnt(0)
	v_mfma_f32_16x16x32_bf16 v[124:127], v[140:143], v[204:207], v[124:127]
	v_mfma_f32_16x16x32_bf16 v[120:123], v[148:151], v[204:207], v[120:123]
	v_mfma_f32_16x16x32_bf16 v[108:111], v[140:143], v[212:215], v[108:111]
	v_mfma_f32_16x16x32_bf16 v[104:107], v[148:151], v[212:215], v[104:107]
	v_mfma_f32_16x16x32_bf16 v[92:95], v[140:143], v[220:223], v[92:95]
	v_mfma_f32_16x16x32_bf16 v[88:91], v[148:151], v[220:223], v[88:91]
	v_mfma_f32_16x16x32_bf16 v[76:79], v[140:143], v[230:233], v[76:79]
	v_mfma_f32_16x16x32_bf16 v[72:75], v[148:151], v[230:233], v[72:75]
	v_mfma_f32_16x16x32_bf16 v[124:127], v[144:147], v[208:211], v[124:127]
	v_mfma_f32_16x16x32_bf16 v[120:123], v[152:155], v[208:211], v[120:123]
	v_mfma_f32_16x16x32_bf16 v[108:111], v[144:147], v[216:219], v[108:111]
	v_mfma_f32_16x16x32_bf16 v[104:107], v[152:155], v[216:219], v[104:107]
	v_mfma_f32_16x16x32_bf16 v[92:95], v[144:147], v[224:227], v[92:95]
	v_mfma_f32_16x16x32_bf16 v[88:91], v[152:155], v[224:227], v[88:91]
	v_mfma_f32_16x16x32_bf16 v[76:79], v[144:147], v[234:237], v[76:79]
	v_mfma_f32_16x16x32_bf16 v[72:75], v[152:155], v[234:237], v[72:75]
	v_mfma_f32_16x16x32_bf16 v[116:119], v[188:191], v[204:207], v[116:119]
	v_mfma_f32_16x16x32_bf16 v[112:115], v[196:199], v[204:207], v[112:115]
	v_mfma_f32_16x16x32_bf16 v[100:103], v[188:191], v[212:215], v[100:103]
	v_mfma_f32_16x16x32_bf16 v[96:99], v[196:199], v[212:215], v[96:99]
	v_mfma_f32_16x16x32_bf16 v[84:87], v[188:191], v[220:223], v[84:87]
	v_mfma_f32_16x16x32_bf16 v[80:83], v[196:199], v[220:223], v[80:83]
	v_mfma_f32_16x16x32_bf16 v[68:71], v[188:191], v[230:233], v[68:71]
	v_mfma_f32_16x16x32_bf16 v[64:67], v[196:199], v[230:233], v[64:67]
	v_mfma_f32_16x16x32_bf16 v[116:119], v[192:195], v[208:211], v[116:119]
	v_mfma_f32_16x16x32_bf16 v[112:115], v[200:203], v[208:211], v[112:115]
	v_mfma_f32_16x16x32_bf16 v[100:103], v[192:195], v[216:219], v[100:103]
	v_mfma_f32_16x16x32_bf16 v[96:99], v[200:203], v[216:219], v[96:99]
	v_mfma_f32_16x16x32_bf16 v[84:87], v[192:195], v[224:227], v[84:87]
	v_mfma_f32_16x16x32_bf16 v[80:83], v[200:203], v[224:227], v[80:83]
	v_mfma_f32_16x16x32_bf16 v[68:71], v[192:195], v[234:237], v[68:71]
	v_mfma_f32_16x16x32_bf16 v[64:67], v[200:203], v[234:237], v[64:67]
	s_setprio 0
	s_barrier
; #define PG8_STAGE(bufoff, gbase, voff) do { _Pragma("unroll") for (int _i = 0; _i < 2; ++_i) \
;         { unsigned _vo = (voff)[_i]; asm volatile("" : "+v"(_vo));     \
;         __builtin_amdgcn_global_load_lds((const unsigned*)((const char*)(gbase) + _vo), (PG8_LAS unsigned*)(lds + (bufoff) + ldsw + _i * 8192), 16, 0, 0); } } while (0)
; #define PG8_LDA(dst, b, h) do { _Pragma("unroll") for (int m = 0; m < 4; ++m) _Pragma("unroll") for (int k = 0; k < 2; ++k) dst[m][k] = *(const PG8_LAS bf16x8*)(lds + PG8_SA(b, h) + aoff + m * 2048 + k * 1024); } while (0)
; #define PG8_WAIT_V(n) asm volatile("s_waitcnt vmcnt(" #n ")" ::: "memory")
; #define PG8_WAIT_L(n) asm volatile("s_waitcnt lgkmcnt(" #n ")" ::: "memory")
; #define PG8_BAR __builtin_amdgcn_s_barrier()
; #define PG8_SCHED __builtin_amdgcn_sched_barrier(0)
; template <class Epi, class Sched, bool ALIGN_EPI = false, bool SP2 = false, bool ABLK = false, bool F8 = false>
; __device__ __forceinline__ void gemm_phase(PG8_LAS unsigned char* lds, const Gemm g, const Sched& S, const Epi& E, const int wave_s) {
;     ...
;             PG8_LDA(At, 1, 1); PG8_STAGE(PG8_SB(1, 0), b3, voffB); PG8_STAGE(PG8_SB(1, 1), b3 + hstep, voffB); PG8_STAGE(PG8_SA(1, 0), a3, voffA);
;             PG8_WAIT_V(8); PG8_WAIT_L(0); PG8_BAR; PG8_MMA(1, 0, At, B0); PG8_MMA(1, 1, At, B1); PG8_BAR; PG8_SCHED;
;     ...
;         if constexpr (ALIGN_EPI) { if (wr == 0) PG8_BAR; }
	v_mov_b32_e32 v128, v159
	ds_read_b128 v[204:207], v178 offset:49152
	ds_read_b128 v[208:211], v178 offset:50176
	ds_read_b128 v[212:215], v178 offset:51200
	ds_read_b128 v[216:219], v178 offset:52224
	ds_read_b128 v[220:223], v178 offset:53248
	ds_read_b128 v[224:227], v178 offset:54272
	ds_read_b128 v[230:233], v178 offset:55296
	ds_read_b128 v[234:237], v178 offset:56320
	s_add_i32 s72, s96, s3
	v_lshl_add_u64 v[156:157], s[66:67], 0, v[128:129]
	v_lshl_add_u64 v[156:157], v[156:157], 0, s[12:13]
	s_mov_b32 m0, s72
	v_mov_b32_e32 v128, v161
	global_load_lds_dwordx4 v[156:157], off
	s_add_i32 m0, s72, 0x2000
	s_nop 0
	v_lshl_add_u64 v[156:157], s[66:67], 0, v[128:129]
	s_add_u32 s66, s66, 0x80080
	v_lshl_add_u64 v[156:157], v[156:157], 0, s[12:13]
	s_addc_u32 s67, s67, 0
	s_add_i32 s72, vcc_hi, s3
	global_load_lds_dwordx4 v[156:157], off
	s_mov_b32 m0, s72
	s_nop 0
	global_load_lds_dwordx4 v159, s[66:67]
	s_add_i32 m0, s72, 0x2000
	s_nop 0
	global_load_lds_dwordx4 v161, s[66:67]
	v_mov_b32_e32 v128, v158
	s_mov_b32 m0, s46
	v_lshl_add_u64 v[156:157], s[64:65], 0, v[128:129]
	v_lshl_add_u64 v[156:157], v[156:157], 0, s[12:13]
	v_mov_b32_e32 v128, v160
	global_load_lds_dwordx4 v[156:157], off
	s_mov_b32 m0, s47
	v_lshl_add_u64 v[156:157], s[64:65], 0, v[128:129]
	v_lshl_add_u64 v[156:157], v[156:157], 0, s[12:13]
	global_load_lds_dwordx4 v[156:157], off
	s_waitcnt vmcnt(8)
	s_waitcnt lgkmcnt(0)
	s_barrier
	s_setprio 1
	s_waitcnt lgkmcnt(0)
	v_mfma_f32_16x16x32_bf16 v[60:63], v[140:143], v[204:207], v[60:63]
	v_mfma_f32_16x16x32_bf16 v[56:59], v[148:151], v[204:207], v[56:59]
	v_mfma_f32_16x16x32_bf16 v[44:47], v[140:143], v[212:215], v[44:47]
	v_mfma_f32_16x16x32_bf16 v[40:43], v[148:151], v[212:215], v[40:43]
	v_mfma_f32_16x16x32_bf16 v[28:31], v[140:143], v[220:223], v[28:31]
	v_mfma_f32_16x16x32_bf16 v[24:27], v[148:151], v[220:223], v[24:27]
	v_mfma_f32_16x16x32_bf16 v[12:15], v[140:143], v[230:233], v[12:15]
	v_mfma_f32_16x16x32_bf16 v[8:11], v[148:151], v[230:233], v[8:11]
	v_mfma_f32_16x16x32_bf16 v[60:63], v[144:147], v[208:211], v[60:63]
	v_mfma_f32_16x16x32_bf16 v[56:59], v[152:155], v[208:211], v[56:59]
	v_mfma_f32_16x16x32_bf16 v[44:47], v[144:147], v[216:219], v[44:47]
	v_mfma_f32_16x16x32_bf16 v[40:43], v[152:155], v[216:219], v[40:43]
	v_mfma_f32_16x16x32_bf16 v[28:31], v[144:147], v[224:227], v[28:31]
	v_mfma_f32_16x16x32_bf16 v[24:27], v[152:155], v[224:227], v[24:27]
	v_mfma_f32_16x16x32_bf16 v[12:15], v[144:147], v[234:237], v[12:15]
	v_mfma_f32_16x16x32_bf16 v[8:11], v[152:155], v[234:237], v[8:11]
	v_mfma_f32_16x16x32_bf16 v[52:55], v[188:191], v[204:207], v[52:55]
	v_mfma_f32_16x16x32_bf16 v[48:51], v[196:199], v[204:207], v[48:51]
	v_mfma_f32_16x16x32_bf16 v[36:39], v[188:191], v[212:215], v[36:39]
	v_mfma_f32_16x16x32_bf16 v[32:35], v[196:199], v[212:215], v[32:35]
	v_mfma_f32_16x16x32_bf16 v[20:23], v[188:191], v[220:223], v[20:23]
	v_mfma_f32_16x16x32_bf16 v[16:19], v[196:199], v[220:223], v[16:19]
	v_mfma_f32_16x16x32_bf16 v[4:7], v[188:191], v[230:233], v[4:7]
	v_mfma_f32_16x16x32_bf16 v[0:3], v[196:199], v[230:233], v[0:3]
	v_mfma_f32_16x16x32_bf16 v[52:55], v[192:195], v[208:211], v[52:55]
	v_mfma_f32_16x16x32_bf16 v[48:51], v[200:203], v[208:211], v[48:51]
	v_mfma_f32_16x16x32_bf16 v[36:39], v[192:195], v[216:219], v[36:39]
	v_mfma_f32_16x16x32_bf16 v[32:35], v[200:203], v[216:219], v[32:35]
	v_mfma_f32_16x16x32_bf16 v[20:23], v[192:195], v[224:227], v[20:23]
	v_mfma_f32_16x16x32_bf16 v[16:19], v[200:203], v[224:227], v[16:19]
	v_mfma_f32_16x16x32_bf16 v[4:7], v[192:195], v[234:237], v[4:7]
	v_mfma_f32_16x16x32_bf16 v[0:3], v[200:203], v[234:237], v[0:3]
	s_setprio 0
	s_barrier
	s_add_i32 vcc_lo, vcc_lo, 2
	s_add_u32 s62, s62, 0x100
	s_addc_u32 s63, s63, 0
	s_add_u32 s59, s59, 0x100
	s_addc_u32 s61, s61, 0
	s_cmp_gt_u32 vcc_lo, 29
	s_cbranch_scc0 .LBB0_395
	s_and_b64 vcc, exec, s[36:37]
	s_cbranch_vccz .LBB0_398
	s_barrier

; #define PG8_STAGE(bufoff, gbase, voff) do { _Pragma("unroll") for (int _i = 0; _i < 2; ++_i) \
;         { unsigned _vo = (voff)[_i]; asm volatile("" : "+v"(_vo));     \
;         __builtin_amdgcn_global_load_lds((const unsigned*)((const char*)(gbase) + _vo), (PG8_LAS unsigned*)(lds + (bufoff) + ldsw + _i * 8192), 16, 0, 0); } } while (0)
; #define PG8_LDA(dst, b, h) do { _Pragma("unroll") for (int m = 0; m < 4; ++m) _Pragma("unroll") for (int k = 0; k < 2; ++k) dst[m][k] = *(const PG8_LAS bf16x8*)(lds + PG8_SA(b, h) + aoff + m * 2048 + k * 1024); } while (0)
; #define PG8_LDB(dst, b, h) do { _Pragma("unroll") for (int n = 0; n < 2; ++n) _Pragma("unroll") for (int k = 0; k < 2; ++k) dst[n][k] = *(const PG8_LAS bf16x8*)(lds + PG8_SB(b, h) + boff + n * 2048 + k * 1024); } while (0)
; #define PG8_WAIT_V(n) asm volatile("s_waitcnt vmcnt(" #n ")" ::: "memory")
; #define PG8_WAIT_L(n) asm volatile("s_waitcnt lgkmcnt(" #n ")" ::: "memory")
; #define PG8_BAR __builtin_amdgcn_s_barrier()
; #define PG8_SCHED __builtin_amdgcn_sched_barrier(0)
; template <class Epi, class Sched, bool ALIGN_EPI = false, bool SP2 = false, bool ABLK = false, bool F8 = false>
; __device__ __forceinline__ void gemm_phase(PG8_LAS unsigned char* lds, const Gemm g, const Sched& S, const Epi& E, const int wave_s) {
;     ...
;             PG8_LDB(B0, 0, 0); PG8_LDB(B1, 0, 1); PG8_SCHED; PG8_LDA(At, 0, 0); PG8_STAGE(PG8_SA(1, 1), a1 + hstepA, voffA);
;             PG8_WAIT_V(8); PG8_WAIT_L(0); PG8_BAR; PG8_MMA(0, 0, At, B0); PG8_MMA(0, 1, At, B1); PG8_BAR; PG8_SCHED;
;             PG8_LDA(At, 0, 1); PG8_STAGE(PG8_SB(0, 0), b2, voffB); PG8_STAGE(PG8_SB(0, 1), b2 + hstep, voffB); PG8_STAGE(PG8_SA(0, 0), a2, voffA);
;             PG8_WAIT_V(8); PG8_WAIT_L(0); PG8_BAR; PG8_MMA(1, 0, At, B0); PG8_MMA(1, 1, At, B1); PG8_BAR; PG8_SCHED;
.LBB0_592:
	ds_read_b128 v[64:67], v236
	ds_read_b128 v[68:71], v236 offset:1024
	ds_read_b128 v[76:79], v236 offset:2048
	ds_read_b128 v[80:83], v236 offset:3072
	ds_read_b128 v[88:91], v237
	ds_read_b128 v[100:103], v237 offset:1024
	ds_read_b128 v[112:115], v237 offset:2048
	ds_read_b128 v[124:127], v237 offset:3072
	s_add_u32 s62, s60, 0xfffc0080
	s_addc_u32 s63, s61, -1
	s_cmp_eq_u32 s76, 12
	s_cselect_b32 s63, s51, s63
	s_cselect_b32 s62, s57, s62
	s_cselect_b32 s65, s49, s75
	s_cselect_b32 s64, s67, s74
	ds_read_b128 v[136:139], v238
	ds_read_b128 v[144:147], v238 offset:1024
	ds_read_b128 v[160:163], v238 offset:2048
	ds_read_b128 v[164:167], v238 offset:3072
	ds_read_b128 v[176:179], v238 offset:4096
	ds_read_b128 v[180:183], v238 offset:5120
	ds_read_b128 v[184:187], v238 offset:6144
	ds_read_b128 v[188:191], v238 offset:7168
	s_add_i32 m0, s20, 0xc000
	s_nop 0
	global_load_lds_dwordx4 v229, s[60:61]
	s_add_i32 m0, s20, 0xe000
	s_nop 0
	global_load_lds_dwordx4 v231, s[60:61]
	s_waitcnt vmcnt(8)
	s_waitcnt lgkmcnt(0)
	s_barrier
	s_setprio 1
	s_waitcnt lgkmcnt(0)
	v_mfma_f32_16x16x32_bf16 v[172:175], v[64:67], v[136:139], v[172:175]
	v_mfma_f32_16x16x32_bf16 v[168:171], v[76:79], v[136:139], v[168:171]
	v_mfma_f32_16x16x32_bf16 v[148:151], v[64:67], v[160:163], v[148:151]
	v_mfma_f32_16x16x32_bf16 v[140:143], v[76:79], v[160:163], v[140:143]
	v_mfma_f32_16x16x32_bf16 v[120:123], v[64:67], v[176:179], v[120:123]
	v_mfma_f32_16x16x32_bf16 v[116:119], v[76:79], v[176:179], v[116:119]
	v_mfma_f32_16x16x32_bf16 v[96:99], v[64:67], v[184:187], v[96:99]
	v_mfma_f32_16x16x32_bf16 v[92:95], v[76:79], v[184:187], v[92:95]
	v_mfma_f32_16x16x32_bf16 v[172:175], v[68:71], v[144:147], v[172:175]
	v_mfma_f32_16x16x32_bf16 v[168:171], v[80:83], v[144:147], v[168:171]
	v_mfma_f32_16x16x32_bf16 v[148:151], v[68:71], v[164:167], v[148:151]
	v_mfma_f32_16x16x32_bf16 v[140:143], v[80:83], v[164:167], v[140:143]
	v_mfma_f32_16x16x32_bf16 v[120:123], v[68:71], v[180:183], v[120:123]
	v_mfma_f32_16x16x32_bf16 v[116:119], v[80:83], v[180:183], v[116:119]
	v_mfma_f32_16x16x32_bf16 v[96:99], v[68:71], v[188:191], v[96:99]
	v_mfma_f32_16x16x32_bf16 v[92:95], v[80:83], v[188:191], v[92:95]
	v_mfma_f32_16x16x32_bf16 v[156:159], v[88:91], v[136:139], v[156:159]
	v_mfma_f32_16x16x32_bf16 v[132:135], v[88:91], v[160:163], v[132:135]
	v_mfma_f32_16x16x32_bf16 v[128:131], v[112:115], v[160:163], v[128:131]
	v_mfma_f32_16x16x32_bf16 v[108:111], v[88:91], v[176:179], v[108:111]
	v_mfma_f32_16x16x32_bf16 v[104:107], v[112:115], v[176:179], v[104:107]
	v_mfma_f32_16x16x32_bf16 v[84:87], v[88:91], v[184:187], v[84:87]
	v_mfma_f32_16x16x32_bf16 v[72:75], v[112:115], v[184:187], v[72:75]
	v_mfma_f32_16x16x32_bf16 v[156:159], v[100:103], v[144:147], v[156:159]
	v_mfma_f32_16x16x32_bf16 v[136:139], v[112:115], v[136:139], v[152:155]
	v_mfma_f32_16x16x32_bf16 v[132:135], v[100:103], v[164:167], v[132:135]
	v_mfma_f32_16x16x32_bf16 v[128:131], v[124:127], v[164:167], v[128:131]
	v_mfma_f32_16x16x32_bf16 v[108:111], v[100:103], v[180:183], v[108:111]
	v_mfma_f32_16x16x32_bf16 v[104:107], v[124:127], v[180:183], v[104:107]
	v_mfma_f32_16x16x32_bf16 v[84:87], v[100:103], v[188:191], v[84:87]
	v_mfma_f32_16x16x32_bf16 v[72:75], v[124:127], v[188:191], v[72:75]
	v_mfma_f32_16x16x32_bf16 v[136:139], v[124:127], v[144:147], v[136:139]
	s_setprio 0
	s_barrier
	s_add_i32 s72, s59, s3
	ds_read_b128 v[144:147], v238 offset:16384
	ds_read_b128 v[152:155], v238 offset:17408
	ds_read_b128 v[160:163], v238 offset:18432
	ds_read_b128 v[164:167], v238 offset:19456
	ds_read_b128 v[176:179], v238 offset:20480
	ds_read_b128 v[180:183], v238 offset:21504
	ds_read_b128 v[184:187], v238 offset:22528
	ds_read_b128 v[188:191], v238 offset:23552
	s_mov_b32 m0, s72
	s_nop 0
	global_load_lds_dwordx4 v230, s[64:65]
	s_add_i32 m0, s72, 0x2000
	s_add_u32 s72, s64, 0x40000
	global_load_lds_dwordx4 v232, s[64:65]
	s_addc_u32 s73, s65, 0
	s_add_i32 s77, s66, s3
	s_mov_b32 m0, s77
	s_nop 0
	global_load_lds_dwordx4 v230, s[72:73]
	s_add_i32 m0, s77, 0x2000
	s_nop 0
	global_load_lds_dwordx4 v232, s[72:73]
	s_mov_b32 m0, s20
	s_nop 0
	global_load_lds_dwordx4 v229, s[62:63]
	s_mov_b32 m0, s21
	s_nop 0
	global_load_lds_dwordx4 v231, s[62:63]
	s_waitcnt vmcnt(8)
	s_waitcnt lgkmcnt(0)
	s_barrier
	s_setprio 1
	s_waitcnt lgkmcnt(0)
	v_mfma_f32_16x16x32_bf16 v[60:63], v[64:67], v[144:147], v[60:63]
	v_mfma_f32_16x16x32_bf16 v[56:59], v[76:79], v[144:147], v[56:59]
	v_mfma_f32_16x16x32_bf16 v[44:47], v[64:67], v[160:163], v[44:47]
	v_mfma_f32_16x16x32_bf16 v[40:43], v[76:79], v[160:163], v[40:43]
	v_mfma_f32_16x16x32_bf16 v[28:31], v[64:67], v[176:179], v[28:31]
	v_mfma_f32_16x16x32_bf16 v[24:27], v[76:79], v[176:179], v[24:27]
	v_mfma_f32_16x16x32_bf16 v[12:15], v[64:67], v[184:187], v[12:15]
	v_mfma_f32_16x16x32_bf16 v[8:11], v[76:79], v[184:187], v[8:11]
	v_mfma_f32_16x16x32_bf16 v[60:63], v[68:71], v[152:155], v[60:63]
	v_mfma_f32_16x16x32_bf16 v[56:59], v[80:83], v[152:155], v[56:59]
	v_mfma_f32_16x16x32_bf16 v[44:47], v[68:71], v[164:167], v[44:47]
	v_mfma_f32_16x16x32_bf16 v[40:43], v[80:83], v[164:167], v[40:43]
	v_mfma_f32_16x16x32_bf16 v[28:31], v[68:71], v[180:183], v[28:31]
	v_mfma_f32_16x16x32_bf16 v[24:27], v[80:83], v[180:183], v[24:27]
	v_mfma_f32_16x16x32_bf16 v[12:15], v[68:71], v[188:191], v[12:15]
	v_mfma_f32_16x16x32_bf16 v[8:11], v[80:83], v[188:191], v[8:11]
	v_mfma_f32_16x16x32_bf16 v[52:55], v[88:91], v[144:147], v[52:55]
	v_mfma_f32_16x16x32_bf16 v[48:51], v[112:115], v[144:147], v[48:51]
	v_mfma_f32_16x16x32_bf16 v[36:39], v[88:91], v[160:163], v[36:39]
	v_mfma_f32_16x16x32_bf16 v[32:35], v[112:115], v[160:163], v[32:35]
	v_mfma_f32_16x16x32_bf16 v[20:23], v[88:91], v[176:179], v[20:23]
	v_mfma_f32_16x16x32_bf16 v[16:19], v[112:115], v[176:179], v[16:19]
	v_mfma_f32_16x16x32_bf16 v[4:7], v[88:91], v[184:187], v[4:7]
	v_mfma_f32_16x16x32_bf16 v[0:3], v[112:115], v[184:187], v[0:3]
	v_mfma_f32_16x16x32_bf16 v[52:55], v[100:103], v[152:155], v[52:55]
	v_mfma_f32_16x16x32_bf16 v[48:51], v[124:127], v[152:155], v[48:51]
	v_mfma_f32_16x16x32_bf16 v[36:39], v[100:103], v[164:167], v[36:39]
	v_mfma_f32_16x16x32_bf16 v[32:35], v[124:127], v[164:167], v[32:35]
	v_mfma_f32_16x16x32_bf16 v[20:23], v[100:103], v[180:183], v[20:23]
	v_mfma_f32_16x16x32_bf16 v[16:19], v[124:127], v[180:183], v[16:19]
	v_mfma_f32_16x16x32_bf16 v[4:7], v[100:103], v[188:191], v[4:7]
	v_mfma_f32_16x16x32_bf16 v[0:3], v[124:127], v[188:191], v[0:3]
	s_setprio 0
	s_barrier
; #define PG8_STAGE(bufoff, gbase, voff) do { _Pragma("unroll") for (int _i = 0; _i < 2; ++_i) \
;         { unsigned _vo = (voff)[_i]; asm volatile("" : "+v"(_vo));     \
;         __builtin_amdgcn_global_load_lds((const unsigned*)((const char*)(gbase) + _vo), (PG8_LAS unsigned*)(lds + (bufoff) + ldsw + _i * 8192), 16, 0, 0); } } while (0)
; #define PG8_LDA(dst, b, h) do { _Pragma("unroll") for (int m = 0; m < 4; ++m) _Pragma("unroll") for (int k = 0; k < 2; ++k) dst[m][k] = *(const PG8_LAS bf16x8*)(lds + PG8_SA(b, h) + aoff + m * 2048 + k * 1024); } while (0)
; #define PG8_LDB(dst, b, h) do { _Pragma("unroll") for (int n = 0; n < 2; ++n) _Pragma("unroll") for (int k = 0; k < 2; ++k) dst[n][k] = *(const PG8_LAS bf16x8*)(lds + PG8_SB(b, h) + boff + n * 2048 + k * 1024); } while (0)
; #define PG8_WAIT_V(n) asm volatile("s_waitcnt vmcnt(" #n ")" ::: "memory")
; #define PG8_WAIT_L(n) asm volatile("s_waitcnt lgkmcnt(" #n ")" ::: "memory")
; #define PG8_BAR __builtin_amdgcn_s_barrier()
; #define PG8_SCHED __builtin_amdgcn_sched_barrier(0)
; template <class Epi, class Sched, bool ALIGN_EPI = false, bool SP2 = false, bool ABLK = false, bool F8 = false>
; __device__ __forceinline__ void gemm_phase(PG8_LAS unsigned char* lds, const Gemm g, const Sched& S, const Epi& E, const int wave_s) {
;     ...
;             PG8_LDB(B0, 1, 0); PG8_LDB(B1, 1, 1); PG8_SCHED; PG8_LDA(At, 1, 0); PG8_STAGE(PG8_SA(0, 1), a2 + hstepA, voffA);
;             PG8_WAIT_V(8); PG8_WAIT_L(0); PG8_BAR; PG8_MMA(0, 0, At, B0); PG8_MMA(0, 1, At, B1); PG8_BAR; PG8_SCHED;
;             PG8_LDA(At, 1, 1); PG8_STAGE(PG8_SB(1, 0), b3, voffB); PG8_STAGE(PG8_SB(1, 1), b3 + hstep, voffB); PG8_STAGE(PG8_SA(1, 0), a3, voffA);
;             PG8_WAIT_V(8); PG8_WAIT_L(0); PG8_BAR; PG8_MMA(1, 0, At, B0); PG8_MMA(1, 1, At, B1); PG8_BAR; PG8_SCHED;
;     ...
;         if constexpr (ALIGN_EPI) { if (wr == 0) PG8_BAR; }
	s_add_i32 s77, 0, 0x18000
	s_add_i32 s78, 0, 0x1c000
	v_add_u32_e32 v80, s77, v234
	v_add_u32_e32 v124, s78, v234
	ds_read_b128 v[64:67], v80
	ds_read_b128 v[68:71], v80 offset:1024
	ds_read_b128 v[76:79], v80 offset:2048
	ds_read_b128 v[80:83], v80 offset:3072
	ds_read_b128 v[88:91], v124
	ds_read_b128 v[100:103], v124 offset:1024
	ds_read_b128 v[112:115], v124 offset:2048
	ds_read_b128 v[124:127], v124 offset:3072
	s_add_u32 s72, s62, 0x40000
	s_mov_b32 m0, s22
	ds_read_b128 v[144:147], v238 offset:32768
	ds_read_b128 v[152:155], v238 offset:33792
	ds_read_b128 v[160:163], v238 offset:34816
	ds_read_b128 v[164:167], v238 offset:35840
	ds_read_b128 v[176:179], v238 offset:36864
	ds_read_b128 v[180:183], v238 offset:37888
	ds_read_b128 v[184:187], v238 offset:38912
	ds_read_b128 v[188:191], v238 offset:39936
	s_addc_u32 s73, s63, 0
	s_nop 0
	global_load_lds_dwordx4 v229, s[72:73]
	s_mov_b32 m0, s23
	s_nop 0
	global_load_lds_dwordx4 v231, s[72:73]
	s_waitcnt vmcnt(8)
	s_waitcnt lgkmcnt(0)
	s_barrier
	s_setprio 1
	s_waitcnt lgkmcnt(0)
	v_mfma_f32_16x16x32_bf16 v[172:175], v[64:67], v[144:147], v[172:175]
	v_mfma_f32_16x16x32_bf16 v[168:171], v[76:79], v[144:147], v[168:171]
	v_mfma_f32_16x16x32_bf16 v[148:151], v[64:67], v[160:163], v[148:151]
	v_mfma_f32_16x16x32_bf16 v[140:143], v[76:79], v[160:163], v[140:143]
	v_mfma_f32_16x16x32_bf16 v[120:123], v[64:67], v[176:179], v[120:123]
	v_mfma_f32_16x16x32_bf16 v[116:119], v[76:79], v[176:179], v[116:119]
	v_mfma_f32_16x16x32_bf16 v[96:99], v[64:67], v[184:187], v[96:99]
	v_mfma_f32_16x16x32_bf16 v[92:95], v[76:79], v[184:187], v[92:95]
	v_mfma_f32_16x16x32_bf16 v[172:175], v[68:71], v[152:155], v[172:175]
	v_mfma_f32_16x16x32_bf16 v[168:171], v[80:83], v[152:155], v[168:171]
	v_mfma_f32_16x16x32_bf16 v[148:151], v[68:71], v[164:167], v[148:151]
	v_mfma_f32_16x16x32_bf16 v[140:143], v[80:83], v[164:167], v[140:143]
	v_mfma_f32_16x16x32_bf16 v[120:123], v[68:71], v[180:183], v[120:123]
	v_mfma_f32_16x16x32_bf16 v[116:119], v[80:83], v[180:183], v[116:119]
	v_mfma_f32_16x16x32_bf16 v[96:99], v[68:71], v[188:191], v[96:99]
	v_mfma_f32_16x16x32_bf16 v[92:95], v[80:83], v[188:191], v[92:95]
	v_mfma_f32_16x16x32_bf16 v[156:159], v[88:91], v[144:147], v[156:159]
	v_mfma_f32_16x16x32_bf16 v[136:139], v[112:115], v[144:147], v[136:139]
	v_mfma_f32_16x16x32_bf16 v[132:135], v[88:91], v[160:163], v[132:135]
	v_mfma_f32_16x16x32_bf16 v[128:131], v[112:115], v[160:163], v[128:131]
	v_mfma_f32_16x16x32_bf16 v[108:111], v[88:91], v[176:179], v[108:111]
	v_mfma_f32_16x16x32_bf16 v[104:107], v[112:115], v[176:179], v[104:107]
	v_mfma_f32_16x16x32_bf16 v[84:87], v[88:91], v[184:187], v[84:87]
	v_mfma_f32_16x16x32_bf16 v[72:75], v[112:115], v[184:187], v[72:75]
	v_mfma_f32_16x16x32_bf16 v[156:159], v[100:103], v[152:155], v[156:159]
	v_mfma_f32_16x16x32_bf16 v[152:155], v[124:127], v[152:155], v[136:139]
	v_mfma_f32_16x16x32_bf16 v[132:135], v[100:103], v[164:167], v[132:135]
	v_mfma_f32_16x16x32_bf16 v[128:131], v[124:127], v[164:167], v[128:131]
	v_mfma_f32_16x16x32_bf16 v[108:111], v[100:103], v[180:183], v[108:111]
	v_mfma_f32_16x16x32_bf16 v[104:107], v[124:127], v[180:183], v[104:107]
	v_mfma_f32_16x16x32_bf16 v[84:87], v[100:103], v[188:191], v[84:87]
	v_mfma_f32_16x16x32_bf16 v[72:75], v[124:127], v[188:191], v[72:75]
	s_setprio 0
	s_barrier
	ds_read_b128 v[136:139], v238 offset:49152
	ds_read_b128 v[144:147], v238 offset:50176
	ds_read_b128 v[160:163], v238 offset:51200
	ds_read_b128 v[164:167], v238 offset:52224
	ds_read_b128 v[176:179], v238 offset:53248
	ds_read_b128 v[180:183], v238 offset:54272
	ds_read_b128 v[184:187], v238 offset:55296
	ds_read_b128 v[188:191], v238 offset:56320
	s_add_i32 s72, s77, s3
	s_add_u32 vcc_lo, s64, s42
	s_addc_u32 vcc_hi, s65, s43
	s_mov_b32 m0, s72
	s_nop 0
	global_load_lds_dwordx4 v230, vcc
	s_add_i32 m0, s72, 0x2000
	s_add_u32 vcc_lo, s64, s42
	s_addc_u32 vcc_hi, s65, s43
	s_add_u32 s64, s64, 0x40080
	global_load_lds_dwordx4 v232, vcc
	s_addc_u32 s65, s65, 0
	s_add_i32 s72, s78, s3
	s_mov_b32 m0, s72
	s_nop 0
	global_load_lds_dwordx4 v230, s[64:65]
	v_mov_b32_e32 v192, v232
	s_add_i32 m0, s72, 0x2000
	s_nop 0
	global_load_lds_dwordx4 v232, s[64:65]
	s_mov_b32 m0, s46
	s_add_u32 vcc_lo, s62, s42
	s_addc_u32 vcc_hi, s63, s43
	v_mov_b32_e32 v200, v231
	global_load_lds_dwordx4 v229, vcc
	s_mov_b32 m0, s47
	s_add_u32 vcc_lo, s62, s42
	s_addc_u32 vcc_hi, s63, s43
	global_load_lds_dwordx4 v231, vcc
	s_waitcnt vmcnt(8)
	s_waitcnt lgkmcnt(0)
	s_barrier
	s_setprio 1
	s_waitcnt lgkmcnt(0)
	v_mfma_f32_16x16x32_bf16 v[60:63], v[64:67], v[136:139], v[60:63]
	v_mfma_f32_16x16x32_bf16 v[56:59], v[76:79], v[136:139], v[56:59]
	v_mfma_f32_16x16x32_bf16 v[44:47], v[64:67], v[160:163], v[44:47]
	v_mfma_f32_16x16x32_bf16 v[40:43], v[76:79], v[160:163], v[40:43]
	v_mfma_f32_16x16x32_bf16 v[28:31], v[64:67], v[176:179], v[28:31]
	v_mfma_f32_16x16x32_bf16 v[24:27], v[76:79], v[176:179], v[24:27]
	v_mfma_f32_16x16x32_bf16 v[12:15], v[64:67], v[184:187], v[12:15]
	v_mfma_f32_16x16x32_bf16 v[8:11], v[76:79], v[184:187], v[8:11]
	v_mfma_f32_16x16x32_bf16 v[60:63], v[68:71], v[144:147], v[60:63]
	v_mfma_f32_16x16x32_bf16 v[56:59], v[80:83], v[144:147], v[56:59]
	v_mfma_f32_16x16x32_bf16 v[44:47], v[68:71], v[164:167], v[44:47]
	v_mfma_f32_16x16x32_bf16 v[40:43], v[80:83], v[164:167], v[40:43]
	v_mfma_f32_16x16x32_bf16 v[28:31], v[68:71], v[180:183], v[28:31]
	v_mfma_f32_16x16x32_bf16 v[24:27], v[80:83], v[180:183], v[24:27]
	v_mfma_f32_16x16x32_bf16 v[12:15], v[68:71], v[188:191], v[12:15]
	v_mfma_f32_16x16x32_bf16 v[8:11], v[80:83], v[188:191], v[8:11]
	v_mfma_f32_16x16x32_bf16 v[52:55], v[88:91], v[136:139], v[52:55]
	v_mfma_f32_16x16x32_bf16 v[48:51], v[112:115], v[136:139], v[48:51]
	v_mfma_f32_16x16x32_bf16 v[36:39], v[88:91], v[160:163], v[36:39]
	v_mfma_f32_16x16x32_bf16 v[32:35], v[112:115], v[160:163], v[32:35]
	v_mfma_f32_16x16x32_bf16 v[20:23], v[88:91], v[176:179], v[20:23]
	v_mfma_f32_16x16x32_bf16 v[16:19], v[112:115], v[176:179], v[16:19]
	v_mfma_f32_16x16x32_bf16 v[4:7], v[88:91], v[184:187], v[4:7]
	v_mfma_f32_16x16x32_bf16 v[0:3], v[112:115], v[184:187], v[0:3]
	v_mfma_f32_16x16x32_bf16 v[52:55], v[100:103], v[144:147], v[52:55]
	v_mfma_f32_16x16x32_bf16 v[48:51], v[124:127], v[144:147], v[48:51]
	v_mfma_f32_16x16x32_bf16 v[36:39], v[100:103], v[164:167], v[36:39]
	v_mfma_f32_16x16x32_bf16 v[32:35], v[124:127], v[164:167], v[32:35]
	v_mfma_f32_16x16x32_bf16 v[20:23], v[100:103], v[180:183], v[20:23]
	v_mfma_f32_16x16x32_bf16 v[16:19], v[124:127], v[180:183], v[16:19]
	v_mfma_f32_16x16x32_bf16 v[4:7], v[100:103], v[188:191], v[4:7]
	v_mfma_f32_16x16x32_bf16 v[0:3], v[124:127], v[188:191], v[0:3]
	s_setprio 0
	s_barrier
	s_add_i32 s76, s76, 2
	s_add_u32 s60, s60, 0x100
	s_addc_u32 s61, s61, 0
	s_add_u32 s74, s74, 0x100
	s_addc_u32 s75, s75, 0
	s_cmp_gt_u32 s76, 13
	s_cbranch_scc0 .LBB0_592
	s_and_b64 vcc, exec, s[36:37]
	s_cbranch_vccz .LBB0_595
	s_barrier

; #define PG8_STAGE(bufoff, gbase, voff) do { _Pragma("unroll") for (int _i = 0; _i < 2; ++_i) \
;         { unsigned _vo = (voff)[_i]; asm volatile("" : "+v"(_vo));     \
;         __builtin_amdgcn_global_load_lds((const unsigned*)((const char*)(gbase) + _vo), (PG8_LAS unsigned*)(lds + (bufoff) + ldsw + _i * 8192), 16, 0, 0); } } while (0)
; #define PG8_LDA(dst, b, h) do { _Pragma("unroll") for (int m = 0; m < 4; ++m) _Pragma("unroll") for (int k = 0; k < 2; ++k) dst[m][k] = *(const PG8_LAS bf16x8*)(lds + PG8_SA(b, h) + aoff + m * 2048 + k * 1024); } while (0)
; #define PG8_LDB(dst, b, h) do { _Pragma("unroll") for (int n = 0; n < 2; ++n) _Pragma("unroll") for (int k = 0; k < 2; ++k) dst[n][k] = *(const PG8_LAS bf16x8*)(lds + PG8_SB(b, h) + boff + n * 2048 + k * 1024); } while (0)
; #define PG8_WAIT_V(n) asm volatile("s_waitcnt vmcnt(" #n ")" ::: "memory")
; #define PG8_WAIT_L(n) asm volatile("s_waitcnt lgkmcnt(" #n ")" ::: "memory")
; #define PG8_BAR __builtin_amdgcn_s_barrier()
; #define PG8_SCHED __builtin_amdgcn_sched_barrier(0)
; template <class Epi, class Sched, bool ALIGN_EPI = false, bool SP2 = false, bool ABLK = false, bool F8 = false>
; __device__ __forceinline__ void gemm_phase(PG8_LAS unsigned char* lds, const Gemm g, const Sched& S, const Epi& E, const int wave_s) {
;     ...
;             PG8_LDB(B0, 0, 0); PG8_LDB(B1, 0, 1); PG8_SCHED; PG8_LDA(At, 0, 0); PG8_STAGE(PG8_SA(1, 1), a1 + hstepA, voffA);
;             PG8_WAIT_V(8); PG8_WAIT_L(0); PG8_BAR; PG8_MMA(0, 0, At, B0); PG8_MMA(0, 1, At, B1); PG8_BAR; PG8_SCHED;
;             PG8_LDA(At, 0, 1); PG8_STAGE(PG8_SB(0, 0), b2, voffB); PG8_STAGE(PG8_SB(0, 1), b2 + hstep, voffB); PG8_STAGE(PG8_SA(0, 0), a2, voffA);
;             PG8_WAIT_V(8); PG8_WAIT_L(0); PG8_BAR; PG8_MMA(1, 0, At, B0); PG8_MMA(1, 1, At, B1); PG8_BAR; PG8_SCHED;
.LBB0_686:
	v_add_u32_e32 v0, s47, v166
	s_waitcnt lgkmcnt(0)
	ds_read_b128 v[136:139], v0
	ds_read_b128 v[140:143], v0 offset:1024
	ds_read_b128 v[144:147], v0 offset:2048
	ds_read_b128 v[148:151], v0 offset:3072
	v_add_u32_e32 v0, s74, v166
	ds_read_b128 v[152:155], v0
	ds_read_b128 v[156:159], v0 offset:1024
	ds_read_b128 v[172:175], v0 offset:2048
	ds_read_b128 v[176:179], v0 offset:3072
	s_add_u32 s64, s62, 0xfff80080
	s_addc_u32 s65, s63, -1
	s_cmp_eq_u32 s81, 12
	s_cselect_b32 s65, s13, s65
	s_cselect_b32 s64, s57, s64
	s_cselect_b32 s67, s55, s80
	s_cselect_b32 s66, s78, s79
	ds_read_b128 v[180:183], v167
	ds_read_b128 v[184:187], v167 offset:1024
	ds_read_b128 v[188:191], v167 offset:2048
	ds_read_b128 v[192:195], v167 offset:3072
	ds_read_b128 v[196:199], v167 offset:4096
	ds_read_b128 v[200:203], v167 offset:5120
	ds_read_b128 v[204:207], v167 offset:6144
	ds_read_b128 v[208:211], v167 offset:7168
	s_add_i32 m0, s20, 0xc000
	s_nop 0
	global_load_lds_dwordx4 v162, s[62:63]
	s_add_i32 m0, s20, 0xe000
	s_nop 0
	global_load_lds_dwordx4 v164, s[62:63]
	s_waitcnt vmcnt(8)
	s_waitcnt lgkmcnt(0)
	s_barrier
	s_setprio 1
	s_waitcnt lgkmcnt(0)
	v_mfma_f32_16x16x32_bf16 v[128:131], v[136:139], v[180:183], v[128:131]
	v_mfma_f32_16x16x32_bf16 v[124:127], v[144:147], v[180:183], v[124:127]
	v_mfma_f32_16x16x32_bf16 v[120:123], v[136:139], v[188:191], v[120:123]
	v_mfma_f32_16x16x32_bf16 v[116:119], v[144:147], v[188:191], v[116:119]
	v_mfma_f32_16x16x32_bf16 v[112:115], v[136:139], v[196:199], v[112:115]
	v_mfma_f32_16x16x32_bf16 v[108:111], v[144:147], v[196:199], v[108:111]
	v_mfma_f32_16x16x32_bf16 v[104:107], v[136:139], v[204:207], v[104:107]
	v_mfma_f32_16x16x32_bf16 v[100:103], v[144:147], v[204:207], v[100:103]
	v_mfma_f32_16x16x32_bf16 v[128:131], v[140:143], v[184:187], v[128:131]
	v_mfma_f32_16x16x32_bf16 v[124:127], v[148:151], v[184:187], v[124:127]
	v_mfma_f32_16x16x32_bf16 v[120:123], v[140:143], v[192:195], v[120:123]
	v_mfma_f32_16x16x32_bf16 v[116:119], v[148:151], v[192:195], v[116:119]
	v_mfma_f32_16x16x32_bf16 v[112:115], v[140:143], v[200:203], v[112:115]
	v_mfma_f32_16x16x32_bf16 v[108:111], v[148:151], v[200:203], v[108:111]
	v_mfma_f32_16x16x32_bf16 v[104:107], v[140:143], v[208:211], v[104:107]
	v_mfma_f32_16x16x32_bf16 v[100:103], v[148:151], v[208:211], v[100:103]
	v_mfma_f32_16x16x32_bf16 v[92:95], v[152:155], v[180:183], v[92:95]
	v_mfma_f32_16x16x32_bf16 v[84:87], v[172:175], v[180:183], v[84:87]
	v_mfma_f32_16x16x32_bf16 v[76:79], v[152:155], v[188:191], v[76:79]
	v_mfma_f32_16x16x32_bf16 v[68:71], v[172:175], v[188:191], v[68:71]
	v_mfma_f32_16x16x32_bf16 v[60:63], v[152:155], v[196:199], v[60:63]
	v_mfma_f32_16x16x32_bf16 v[52:55], v[172:175], v[196:199], v[52:55]
	v_mfma_f32_16x16x32_bf16 v[44:47], v[152:155], v[204:207], v[44:47]
	v_mfma_f32_16x16x32_bf16 v[36:39], v[172:175], v[204:207], v[36:39]
	v_mfma_f32_16x16x32_bf16 v[92:95], v[156:159], v[184:187], v[92:95]
	v_mfma_f32_16x16x32_bf16 v[84:87], v[176:179], v[184:187], v[84:87]
	v_mfma_f32_16x16x32_bf16 v[76:79], v[156:159], v[192:195], v[76:79]
	v_mfma_f32_16x16x32_bf16 v[68:71], v[176:179], v[192:195], v[68:71]
	v_mfma_f32_16x16x32_bf16 v[60:63], v[156:159], v[200:203], v[60:63]
	v_mfma_f32_16x16x32_bf16 v[52:55], v[176:179], v[200:203], v[52:55]
	v_mfma_f32_16x16x32_bf16 v[44:47], v[156:159], v[208:211], v[44:47]
	v_mfma_f32_16x16x32_bf16 v[36:39], v[176:179], v[208:211], v[36:39]
	s_setprio 0
	s_barrier
	s_add_i32 s72, s47, s3
	ds_read_b128 v[180:183], v167 offset:16384
	ds_read_b128 v[184:187], v167 offset:17408
	ds_read_b128 v[188:191], v167 offset:18432
	ds_read_b128 v[192:195], v167 offset:19456
	ds_read_b128 v[196:199], v167 offset:20480
	ds_read_b128 v[200:203], v167 offset:21504
	ds_read_b128 v[204:207], v167 offset:22528
	ds_read_b128 v[208:211], v167 offset:23552
	s_mov_b32 m0, s72
	s_nop 0
	global_load_lds_dwordx4 v163, s[66:67]
	s_add_i32 m0, s72, 0x2000
	s_add_u32 s72, s66, 0x80000
	global_load_lds_dwordx4 v165, s[66:67]
	s_addc_u32 s73, s67, 0
	s_add_i32 s82, s74, s3
	s_mov_b32 m0, s82
	s_nop 0
	global_load_lds_dwordx4 v163, s[72:73]
	s_add_i32 m0, s82, 0x2000
	s_nop 0
	global_load_lds_dwordx4 v165, s[72:73]
	s_mov_b32 m0, s20
	s_nop 0
	global_load_lds_dwordx4 v162, s[64:65]
	s_mov_b32 m0, s21
	s_nop 0
	global_load_lds_dwordx4 v164, s[64:65]
	s_waitcnt vmcnt(8)
	s_waitcnt lgkmcnt(0)
	s_barrier
	s_setprio 1
	s_waitcnt lgkmcnt(0)
	v_mfma_f32_16x16x32_bf16 v[96:99], v[136:139], v[180:183], v[96:99]
	v_mfma_f32_16x16x32_bf16 v[88:91], v[144:147], v[180:183], v[88:91]
	v_mfma_f32_16x16x32_bf16 v[80:83], v[136:139], v[188:191], v[80:83]
	v_mfma_f32_16x16x32_bf16 v[72:75], v[144:147], v[188:191], v[72:75]
	v_mfma_f32_16x16x32_bf16 v[64:67], v[136:139], v[196:199], v[64:67]
	v_mfma_f32_16x16x32_bf16 v[56:59], v[144:147], v[196:199], v[56:59]
	v_mfma_f32_16x16x32_bf16 v[48:51], v[136:139], v[204:207], v[48:51]
	v_mfma_f32_16x16x32_bf16 v[40:43], v[144:147], v[204:207], v[40:43]
	v_mfma_f32_16x16x32_bf16 v[96:99], v[140:143], v[184:187], v[96:99]
	v_mfma_f32_16x16x32_bf16 v[88:91], v[148:151], v[184:187], v[88:91]
	v_mfma_f32_16x16x32_bf16 v[80:83], v[140:143], v[192:195], v[80:83]
	v_mfma_f32_16x16x32_bf16 v[72:75], v[148:151], v[192:195], v[72:75]
	v_mfma_f32_16x16x32_bf16 v[64:67], v[140:143], v[200:203], v[64:67]
	v_mfma_f32_16x16x32_bf16 v[56:59], v[148:151], v[200:203], v[56:59]
	v_mfma_f32_16x16x32_bf16 v[48:51], v[140:143], v[208:211], v[48:51]
	v_mfma_f32_16x16x32_bf16 v[40:43], v[148:151], v[208:211], v[40:43]
	v_mfma_f32_16x16x32_bf16 v[32:35], v[152:155], v[180:183], v[32:35]
	v_mfma_f32_16x16x32_bf16 v[28:31], v[172:175], v[180:183], v[28:31]
	v_mfma_f32_16x16x32_bf16 v[24:27], v[152:155], v[188:191], v[24:27]
	v_mfma_f32_16x16x32_bf16 v[20:23], v[172:175], v[188:191], v[20:23]
	v_mfma_f32_16x16x32_bf16 v[16:19], v[152:155], v[196:199], v[16:19]
	v_mfma_f32_16x16x32_bf16 v[12:15], v[172:175], v[196:199], v[12:15]
	v_mfma_f32_16x16x32_bf16 v[8:11], v[152:155], v[204:207], v[8:11]
	v_mfma_f32_16x16x32_bf16 v[2:5], v[172:175], v[204:207], v[4:7]
	v_mfma_f32_16x16x32_bf16 v[32:35], v[156:159], v[184:187], v[32:35]
	v_mfma_f32_16x16x32_bf16 v[28:31], v[176:179], v[184:187], v[28:31]
	v_mfma_f32_16x16x32_bf16 v[24:27], v[156:159], v[192:195], v[24:27]
	v_mfma_f32_16x16x32_bf16 v[20:23], v[176:179], v[192:195], v[20:23]
	v_mfma_f32_16x16x32_bf16 v[16:19], v[156:159], v[200:203], v[16:19]
	v_mfma_f32_16x16x32_bf16 v[12:15], v[176:179], v[200:203], v[12:15]
	v_mfma_f32_16x16x32_bf16 v[8:11], v[156:159], v[208:211], v[8:11]
	v_mfma_f32_16x16x32_bf16 v[2:5], v[176:179], v[208:211], v[2:5]
	s_setprio 0
	s_barrier
; #define PG8_STAGE(bufoff, gbase, voff) do { _Pragma("unroll") for (int _i = 0; _i < 2; ++_i) \
;         { unsigned _vo = (voff)[_i]; asm volatile("" : "+v"(_vo));     \
;         __builtin_amdgcn_global_load_lds((const unsigned*)((const char*)(gbase) + _vo), (PG8_LAS unsigned*)(lds + (bufoff) + ldsw + _i * 8192), 16, 0, 0); } } while (0)
; #define PG8_LDA(dst, b, h) do { _Pragma("unroll") for (int m = 0; m < 4; ++m) _Pragma("unroll") for (int k = 0; k < 2; ++k) dst[m][k] = *(const PG8_LAS bf16x8*)(lds + PG8_SA(b, h) + aoff + m * 2048 + k * 1024); } while (0)
; #define PG8_LDB(dst, b, h) do { _Pragma("unroll") for (int n = 0; n < 2; ++n) _Pragma("unroll") for (int k = 0; k < 2; ++k) dst[n][k] = *(const PG8_LAS bf16x8*)(lds + PG8_SB(b, h) + boff + n * 2048 + k * 1024); } while (0)
; #define PG8_WAIT_V(n) asm volatile("s_waitcnt vmcnt(" #n ")" ::: "memory")
; #define PG8_WAIT_L(n) asm volatile("s_waitcnt lgkmcnt(" #n ")" ::: "memory")
; #define PG8_BAR __builtin_amdgcn_s_barrier()
; #define PG8_SCHED __builtin_amdgcn_sched_barrier(0)
; template <class Epi, class Sched, bool ALIGN_EPI = false, bool SP2 = false, bool ABLK = false, bool F8 = false>
; __device__ __forceinline__ void gemm_phase(PG8_LAS unsigned char* lds, const Gemm g, const Sched& S, const Epi& E, const int wave_s) {
;     ...
;             PG8_LDB(B0, 1, 0); PG8_LDB(B1, 1, 1); PG8_SCHED; PG8_LDA(At, 1, 0); PG8_STAGE(PG8_SA(0, 1), a2 + hstepA, voffA);
;             PG8_WAIT_V(8); PG8_WAIT_L(0); PG8_BAR; PG8_MMA(0, 0, At, B0); PG8_MMA(0, 1, At, B1); PG8_BAR; PG8_SCHED;
;             PG8_LDA(At, 1, 1); PG8_STAGE(PG8_SB(1, 0), b3, voffB); PG8_STAGE(PG8_SB(1, 1), b3 + hstep, voffB); PG8_STAGE(PG8_SA(1, 0), a3, voffA);
;             PG8_WAIT_V(8); PG8_WAIT_L(0); PG8_BAR; PG8_MMA(1, 0, At, B0); PG8_MMA(1, 1, At, B1); PG8_BAR; PG8_SCHED;
;     ...
;         if constexpr (ALIGN_EPI) { if (wr == 0) PG8_BAR; }
	s_add_i32 s82, 0, 0x18000
	v_add_u32_e32 v0, s82, v166
	s_add_i32 s83, 0, 0x1c000
	ds_read_b128 v[136:139], v0
	ds_read_b128 v[140:143], v0 offset:1024
	ds_read_b128 v[144:147], v0 offset:2048
	ds_read_b128 v[148:151], v0 offset:3072
	v_add_u32_e32 v0, s83, v166
	ds_read_b128 v[152:155], v0
	ds_read_b128 v[156:159], v0 offset:1024
	ds_read_b128 v[172:175], v0 offset:2048
	ds_read_b128 v[176:179], v0 offset:3072
	s_add_u32 s72, s64, 0x80000
	s_mov_b32 m0, s22
	ds_read_b128 v[180:183], v167 offset:32768
	ds_read_b128 v[184:187], v167 offset:33792
	ds_read_b128 v[188:191], v167 offset:34816
	ds_read_b128 v[192:195], v167 offset:35840
	ds_read_b128 v[196:199], v167 offset:36864
	ds_read_b128 v[200:203], v167 offset:37888
	ds_read_b128 v[204:207], v167 offset:38912
	ds_read_b128 v[208:211], v167 offset:39936
	s_addc_u32 s73, s65, 0
	s_nop 0
	global_load_lds_dwordx4 v162, s[72:73]
	s_mov_b32 m0, s23
	s_nop 0
	global_load_lds_dwordx4 v164, s[72:73]
	s_waitcnt vmcnt(8)
	s_waitcnt lgkmcnt(0)
	s_barrier
	s_setprio 1
	s_waitcnt lgkmcnt(0)
	v_mfma_f32_16x16x32_bf16 v[128:131], v[136:139], v[180:183], v[128:131]
	v_mfma_f32_16x16x32_bf16 v[124:127], v[144:147], v[180:183], v[124:127]
	v_mfma_f32_16x16x32_bf16 v[120:123], v[136:139], v[188:191], v[120:123]
	v_mfma_f32_16x16x32_bf16 v[116:119], v[144:147], v[188:191], v[116:119]
	v_mfma_f32_16x16x32_bf16 v[112:115], v[136:139], v[196:199], v[112:115]
	v_mfma_f32_16x16x32_bf16 v[108:111], v[144:147], v[196:199], v[108:111]
	v_mfma_f32_16x16x32_bf16 v[104:107], v[136:139], v[204:207], v[104:107]
	v_mfma_f32_16x16x32_bf16 v[100:103], v[144:147], v[204:207], v[100:103]
	v_mfma_f32_16x16x32_bf16 v[128:131], v[140:143], v[184:187], v[128:131]
	v_mfma_f32_16x16x32_bf16 v[124:127], v[148:151], v[184:187], v[124:127]
	v_mfma_f32_16x16x32_bf16 v[120:123], v[140:143], v[192:195], v[120:123]
	v_mfma_f32_16x16x32_bf16 v[116:119], v[148:151], v[192:195], v[116:119]
	v_mfma_f32_16x16x32_bf16 v[112:115], v[140:143], v[200:203], v[112:115]
	v_mfma_f32_16x16x32_bf16 v[108:111], v[148:151], v[200:203], v[108:111]
	v_mfma_f32_16x16x32_bf16 v[104:107], v[140:143], v[208:211], v[104:107]
	v_mfma_f32_16x16x32_bf16 v[100:103], v[148:151], v[208:211], v[100:103]
	v_mfma_f32_16x16x32_bf16 v[92:95], v[152:155], v[180:183], v[92:95]
	v_mfma_f32_16x16x32_bf16 v[84:87], v[172:175], v[180:183], v[84:87]
	v_mfma_f32_16x16x32_bf16 v[76:79], v[152:155], v[188:191], v[76:79]
	v_mfma_f32_16x16x32_bf16 v[68:71], v[172:175], v[188:191], v[68:71]
	v_mfma_f32_16x16x32_bf16 v[60:63], v[152:155], v[196:199], v[60:63]
	v_mfma_f32_16x16x32_bf16 v[52:55], v[172:175], v[196:199], v[52:55]
	v_mfma_f32_16x16x32_bf16 v[44:47], v[152:155], v[204:207], v[44:47]
	v_mfma_f32_16x16x32_bf16 v[36:39], v[172:175], v[204:207], v[36:39]
	v_mfma_f32_16x16x32_bf16 v[92:95], v[156:159], v[184:187], v[92:95]
	v_mfma_f32_16x16x32_bf16 v[84:87], v[176:179], v[184:187], v[84:87]
	v_mfma_f32_16x16x32_bf16 v[76:79], v[156:159], v[192:195], v[76:79]
	v_mfma_f32_16x16x32_bf16 v[68:71], v[176:179], v[192:195], v[68:71]
	v_mfma_f32_16x16x32_bf16 v[60:63], v[156:159], v[200:203], v[60:63]
	v_mfma_f32_16x16x32_bf16 v[52:55], v[176:179], v[200:203], v[52:55]
	v_mfma_f32_16x16x32_bf16 v[44:47], v[156:159], v[208:211], v[44:47]
	v_mfma_f32_16x16x32_bf16 v[36:39], v[176:179], v[208:211], v[36:39]
	s_setprio 0
	s_barrier
	ds_read_b128 v[180:183], v167 offset:49152
	ds_read_b128 v[184:187], v167 offset:50176
	ds_read_b128 v[188:191], v167 offset:51200
	ds_read_b128 v[192:195], v167 offset:52224
	ds_read_b128 v[196:199], v167 offset:53248
	ds_read_b128 v[200:203], v167 offset:54272
	ds_read_b128 v[204:207], v167 offset:55296
	ds_read_b128 v[208:211], v167 offset:56320
	s_add_i32 s72, s82, s3
	s_add_u32 vcc_lo, s66, s50
	s_addc_u32 vcc_hi, s67, s51
	s_mov_b32 m0, s72
	s_nop 0
	global_load_lds_dwordx4 v163, vcc
	s_add_i32 m0, s72, 0x2000
	s_nop 0
	s_add_u32 vcc_lo, s66, s50
	s_addc_u32 vcc_hi, s67, s51
	s_add_u32 s66, s66, 0x80080
	s_addc_u32 s67, s67, 0
	s_add_i32 s72, s83, s3
	global_load_lds_dwordx4 v165, vcc
	s_mov_b32 m0, s72
	s_nop 0
	global_load_lds_dwordx4 v163, s[66:67]
	s_add_i32 m0, s72, 0x2000
	s_nop 0
	global_load_lds_dwordx4 v165, s[66:67]
	s_mov_b32 m0, s33
	s_add_u32 vcc_lo, s64, s50
	s_addc_u32 vcc_hi, s65, s51
	v_mov_b32_e32 v0, v164
	global_load_lds_dwordx4 v162, vcc
	s_mov_b32 m0, s46
	s_add_u32 vcc_lo, s64, s50
	s_addc_u32 vcc_hi, s65, s51
	global_load_lds_dwordx4 v164, vcc
	s_waitcnt vmcnt(8)
	s_waitcnt lgkmcnt(0)
	s_barrier
	s_setprio 1
	s_waitcnt lgkmcnt(0)
	v_mfma_f32_16x16x32_bf16 v[96:99], v[136:139], v[180:183], v[96:99]
	v_mfma_f32_16x16x32_bf16 v[88:91], v[144:147], v[180:183], v[88:91]
	v_mfma_f32_16x16x32_bf16 v[80:83], v[136:139], v[188:191], v[80:83]
	v_mfma_f32_16x16x32_bf16 v[72:75], v[144:147], v[188:191], v[72:75]
	v_mfma_f32_16x16x32_bf16 v[64:67], v[136:139], v[196:199], v[64:67]
	v_mfma_f32_16x16x32_bf16 v[56:59], v[144:147], v[196:199], v[56:59]
	v_mfma_f32_16x16x32_bf16 v[48:51], v[136:139], v[204:207], v[48:51]
	v_mfma_f32_16x16x32_bf16 v[40:43], v[144:147], v[204:207], v[40:43]
	v_mfma_f32_16x16x32_bf16 v[96:99], v[140:143], v[184:187], v[96:99]
	v_mfma_f32_16x16x32_bf16 v[88:91], v[148:151], v[184:187], v[88:91]
	v_mfma_f32_16x16x32_bf16 v[80:83], v[140:143], v[192:195], v[80:83]
	v_mfma_f32_16x16x32_bf16 v[72:75], v[148:151], v[192:195], v[72:75]
	v_mfma_f32_16x16x32_bf16 v[64:67], v[140:143], v[200:203], v[64:67]
	v_mfma_f32_16x16x32_bf16 v[56:59], v[148:151], v[200:203], v[56:59]
	v_mfma_f32_16x16x32_bf16 v[48:51], v[140:143], v[208:211], v[48:51]
	v_mfma_f32_16x16x32_bf16 v[40:43], v[148:151], v[208:211], v[40:43]
	v_mfma_f32_16x16x32_bf16 v[32:35], v[152:155], v[180:183], v[32:35]
	v_mfma_f32_16x16x32_bf16 v[28:31], v[172:175], v[180:183], v[28:31]
	v_mfma_f32_16x16x32_bf16 v[24:27], v[152:155], v[188:191], v[24:27]
	v_mfma_f32_16x16x32_bf16 v[20:23], v[172:175], v[188:191], v[20:23]
	v_mfma_f32_16x16x32_bf16 v[16:19], v[152:155], v[196:199], v[16:19]
	v_mfma_f32_16x16x32_bf16 v[12:15], v[172:175], v[196:199], v[12:15]
	v_mfma_f32_16x16x32_bf16 v[6:9], v[152:155], v[204:207], v[8:11]
	v_mfma_f32_16x16x32_bf16 v[2:5], v[172:175], v[204:207], v[2:5]
	v_mfma_f32_16x16x32_bf16 v[32:35], v[156:159], v[184:187], v[32:35]
	v_mfma_f32_16x16x32_bf16 v[28:31], v[176:179], v[184:187], v[28:31]
	v_mfma_f32_16x16x32_bf16 v[24:27], v[156:159], v[192:195], v[24:27]
	v_mfma_f32_16x16x32_bf16 v[20:23], v[176:179], v[192:195], v[20:23]
	v_mfma_f32_16x16x32_bf16 v[16:19], v[156:159], v[200:203], v[16:19]
	v_mfma_f32_16x16x32_bf16 v[12:15], v[176:179], v[200:203], v[12:15]
	v_mfma_f32_16x16x32_bf16 v[8:11], v[156:159], v[208:211], v[6:9]
	v_mfma_f32_16x16x32_bf16 v[4:7], v[176:179], v[208:211], v[2:5]
	s_setprio 0
	s_barrier
	s_add_i32 s81, s81, 2
	s_add_u32 s62, s62, 0x100
	s_addc_u32 s63, s63, 0
	s_add_u32 s79, s79, 0x100
	s_addc_u32 s80, s80, 0
	s_cmp_gt_u32 s81, 13
	s_cbranch_scc0 .LBB0_686
	s_and_b64 vcc, exec, s[36:37]
	s_cbranch_vccz .LBB0_689
	s_barrier

; #define PG8_STAGE(bufoff, gbase, voff) do { _Pragma("unroll") for (int _i = 0; _i < 2; ++_i) \
;         { unsigned _vo = (voff)[_i]; asm volatile("" : "+v"(_vo));     \
;         __builtin_amdgcn_global_load_lds((const unsigned*)((const char*)(gbase) + _vo), (PG8_LAS unsigned*)(lds + (bufoff) + ldsw + _i * 8192), 16, 0, 0); } } while (0)
; #define PG8_LDA(dst, b, h) do { _Pragma("unroll") for (int m = 0; m < 4; ++m) _Pragma("unroll") for (int k = 0; k < 2; ++k) dst[m][k] = *(const PG8_LAS bf16x8*)(lds + PG8_SA(b, h) + aoff + m * 2048 + k * 1024); } while (0)
; #define PG8_LDB(dst, b, h) do { _Pragma("unroll") for (int n = 0; n < 2; ++n) _Pragma("unroll") for (int k = 0; k < 2; ++k) dst[n][k] = *(const PG8_LAS bf16x8*)(lds + PG8_SB(b, h) + boff + n * 2048 + k * 1024); } while (0)
; #define PG8_WAIT_V(n) asm volatile("s_waitcnt vmcnt(" #n ")" ::: "memory")
; #define PG8_WAIT_L(n) asm volatile("s_waitcnt lgkmcnt(" #n ")" ::: "memory")
; #define PG8_BAR __builtin_amdgcn_s_barrier()
; #define PG8_SCHED __builtin_amdgcn_sched_barrier(0)
; template <class Epi, class Sched, bool ALIGN_EPI = false, bool SP2 = false, bool ABLK = false, bool F8 = false>
; __device__ __forceinline__ void gemm_phase(PG8_LAS unsigned char* lds, const Gemm g, const Sched& S, const Epi& E, const int wave_s) {
;     ...
;             PG8_LDB(B0, 0, 0); PG8_LDB(B1, 0, 1); PG8_SCHED; PG8_LDA(At, 0, 0); PG8_STAGE(PG8_SA(1, 1), a1 + hstepA, voffA);
;             PG8_WAIT_V(8); PG8_WAIT_L(0); PG8_BAR; PG8_MMA(0, 0, At, B0); PG8_MMA(0, 1, At, B1); PG8_BAR; PG8_SCHED;
;             PG8_LDA(At, 0, 1); PG8_STAGE(PG8_SB(0, 0), b2, voffB); PG8_STAGE(PG8_SB(0, 1), b2 + hstep, voffB); PG8_STAGE(PG8_SA(0, 0), a2, voffA);
;             PG8_WAIT_V(8); PG8_WAIT_L(0); PG8_BAR; PG8_MMA(1, 0, At, B0); PG8_MMA(1, 1, At, B1); PG8_BAR; PG8_SCHED;
.LBB0_810:
	v_add_u32_e32 v128, s61, v142
	ds_read_b128 v[148:151], v128
	ds_read_b128 v[152:155], v128 offset:1024
	ds_read_b128 v[156:159], v128 offset:2048
	ds_read_b128 v[160:163], v128 offset:3072
	v_add_u32_e32 v128, s62, v142
	ds_read_b128 v[164:167], v128
	ds_read_b128 v[168:171], v128 offset:1024
	ds_read_b128 v[172:175], v128 offset:2048
	ds_read_b128 v[176:179], v128 offset:3072
	s_add_u32 s58, s54, 0xfffc0080
	s_addc_u32 s59, s55, -1
	s_and_b64 s[56:57], s[56:57], exec
	s_cselect_b32 s57, s59, s43
	s_cselect_b32 s56, s58, s66
	s_cselect_b32 s59, s73, s41
	s_cselect_b32 s58, s72, s67
	ds_read_b128 v[180:183], v143
	ds_read_b128 v[184:187], v143 offset:1024
	ds_read_b128 v[188:191], v143 offset:2048
	ds_read_b128 v[192:195], v143 offset:3072
	ds_read_b128 v[196:199], v143 offset:4096
	ds_read_b128 v[200:203], v143 offset:5120
	ds_read_b128 v[204:207], v143 offset:6144
	ds_read_b128 v[208:211], v143 offset:7168
	s_add_i32 m0, s20, 0xc000
	s_nop 0
	global_load_lds_dwordx4 v147, s[54:55]
	s_add_i32 m0, s20, 0xe000
	s_nop 0
	global_load_lds_dwordx4 v140, s[54:55]
	s_waitcnt vmcnt(8)
	s_waitcnt lgkmcnt(0)
	s_barrier
	s_setprio 1
	s_waitcnt lgkmcnt(0)
	v_mfma_f32_16x16x128_f8f6f4 v[124:127], v[148:155], v[180:187], v[124:127]
	v_mfma_f32_16x16x128_f8f6f4 v[116:119], v[156:163], v[180:187], v[116:119]
	v_mfma_f32_16x16x128_f8f6f4 v[108:111], v[148:155], v[188:195], v[108:111]
	v_mfma_f32_16x16x128_f8f6f4 v[100:103], v[156:163], v[188:195], v[100:103]
	v_mfma_f32_16x16x128_f8f6f4 v[212:215], v[148:155], v[196:203], v[92:95]
	v_mfma_f32_16x16x128_f8f6f4 v[216:219], v[156:163], v[196:203], v[84:87]
	v_mfma_f32_16x16x128_f8f6f4 v[220:223], v[148:155], v[204:211], v[76:79]
	v_mfma_f32_16x16x128_f8f6f4 v[224:227], v[156:163], v[204:211], v[68:71]
	v_mfma_f32_16x16x128_f8f6f4 v[120:123], v[164:171], v[180:187], v[120:123]
	v_mfma_f32_16x16x128_f8f6f4 v[112:115], v[172:179], v[180:187], v[112:115]
	v_mfma_f32_16x16x128_f8f6f4 v[104:107], v[164:171], v[188:195], v[104:107]
	v_mfma_f32_16x16x128_f8f6f4 v[96:99], v[172:179], v[188:195], v[96:99]
	v_mfma_f32_16x16x128_f8f6f4 v[180:183], v[164:171], v[196:203], v[88:91]
	v_mfma_f32_16x16x128_f8f6f4 v[184:187], v[172:179], v[196:203], v[80:83]
	v_mfma_f32_16x16x128_f8f6f4 v[188:191], v[164:171], v[204:211], v[72:75]
	v_mfma_f32_16x16x128_f8f6f4 v[192:195], v[172:179], v[204:211], v[64:67]
	s_setprio 0
	s_barrier
	s_add_i32 s76, s61, s3
	s_nop 2
	ds_read_b128 v[64:67], v143 offset:16384
	ds_read_b128 v[68:71], v143 offset:17408
	ds_read_b128 v[72:75], v143 offset:18432
	ds_read_b128 v[76:79], v143 offset:19456
	ds_read_b128 v[80:83], v143 offset:20480
	ds_read_b128 v[84:87], v143 offset:21504
	ds_read_b128 v[88:91], v143 offset:22528
	ds_read_b128 v[92:95], v143 offset:23552
	s_mov_b32 m0, s76
	s_nop 0
	global_load_lds_dwordx4 v254, s[58:59]
	s_add_i32 m0, s76, 0x2000
	s_add_u32 s76, s58, 0x40000
	global_load_lds_dwordx4 v141, s[58:59]
	s_addc_u32 s77, s59, 0
	s_add_i32 s78, s62, s3
	s_mov_b32 m0, s78
	s_nop 0
	global_load_lds_dwordx4 v254, s[76:77]
	s_add_i32 m0, s78, 0x2000
	s_nop 0
	global_load_lds_dwordx4 v141, s[76:77]
	s_mov_b32 m0, s20
	s_nop 0
	global_load_lds_dwordx4 v147, s[56:57]
	s_mov_b32 m0, s21
	s_nop 0
	global_load_lds_dwordx4 v140, s[56:57]
	s_waitcnt vmcnt(8)
	s_waitcnt lgkmcnt(0)
	s_barrier
	s_setprio 1
	s_waitcnt lgkmcnt(0)
	v_mfma_f32_16x16x128_f8f6f4 v[60:63], v[148:155], v[64:71], v[60:63]
	v_mfma_f32_16x16x128_f8f6f4 v[52:55], v[156:163], v[64:71], v[52:55]
	v_mfma_f32_16x16x128_f8f6f4 v[44:47], v[148:155], v[72:79], v[44:47]
	v_mfma_f32_16x16x128_f8f6f4 v[204:207], v[156:163], v[72:79], v[36:39]
	v_mfma_f32_16x16x128_f8f6f4 v[208:211], v[148:155], v[80:87], v[28:31]
	v_mfma_f32_16x16x128_f8f6f4 v[230:233], v[156:163], v[80:87], v[20:23]
	v_mfma_f32_16x16x128_f8f6f4 v[234:237], v[148:155], v[88:95], v[12:15]
	v_mfma_f32_16x16x128_f8f6f4 v[238:241], v[156:163], v[88:95], v[4:7]
	v_mfma_f32_16x16x128_f8f6f4 v[56:59], v[164:171], v[64:71], v[56:59]
	v_mfma_f32_16x16x128_f8f6f4 v[48:51], v[172:179], v[64:71], v[48:51]
	v_mfma_f32_16x16x128_f8f6f4 v[40:43], v[164:171], v[72:79], v[40:43]
	v_mfma_f32_16x16x128_f8f6f4 v[242:245], v[172:179], v[72:79], v[32:35]
	v_mfma_f32_16x16x128_f8f6f4 v[246:249], v[164:171], v[80:87], v[24:27]
	v_mfma_f32_16x16x128_f8f6f4 v[250:253], v[172:179], v[80:87], v[16:19]
	v_mfma_f32_16x16x128_f8f6f4 v[132:135], v[164:171], v[88:95], v[8:11]
	v_mfma_f32_16x16x128_f8f6f4 v[136:139], v[172:179], v[88:95], v[0:3]
	s_setprio 0
	s_barrier
; #define PG8_STAGE(bufoff, gbase, voff) do { _Pragma("unroll") for (int _i = 0; _i < 2; ++_i) \
;         { unsigned _vo = (voff)[_i]; asm volatile("" : "+v"(_vo));     \
;         __builtin_amdgcn_global_load_lds((const unsigned*)((const char*)(gbase) + _vo), (PG8_LAS unsigned*)(lds + (bufoff) + ldsw + _i * 8192), 16, 0, 0); } } while (0)
; #define PG8_LDA(dst, b, h) do { _Pragma("unroll") for (int m = 0; m < 4; ++m) _Pragma("unroll") for (int k = 0; k < 2; ++k) dst[m][k] = *(const PG8_LAS bf16x8*)(lds + PG8_SA(b, h) + aoff + m * 2048 + k * 1024); } while (0)
; #define PG8_LDB(dst, b, h) do { _Pragma("unroll") for (int n = 0; n < 2; ++n) _Pragma("unroll") for (int k = 0; k < 2; ++k) dst[n][k] = *(const PG8_LAS bf16x8*)(lds + PG8_SB(b, h) + boff + n * 2048 + k * 1024); } while (0)
; #define PG8_WAIT_V(n) asm volatile("s_waitcnt vmcnt(" #n ")" ::: "memory")
; #define PG8_WAIT_L(n) asm volatile("s_waitcnt lgkmcnt(" #n ")" ::: "memory")
; #define PG8_BAR __builtin_amdgcn_s_barrier()
; #define PG8_SCHED __builtin_amdgcn_sched_barrier(0)
; template <class Epi, class Sched, bool ALIGN_EPI = false, bool SP2 = false, bool ABLK = false, bool F8 = false>
; __device__ __forceinline__ void gemm_phase(PG8_LAS unsigned char* lds, const Gemm g, const Sched& S, const Epi& E, const int wave_s) {
;     ...
;             PG8_LDB(B0, 1, 0); PG8_LDB(B1, 1, 1); PG8_SCHED; PG8_LDA(At, 1, 0); PG8_STAGE(PG8_SA(0, 1), a2 + hstepA, voffA);
;             PG8_WAIT_V(8); PG8_WAIT_L(0); PG8_BAR; PG8_MMA(0, 0, At, B0); PG8_MMA(0, 1, At, B1); PG8_BAR; PG8_SCHED;
;             PG8_LDA(At, 1, 1); PG8_STAGE(PG8_SB(1, 0), b3, voffB); PG8_STAGE(PG8_SB(1, 1), b3 + hstep, voffB); PG8_STAGE(PG8_SA(1, 0), a3, voffA);
;             PG8_WAIT_V(8); PG8_WAIT_L(0); PG8_BAR; PG8_MMA(1, 0, At, B0); PG8_MMA(1, 1, At, B1); PG8_BAR; PG8_SCHED;
	s_add_i32 s78, 0, 0x18000
	s_nop 2
	v_add_u32_e32 v8, s78, v142
	s_add_i32 s79, 0, 0x1c000
	ds_read_b128 v[0:3], v8
	ds_read_b128 v[4:7], v8 offset:1024
	ds_read_b128 v[148:151], v8 offset:2048
	ds_read_b128 v[152:155], v8 offset:3072
	v_add_u32_e32 v8, s79, v142
	ds_read_b128 v[156:159], v8
	ds_read_b128 v[160:163], v8 offset:1024
	ds_read_b128 v[164:167], v8 offset:2048
	ds_read_b128 v[168:171], v8 offset:3072
	s_add_u32 s76, s56, 0x40000
	s_mov_b32 m0, s22
	ds_read_b128 v[8:11], v143 offset:32768
	ds_read_b128 v[12:15], v143 offset:33792
	ds_read_b128 v[16:19], v143 offset:34816
	ds_read_b128 v[20:23], v143 offset:35840
	ds_read_b128 v[24:27], v143 offset:36864
	ds_read_b128 v[28:31], v143 offset:37888
	ds_read_b128 v[32:35], v143 offset:38912
	ds_read_b128 v[36:39], v143 offset:39936
	s_addc_u32 s77, s57, 0
	s_nop 0
	global_load_lds_dwordx4 v147, s[76:77]
	s_mov_b32 m0, s23
	s_nop 0
	global_load_lds_dwordx4 v140, s[76:77]
	s_waitcnt vmcnt(8)
	s_waitcnt lgkmcnt(0)
	s_barrier
	s_setprio 1
	s_waitcnt lgkmcnt(0)
	v_mfma_f32_16x16x128_f8f6f4 v[124:127], v[0:7], v[8:15], v[124:127]
	v_mfma_f32_16x16x128_f8f6f4 v[116:119], v[148:155], v[8:15], v[116:119]
	v_mfma_f32_16x16x128_f8f6f4 v[108:111], v[0:7], v[16:23], v[108:111]
	v_mfma_f32_16x16x128_f8f6f4 v[100:103], v[148:155], v[16:23], v[100:103]
	v_mfma_f32_16x16x128_f8f6f4 v[92:95], v[0:7], v[24:31], v[212:215]
	v_mfma_f32_16x16x128_f8f6f4 v[84:87], v[148:155], v[24:31], v[216:219]
	v_mfma_f32_16x16x128_f8f6f4 v[76:79], v[0:7], v[32:39], v[220:223]
	v_mfma_f32_16x16x128_f8f6f4 v[68:71], v[148:155], v[32:39], v[224:227]
	v_mfma_f32_16x16x128_f8f6f4 v[120:123], v[156:163], v[8:15], v[120:123]
	v_mfma_f32_16x16x128_f8f6f4 v[112:115], v[164:171], v[8:15], v[112:115]
	v_mfma_f32_16x16x128_f8f6f4 v[104:107], v[156:163], v[16:23], v[104:107]
	v_mfma_f32_16x16x128_f8f6f4 v[96:99], v[164:171], v[16:23], v[96:99]
	v_mfma_f32_16x16x128_f8f6f4 v[88:91], v[156:163], v[24:31], v[180:183]
	v_mfma_f32_16x16x128_f8f6f4 v[80:83], v[164:171], v[24:31], v[184:187]
	v_mfma_f32_16x16x128_f8f6f4 v[72:75], v[156:163], v[32:39], v[188:191]
	v_mfma_f32_16x16x128_f8f6f4 v[64:67], v[164:171], v[32:39], v[192:195]
	s_setprio 0
	s_barrier
	ds_read_b128 v[172:175], v143 offset:49152
	ds_read_b128 v[176:179], v143 offset:50176
	ds_read_b128 v[180:183], v143 offset:51200
	ds_read_b128 v[184:187], v143 offset:52224
	ds_read_b128 v[188:191], v143 offset:53248
	ds_read_b128 v[192:195], v143 offset:54272
	ds_read_b128 v[196:199], v143 offset:55296
	ds_read_b128 v[200:203], v143 offset:56320
	s_add_i32 s76, s78, s3
	s_add_u32 vcc_lo, s58, s12
	s_addc_u32 vcc_hi, s59, s13
	s_mov_b32 m0, s76
	s_nop 0
	global_load_lds_dwordx4 v254, vcc
	s_add_i32 m0, s76, 0x2000
	s_add_u32 vcc_lo, s58, s12
	s_addc_u32 vcc_hi, s59, s13
	s_add_u32 s58, s58, 0x40080
	global_load_lds_dwordx4 v141, vcc
	s_addc_u32 s59, s59, 0
	s_add_i32 s76, s79, s3
	s_mov_b32 m0, s76
	s_nop 0
	global_load_lds_dwordx4 v254, s[58:59]
	s_add_i32 m0, s76, 0x2000
	s_nop 0
	global_load_lds_dwordx4 v141, s[58:59]
	s_mov_b32 m0, s33
	s_add_u32 vcc_lo, s56, s12
	s_addc_u32 vcc_hi, s57, s13
	v_mov_b32_e32 v128, v140
	global_load_lds_dwordx4 v147, vcc
	s_mov_b32 m0, s51
	s_add_u32 vcc_lo, s56, s12
	s_addc_u32 vcc_hi, s57, s13
	global_load_lds_dwordx4 v140, vcc
	s_waitcnt vmcnt(8)
	s_waitcnt lgkmcnt(0)
	s_barrier
	s_setprio 1
	s_waitcnt lgkmcnt(0)
	v_mfma_f32_16x16x128_f8f6f4 v[60:63], v[0:7], v[172:179], v[60:63]
	v_mfma_f32_16x16x128_f8f6f4 v[52:55], v[148:155], v[172:179], v[52:55]
	v_mfma_f32_16x16x128_f8f6f4 v[44:47], v[0:7], v[180:187], v[44:47]
	v_mfma_f32_16x16x128_f8f6f4 v[36:39], v[148:155], v[180:187], v[204:207]
	v_mfma_f32_16x16x128_f8f6f4 v[28:31], v[0:7], v[188:195], v[208:211]
	v_mfma_f32_16x16x128_f8f6f4 v[20:23], v[148:155], v[188:195], v[230:233]
	v_mfma_f32_16x16x128_f8f6f4 v[12:15], v[0:7], v[196:203], v[234:237]
	v_mfma_f32_16x16x128_f8f6f4 v[4:7], v[148:155], v[196:203], v[238:241]
	v_mfma_f32_16x16x128_f8f6f4 v[56:59], v[156:163], v[172:179], v[56:59]
	v_mfma_f32_16x16x128_f8f6f4 v[48:51], v[164:171], v[172:179], v[48:51]
	v_mfma_f32_16x16x128_f8f6f4 v[40:43], v[156:163], v[180:187], v[40:43]
	v_mfma_f32_16x16x128_f8f6f4 v[32:35], v[164:171], v[180:187], v[242:245]
	v_mfma_f32_16x16x128_f8f6f4 v[24:27], v[156:163], v[188:195], v[246:249]
	v_mfma_f32_16x16x128_f8f6f4 v[16:19], v[164:171], v[188:195], v[250:253]
	v_mfma_f32_16x16x128_f8f6f4 v[8:11], v[156:163], v[196:203], v[132:135]
	v_mfma_f32_16x16x128_f8f6f4 v[0:3], v[164:171], v[196:203], v[136:139]
	s_setprio 0
	s_barrier
	s_add_i32 s74, s74, 2
	s_add_u32 s54, s54, 0x100
	s_addc_u32 s55, s55, 0
	s_add_u32 s72, s72, 0x100
	s_addc_u32 s73, s73, 0
	s_cmp_gt_u32 s74, 13
	s_cbranch_scc1 .LBB0_813

; #define PG8_STAGE(bufoff, gbase, voff) do { _Pragma("unroll") for (int _i = 0; _i < 2; ++_i) \
;         { unsigned _vo = (voff)[_i]; asm volatile("" : "+v"(_vo));     \
;         __builtin_amdgcn_global_load_lds((const unsigned*)((const char*)(gbase) + _vo), (PG8_LAS unsigned*)(lds + (bufoff) + ldsw + _i * 8192), 16, 0, 0); } } while (0)
; #define PG8_LDA(dst, b, h) do { _Pragma("unroll") for (int m = 0; m < 4; ++m) _Pragma("unroll") for (int k = 0; k < 2; ++k) dst[m][k] = *(const PG8_LAS bf16x8*)(lds + PG8_SA(b, h) + aoff + m * 2048 + k * 1024); } while (0)
; #define PG8_LDB(dst, b, h) do { _Pragma("unroll") for (int n = 0; n < 2; ++n) _Pragma("unroll") for (int k = 0; k < 2; ++k) dst[n][k] = *(const PG8_LAS bf16x8*)(lds + PG8_SB(b, h) + boff + n * 2048 + k * 1024); } while (0)
; #define PG8_WAIT_V(n) asm volatile("s_waitcnt vmcnt(" #n ")" ::: "memory")
; #define PG8_WAIT_L(n) asm volatile("s_waitcnt lgkmcnt(" #n ")" ::: "memory")
; #define PG8_BAR __builtin_amdgcn_s_barrier()
; #define PG8_SCHED __builtin_amdgcn_sched_barrier(0)
; template <class Epi, class Sched, bool ALIGN_EPI = false, bool SP2 = false, bool ABLK = false, bool F8 = false>
; __device__ __forceinline__ void gemm_phase(PG8_LAS unsigned char* lds, const Gemm g, const Sched& S, const Epi& E, const int wave_s) {
;     ...
;             PG8_LDB(B0, 0, 0); PG8_LDB(B1, 0, 1); PG8_SCHED; PG8_LDA(At, 0, 0); PG8_STAGE(PG8_SA(1, 1), a1 + hstepA, voffA);
;             PG8_WAIT_V(8); PG8_WAIT_L(0); PG8_BAR; PG8_MMA(0, 0, At, B0); PG8_MMA(0, 1, At, B1); PG8_BAR; PG8_SCHED;
;             PG8_LDA(At, 0, 1); PG8_STAGE(PG8_SB(0, 0), b2, voffB); PG8_STAGE(PG8_SB(0, 1), b2 + hstep, voffB); PG8_STAGE(PG8_SA(0, 0), a2, voffA);
;             PG8_WAIT_V(8); PG8_WAIT_L(0); PG8_BAR; PG8_MMA(1, 0, At, B0); PG8_MMA(1, 1, At, B1); PG8_BAR; PG8_SCHED;
.LBB0_894:
	ds_read_b128 v[104:107], v230
	ds_read_b128 v[116:119], v230 offset:1024
	ds_read_b128 v[128:131], v230 offset:2048
	ds_read_b128 v[140:143], v230 offset:3072
	ds_read_b128 v[144:147], v231
	ds_read_b128 v[148:151], v231 offset:1024
	ds_read_b128 v[152:155], v231 offset:2048
	ds_read_b128 v[156:159], v231 offset:3072
	s_add_u32 s46, s44, 0x4000
	s_addc_u32 s47, s45, 0
	s_cmpk_eq_i32 s62, 0x54
	s_cselect_b32 s50, s12, s46
	s_cselect_b32 s51, s13, s47
	s_cselect_b32 s48, s42, s60
	s_cselect_b32 s49, s43, s61
	s_add_u32 s46, s50, 0x8000
	s_addc_u32 s47, s51, 0
	ds_read_b128 v[160:163], v232
	ds_read_b128 v[164:167], v232 offset:1024
	ds_read_b128 v[168:171], v232 offset:2048
	ds_read_b128 v[172:175], v232 offset:3072
	ds_read_b128 v[176:179], v232 offset:4096
	ds_read_b128 v[180:183], v232 offset:5120
	ds_read_b128 v[190:193], v232 offset:6144
	ds_read_b128 v[194:197], v232 offset:7168
	s_add_i32 m0, s20, 0xc000
	s_nop 0
	global_load_lds_dwordx4 v222, s[44:45]
	s_add_i32 m0, s20, 0xe000
	s_nop 0
	global_load_lds_dwordx4 v224, s[44:45]
	s_waitcnt vmcnt(8)
	s_waitcnt lgkmcnt(0)
	s_barrier
	s_setprio 1
	s_waitcnt lgkmcnt(0)
	v_mfma_f32_16x16x32_bf16 v[136:139], v[104:107], v[160:163], v[136:139]
	v_mfma_f32_16x16x32_bf16 v[132:135], v[128:131], v[160:163], v[132:135]
	v_mfma_f32_16x16x32_bf16 v[112:115], v[104:107], v[168:171], v[112:115]
	v_mfma_f32_16x16x32_bf16 v[108:111], v[128:131], v[168:171], v[108:111]
	v_mfma_f32_16x16x32_bf16 v[92:95], v[104:107], v[176:179], v[92:95]
	v_mfma_f32_16x16x32_bf16 v[88:91], v[128:131], v[176:179], v[88:91]
	v_mfma_f32_16x16x32_bf16 v[76:79], v[104:107], v[190:193], v[76:79]
	v_mfma_f32_16x16x32_bf16 v[72:75], v[128:131], v[190:193], v[72:75]
	v_mfma_f32_16x16x32_bf16 v[136:139], v[116:119], v[164:167], v[136:139]
	v_mfma_f32_16x16x32_bf16 v[132:135], v[140:143], v[164:167], v[132:135]
	v_mfma_f32_16x16x32_bf16 v[112:115], v[116:119], v[172:175], v[112:115]
	v_mfma_f32_16x16x32_bf16 v[108:111], v[140:143], v[172:175], v[108:111]
	v_mfma_f32_16x16x32_bf16 v[92:95], v[116:119], v[180:183], v[92:95]
	v_mfma_f32_16x16x32_bf16 v[88:91], v[140:143], v[180:183], v[88:91]
	v_mfma_f32_16x16x32_bf16 v[76:79], v[116:119], v[194:197], v[76:79]
	v_mfma_f32_16x16x32_bf16 v[72:75], v[140:143], v[194:197], v[72:75]
	v_mfma_f32_16x16x32_bf16 v[124:127], v[144:147], v[160:163], v[124:127]
	v_mfma_f32_16x16x32_bf16 v[120:123], v[152:155], v[160:163], v[120:123]
	v_mfma_f32_16x16x32_bf16 v[100:103], v[144:147], v[168:171], v[100:103]
	v_mfma_f32_16x16x32_bf16 v[96:99], v[152:155], v[168:171], v[96:99]
	v_mfma_f32_16x16x32_bf16 v[84:87], v[144:147], v[176:179], v[84:87]
	v_mfma_f32_16x16x32_bf16 v[80:83], v[152:155], v[176:179], v[80:83]
	v_mfma_f32_16x16x32_bf16 v[68:71], v[144:147], v[190:193], v[68:71]
	v_mfma_f32_16x16x32_bf16 v[64:67], v[152:155], v[190:193], v[64:67]
	v_mfma_f32_16x16x32_bf16 v[124:127], v[148:151], v[164:167], v[124:127]
	v_mfma_f32_16x16x32_bf16 v[120:123], v[156:159], v[164:167], v[120:123]
	v_mfma_f32_16x16x32_bf16 v[100:103], v[148:151], v[172:175], v[100:103]
	v_mfma_f32_16x16x32_bf16 v[96:99], v[156:159], v[172:175], v[96:99]
	v_mfma_f32_16x16x32_bf16 v[84:87], v[148:151], v[180:183], v[84:87]
	v_mfma_f32_16x16x32_bf16 v[80:83], v[156:159], v[180:183], v[80:83]
	v_mfma_f32_16x16x32_bf16 v[68:71], v[148:151], v[194:197], v[68:71]
	v_mfma_f32_16x16x32_bf16 v[64:67], v[156:159], v[194:197], v[64:67]
	s_setprio 0
	s_barrier
	s_add_i32 s63, s54, s3
	ds_read_b128 v[160:163], v232 offset:16384
	ds_read_b128 v[164:167], v232 offset:17408
	ds_read_b128 v[168:171], v232 offset:18432
	ds_read_b128 v[172:175], v232 offset:19456
	ds_read_b128 v[176:179], v232 offset:20480
	ds_read_b128 v[180:183], v232 offset:21504
	ds_read_b128 v[190:193], v232 offset:22528
	ds_read_b128 v[194:197], v232 offset:23552
	s_mov_b32 m0, s63
	s_nop 0
	global_load_lds_dwordx4 v223, s[48:49]
	s_add_i32 m0, s63, 0x2000
	s_add_u32 s64, s48, 0x160000
	global_load_lds_dwordx4 v225, s[48:49]
	s_addc_u32 s65, s49, 0
	s_add_i32 s63, s55, s3
	s_mov_b32 m0, s63
	s_nop 0
	global_load_lds_dwordx4 v223, s[64:65]
	s_add_i32 m0, s63, 0x2000
	s_nop 0
	global_load_lds_dwordx4 v225, s[64:65]
	s_mov_b32 m0, s20
	s_nop 0
	global_load_lds_dwordx4 v222, s[50:51]
	s_mov_b32 m0, s21
	s_nop 0
	global_load_lds_dwordx4 v224, s[50:51]
	s_waitcnt vmcnt(8)
	s_waitcnt lgkmcnt(0)
	s_barrier
	s_setprio 1
	s_waitcnt lgkmcnt(0)
	v_mfma_f32_16x16x32_bf16 v[60:63], v[104:107], v[160:163], v[60:63]
	v_mfma_f32_16x16x32_bf16 v[56:59], v[128:131], v[160:163], v[56:59]
	v_mfma_f32_16x16x32_bf16 v[44:47], v[104:107], v[168:171], v[44:47]
	v_mfma_f32_16x16x32_bf16 v[40:43], v[128:131], v[168:171], v[40:43]
	v_mfma_f32_16x16x32_bf16 v[28:31], v[104:107], v[176:179], v[28:31]
	v_mfma_f32_16x16x32_bf16 v[24:27], v[128:131], v[176:179], v[24:27]
	v_mfma_f32_16x16x32_bf16 v[12:15], v[104:107], v[190:193], v[12:15]
	v_mfma_f32_16x16x32_bf16 v[8:11], v[128:131], v[190:193], v[8:11]
	v_mfma_f32_16x16x32_bf16 v[60:63], v[116:119], v[164:167], v[60:63]
	v_mfma_f32_16x16x32_bf16 v[56:59], v[140:143], v[164:167], v[56:59]
	v_mfma_f32_16x16x32_bf16 v[44:47], v[116:119], v[172:175], v[44:47]
	v_mfma_f32_16x16x32_bf16 v[40:43], v[140:143], v[172:175], v[40:43]
	v_mfma_f32_16x16x32_bf16 v[28:31], v[116:119], v[180:183], v[28:31]
	v_mfma_f32_16x16x32_bf16 v[24:27], v[140:143], v[180:183], v[24:27]
	v_mfma_f32_16x16x32_bf16 v[12:15], v[116:119], v[194:197], v[12:15]
	v_mfma_f32_16x16x32_bf16 v[8:11], v[140:143], v[194:197], v[8:11]
	v_mfma_f32_16x16x32_bf16 v[52:55], v[144:147], v[160:163], v[52:55]
	v_mfma_f32_16x16x32_bf16 v[48:51], v[152:155], v[160:163], v[48:51]
	v_mfma_f32_16x16x32_bf16 v[36:39], v[144:147], v[168:171], v[36:39]
	v_mfma_f32_16x16x32_bf16 v[32:35], v[152:155], v[168:171], v[32:35]
	v_mfma_f32_16x16x32_bf16 v[20:23], v[144:147], v[176:179], v[20:23]
	v_mfma_f32_16x16x32_bf16 v[16:19], v[152:155], v[176:179], v[16:19]
	v_mfma_f32_16x16x32_bf16 v[4:7], v[144:147], v[190:193], v[4:7]
	v_mfma_f32_16x16x32_bf16 v[0:3], v[152:155], v[190:193], v[0:3]
	v_mfma_f32_16x16x32_bf16 v[52:55], v[148:151], v[164:167], v[52:55]
	v_mfma_f32_16x16x32_bf16 v[48:51], v[156:159], v[164:167], v[48:51]
	v_mfma_f32_16x16x32_bf16 v[36:39], v[148:151], v[172:175], v[36:39]
	v_mfma_f32_16x16x32_bf16 v[32:35], v[156:159], v[172:175], v[32:35]
	v_mfma_f32_16x16x32_bf16 v[20:23], v[148:151], v[180:183], v[20:23]
	v_mfma_f32_16x16x32_bf16 v[16:19], v[156:159], v[180:183], v[16:19]
	v_mfma_f32_16x16x32_bf16 v[4:7], v[148:151], v[194:197], v[4:7]
	v_mfma_f32_16x16x32_bf16 v[0:3], v[156:159], v[194:197], v[0:3]
	s_setprio 0
	s_barrier
; #define PG8_STAGE(bufoff, gbase, voff) do { _Pragma("unroll") for (int _i = 0; _i < 2; ++_i) \
;         { unsigned _vo = (voff)[_i]; asm volatile("" : "+v"(_vo));     \
;         __builtin_amdgcn_global_load_lds((const unsigned*)((const char*)(gbase) + _vo), (PG8_LAS unsigned*)(lds + (bufoff) + ldsw + _i * 8192), 16, 0, 0); } } while (0)
; #define PG8_LDA(dst, b, h) do { _Pragma("unroll") for (int m = 0; m < 4; ++m) _Pragma("unroll") for (int k = 0; k < 2; ++k) dst[m][k] = *(const PG8_LAS bf16x8*)(lds + PG8_SA(b, h) + aoff + m * 2048 + k * 1024); } while (0)
; #define PG8_LDB(dst, b, h) do { _Pragma("unroll") for (int n = 0; n < 2; ++n) _Pragma("unroll") for (int k = 0; k < 2; ++k) dst[n][k] = *(const PG8_LAS bf16x8*)(lds + PG8_SB(b, h) + boff + n * 2048 + k * 1024); } while (0)
; #define PG8_WAIT_V(n) asm volatile("s_waitcnt vmcnt(" #n ")" ::: "memory")
; #define PG8_WAIT_L(n) asm volatile("s_waitcnt lgkmcnt(" #n ")" ::: "memory")
; #define PG8_BAR __builtin_amdgcn_s_barrier()
; #define PG8_SCHED __builtin_amdgcn_sched_barrier(0)
; template <class Epi, class Sched, bool ALIGN_EPI = false, bool SP2 = false, bool ABLK = false, bool F8 = false>
; __device__ __forceinline__ void gemm_phase(PG8_LAS unsigned char* lds, const Gemm g, const Sched& S, const Epi& E, const int wave_s) {
;     ...
;             PG8_LDB(B0, 1, 0); PG8_LDB(B1, 1, 1); PG8_SCHED; PG8_LDA(At, 1, 0); PG8_STAGE(PG8_SA(0, 1), a2 + hstepA, voffA);
;             PG8_WAIT_V(8); PG8_WAIT_L(0); PG8_BAR; PG8_MMA(0, 0, At, B0); PG8_MMA(0, 1, At, B1); PG8_BAR; PG8_SCHED;
;             PG8_LDA(At, 1, 1); PG8_STAGE(PG8_SB(1, 0), b3, voffB); PG8_STAGE(PG8_SB(1, 1), b3 + hstep, voffB); PG8_STAGE(PG8_SA(1, 0), a3, voffA);
;             PG8_WAIT_V(8); PG8_WAIT_L(0); PG8_BAR; PG8_MMA(1, 0, At, B0); PG8_MMA(1, 1, At, B1); PG8_BAR; PG8_SCHED;
;     ...
;         if constexpr (ALIGN_EPI) { if (wr == 0) PG8_BAR; }
	s_add_i32 s63, 0, 0x18000
	s_add_i32 s64, 0, 0x1c000
	v_add_u32_e32 v140, s63, v227
	v_add_u32_e32 v156, s64, v227
	ds_read_b128 v[104:107], v140
	ds_read_b128 v[116:119], v140 offset:1024
	ds_read_b128 v[128:131], v140 offset:2048
	ds_read_b128 v[140:143], v140 offset:3072
	ds_read_b128 v[144:147], v156
	ds_read_b128 v[148:151], v156 offset:1024
	ds_read_b128 v[152:155], v156 offset:2048
	ds_read_b128 v[156:159], v156 offset:3072
	s_add_u32 s50, s50, 0x4000
	s_mov_b32 m0, s22
	ds_read_b128 v[160:163], v232 offset:32768
	ds_read_b128 v[164:167], v232 offset:33792
	ds_read_b128 v[168:171], v232 offset:34816
	ds_read_b128 v[172:175], v232 offset:35840
	ds_read_b128 v[176:179], v232 offset:36864
	ds_read_b128 v[180:183], v232 offset:37888
	ds_read_b128 v[190:193], v232 offset:38912
	ds_read_b128 v[194:197], v232 offset:39936
	s_addc_u32 s51, s51, 0
	s_nop 0
	global_load_lds_dwordx4 v222, s[50:51]
	s_mov_b32 m0, s23
	s_nop 0
	global_load_lds_dwordx4 v224, s[50:51]
	s_waitcnt vmcnt(8)
	s_waitcnt lgkmcnt(0)
	s_barrier
	s_setprio 1
	s_waitcnt lgkmcnt(0)
	v_mfma_f32_16x16x32_bf16 v[136:139], v[104:107], v[160:163], v[136:139]
	v_mfma_f32_16x16x32_bf16 v[132:135], v[128:131], v[160:163], v[132:135]
	v_mfma_f32_16x16x32_bf16 v[112:115], v[104:107], v[168:171], v[112:115]
	v_mfma_f32_16x16x32_bf16 v[108:111], v[128:131], v[168:171], v[108:111]
	v_mfma_f32_16x16x32_bf16 v[92:95], v[104:107], v[176:179], v[92:95]
	v_mfma_f32_16x16x32_bf16 v[88:91], v[128:131], v[176:179], v[88:91]
	v_mfma_f32_16x16x32_bf16 v[76:79], v[104:107], v[190:193], v[76:79]
	v_mfma_f32_16x16x32_bf16 v[72:75], v[128:131], v[190:193], v[72:75]
	v_mfma_f32_16x16x32_bf16 v[136:139], v[116:119], v[164:167], v[136:139]
	v_mfma_f32_16x16x32_bf16 v[132:135], v[140:143], v[164:167], v[132:135]
	v_mfma_f32_16x16x32_bf16 v[112:115], v[116:119], v[172:175], v[112:115]
	v_mfma_f32_16x16x32_bf16 v[108:111], v[140:143], v[172:175], v[108:111]
	v_mfma_f32_16x16x32_bf16 v[92:95], v[116:119], v[180:183], v[92:95]
	v_mfma_f32_16x16x32_bf16 v[88:91], v[140:143], v[180:183], v[88:91]
	v_mfma_f32_16x16x32_bf16 v[76:79], v[116:119], v[194:197], v[76:79]
	v_mfma_f32_16x16x32_bf16 v[72:75], v[140:143], v[194:197], v[72:75]
	v_mfma_f32_16x16x32_bf16 v[124:127], v[144:147], v[160:163], v[124:127]
	v_mfma_f32_16x16x32_bf16 v[120:123], v[152:155], v[160:163], v[120:123]
	v_mfma_f32_16x16x32_bf16 v[100:103], v[144:147], v[168:171], v[100:103]
	v_mfma_f32_16x16x32_bf16 v[96:99], v[152:155], v[168:171], v[96:99]
	v_mfma_f32_16x16x32_bf16 v[84:87], v[144:147], v[176:179], v[84:87]
	v_mfma_f32_16x16x32_bf16 v[80:83], v[152:155], v[176:179], v[80:83]
	v_mfma_f32_16x16x32_bf16 v[68:71], v[144:147], v[190:193], v[68:71]
	v_mfma_f32_16x16x32_bf16 v[64:67], v[152:155], v[190:193], v[64:67]
	v_mfma_f32_16x16x32_bf16 v[124:127], v[148:151], v[164:167], v[124:127]
	v_mfma_f32_16x16x32_bf16 v[120:123], v[156:159], v[164:167], v[120:123]
	v_mfma_f32_16x16x32_bf16 v[100:103], v[148:151], v[172:175], v[100:103]
	v_mfma_f32_16x16x32_bf16 v[96:99], v[156:159], v[172:175], v[96:99]
	v_mfma_f32_16x16x32_bf16 v[84:87], v[148:151], v[180:183], v[84:87]
	v_mfma_f32_16x16x32_bf16 v[80:83], v[156:159], v[180:183], v[80:83]
	v_mfma_f32_16x16x32_bf16 v[68:71], v[148:151], v[194:197], v[68:71]
	v_mfma_f32_16x16x32_bf16 v[64:67], v[156:159], v[194:197], v[64:67]
	s_setprio 0
	s_barrier
	ds_read_b128 v[160:163], v232 offset:49152
	ds_read_b128 v[164:167], v232 offset:50176
	ds_read_b128 v[168:171], v232 offset:51200
	ds_read_b128 v[172:175], v232 offset:52224
	ds_read_b128 v[176:179], v232 offset:53248
	ds_read_b128 v[180:183], v232 offset:54272
	ds_read_b128 v[190:193], v232 offset:55296
	ds_read_b128 v[194:197], v232 offset:56320
	s_add_i32 s50, s63, s3
	s_add_u32 vcc_lo, s48, s40
	s_addc_u32 vcc_hi, s49, s41
	s_mov_b32 m0, s50
	s_nop 0
	global_load_lds_dwordx4 v223, vcc
	s_add_i32 m0, s50, 0x2000
	s_nop 0
	s_add_u32 vcc_lo, s48, s40
	s_addc_u32 vcc_hi, s49, s41
	s_add_u32 s48, s48, 0x160080
	s_addc_u32 s49, s49, 0
	s_add_i32 s50, s64, s3
	global_load_lds_dwordx4 v225, vcc
	s_mov_b32 m0, s50
	s_nop 0
	global_load_lds_dwordx4 v223, s[48:49]
	s_add_i32 m0, s50, 0x2000
	s_nop 0
	global_load_lds_dwordx4 v225, s[48:49]
	s_mov_b32 m0, s52
	s_nop 0
	global_load_lds_dwordx4 v222, s[46:47]
	v_mov_b32_e32 v184, v224
	s_mov_b32 m0, s53
	s_nop 0
	global_load_lds_dwordx4 v224, s[46:47]
	s_waitcnt vmcnt(8)
	s_waitcnt lgkmcnt(0)
	s_barrier
	s_setprio 1
	s_waitcnt lgkmcnt(0)
	v_mfma_f32_16x16x32_bf16 v[60:63], v[104:107], v[160:163], v[60:63]
	v_mfma_f32_16x16x32_bf16 v[56:59], v[128:131], v[160:163], v[56:59]
	v_mfma_f32_16x16x32_bf16 v[44:47], v[104:107], v[168:171], v[44:47]
	v_mfma_f32_16x16x32_bf16 v[40:43], v[128:131], v[168:171], v[40:43]
	v_mfma_f32_16x16x32_bf16 v[28:31], v[104:107], v[176:179], v[28:31]
	v_mfma_f32_16x16x32_bf16 v[24:27], v[128:131], v[176:179], v[24:27]
	v_mfma_f32_16x16x32_bf16 v[12:15], v[104:107], v[190:193], v[12:15]
	v_mfma_f32_16x16x32_bf16 v[8:11], v[128:131], v[190:193], v[8:11]
	v_mfma_f32_16x16x32_bf16 v[60:63], v[116:119], v[164:167], v[60:63]
	v_mfma_f32_16x16x32_bf16 v[56:59], v[140:143], v[164:167], v[56:59]
	v_mfma_f32_16x16x32_bf16 v[44:47], v[116:119], v[172:175], v[44:47]
	v_mfma_f32_16x16x32_bf16 v[40:43], v[140:143], v[172:175], v[40:43]
	v_mfma_f32_16x16x32_bf16 v[28:31], v[116:119], v[180:183], v[28:31]
	v_mfma_f32_16x16x32_bf16 v[24:27], v[140:143], v[180:183], v[24:27]
	v_mfma_f32_16x16x32_bf16 v[12:15], v[116:119], v[194:197], v[12:15]
	v_mfma_f32_16x16x32_bf16 v[8:11], v[140:143], v[194:197], v[8:11]
	v_mfma_f32_16x16x32_bf16 v[52:55], v[144:147], v[160:163], v[52:55]
	v_mfma_f32_16x16x32_bf16 v[48:51], v[152:155], v[160:163], v[48:51]
	v_mfma_f32_16x16x32_bf16 v[36:39], v[144:147], v[168:171], v[36:39]
	v_mfma_f32_16x16x32_bf16 v[32:35], v[152:155], v[168:171], v[32:35]
	v_mfma_f32_16x16x32_bf16 v[20:23], v[144:147], v[176:179], v[20:23]
	v_mfma_f32_16x16x32_bf16 v[16:19], v[152:155], v[176:179], v[16:19]
	v_mfma_f32_16x16x32_bf16 v[4:7], v[144:147], v[190:193], v[4:7]
	v_mfma_f32_16x16x32_bf16 v[0:3], v[152:155], v[190:193], v[0:3]
	v_mfma_f32_16x16x32_bf16 v[52:55], v[148:151], v[164:167], v[52:55]
	v_mfma_f32_16x16x32_bf16 v[48:51], v[156:159], v[164:167], v[48:51]
	v_mfma_f32_16x16x32_bf16 v[36:39], v[148:151], v[172:175], v[36:39]
	v_mfma_f32_16x16x32_bf16 v[32:35], v[156:159], v[172:175], v[32:35]
	v_mfma_f32_16x16x32_bf16 v[20:23], v[148:151], v[180:183], v[20:23]
	v_mfma_f32_16x16x32_bf16 v[16:19], v[156:159], v[180:183], v[16:19]
	v_mfma_f32_16x16x32_bf16 v[4:7], v[148:151], v[194:197], v[4:7]
	v_mfma_f32_16x16x32_bf16 v[0:3], v[156:159], v[194:197], v[0:3]
	s_setprio 0
	s_barrier
	s_add_i32 s62, s62, 2
	s_add_u32 s60, s60, 0x100
	s_addc_u32 s61, s61, 0
	s_add_u32 s44, s44, 0x10000
	s_addc_u32 s45, s45, 0
	s_cmpk_gt_u32 s62, 0x55
	s_cbranch_scc0 .LBB0_894
	s_and_b64 vcc, exec, s[36:37]
	s_cbranch_vccz .LBB0_897
	s_barrier

; #define PG8_STAGE(bufoff, gbase, voff) do { _Pragma("unroll") for (int _i = 0; _i < 2; ++_i) \
;         { unsigned _vo = (voff)[_i]; asm volatile("" : "+v"(_vo));     \
;         __builtin_amdgcn_global_load_lds((const unsigned*)((const char*)(gbase) + _vo), (PG8_LAS unsigned*)(lds + (bufoff) + ldsw + _i * 8192), 16, 0, 0); } } while (0)
; #define PG8_LDA(dst, b, h) do { _Pragma("unroll") for (int m = 0; m < 4; ++m) _Pragma("unroll") for (int k = 0; k < 2; ++k) dst[m][k] = *(const PG8_LAS bf16x8*)(lds + PG8_SA(b, h) + aoff + m * 2048 + k * 1024); } while (0)
; #define PG8_LDB(dst, b, h) do { _Pragma("unroll") for (int n = 0; n < 2; ++n) _Pragma("unroll") for (int k = 0; k < 2; ++k) dst[n][k] = *(const PG8_LAS bf16x8*)(lds + PG8_SB(b, h) + boff + n * 2048 + k * 1024); } while (0)
; #define PG8_WAIT_V(n) asm volatile("s_waitcnt vmcnt(" #n ")" ::: "memory")
; #define PG8_WAIT_L(n) asm volatile("s_waitcnt lgkmcnt(" #n ")" ::: "memory")
; #define PG8_BAR __builtin_amdgcn_s_barrier()
; #define PG8_SCHED __builtin_amdgcn_sched_barrier(0)
; template <class Epi, class Sched, bool ALIGN_EPI = false, bool SP2 = false, bool ABLK = false, bool F8 = false>
; __device__ __forceinline__ void gemm_phase(PG8_LAS unsigned char* lds, const Gemm g, const Sched& S, const Epi& E, const int wave_s) {
;     ...
;             PG8_LDB(B0, 0, 0); PG8_LDB(B1, 0, 1); PG8_SCHED; PG8_LDA(At, 0, 0); PG8_STAGE(PG8_SA(1, 1), a1 + hstepA, voffA);
;             PG8_WAIT_V(8); PG8_WAIT_L(0); PG8_BAR; PG8_MMA(0, 0, At, B0); PG8_MMA(0, 1, At, B1); PG8_BAR; PG8_SCHED;
;             PG8_LDA(At, 0, 1); PG8_STAGE(PG8_SB(0, 0), b2, voffB); PG8_STAGE(PG8_SB(0, 1), b2 + hstep, voffB); PG8_STAGE(PG8_SA(0, 0), a2, voffA);
.LBB0_985:
	ds_read_b128 v[0:3], v141
	ds_read_b128 v[4:7], v141 offset:1024
	ds_read_b128 v[8:11], v141 offset:2048
	ds_read_b128 v[12:15], v141 offset:3072
	ds_read_b128 v[16:19], v142
	ds_read_b128 v[20:23], v142 offset:1024
	ds_read_b128 v[24:27], v142 offset:2048
	ds_read_b128 v[28:31], v142 offset:3072
	s_ashr_i32 s53, s52, 31
	s_lshl_b64 s[54:55], s[52:53], 17
	s_add_u32 s54, s21, s54
	s_addc_u32 s55, s22, s55
	s_and_b64 s[56:57], s[8:9], exec
	s_cselect_b32 s63, s55, s61
	s_cselect_b32 s62, s54, s60
	s_ashr_i32 s51, s50, 31
	s_lshl_b64 s[56:57], s[50:51], 17
	s_add_u32 s56, s18, s56
	s_addc_u32 s57, s19, s57
	s_and_b64 s[66:67], s[8:9], exec
	s_cselect_b32 s67, s57, s65
	s_cselect_b32 s66, s56, s64
	s_add_u32 s84, s60, 0x10080
	s_mov_b32 m0, s77
	ds_read_b128 v[32:35], v143
	ds_read_b128 v[36:39], v143 offset:1024
	ds_read_b128 v[40:43], v143 offset:2048
	ds_read_b128 v[44:47], v143 offset:3072
	ds_read_b128 v[48:51], v143 offset:4096
	ds_read_b128 v[52:55], v143 offset:5120
	ds_read_b128 v[56:59], v143 offset:6144
	ds_read_b128 v[60:63], v143 offset:7168
	s_addc_u32 s85, s61, 0
	s_nop 0
	global_load_lds_dwordx4 v134, s[84:85]
	s_mov_b32 m0, s78
	s_nop 0
	global_load_lds_dwordx4 v136, s[84:85]
	s_waitcnt vmcnt(8)
	s_waitcnt lgkmcnt(0)
	s_barrier
	s_setprio 1
	s_waitcnt lgkmcnt(0)
	v_mfma_f32_16x16x32_bf16 v[64:67], v[0:3], v[32:35], 0
	v_mfma_f32_16x16x32_bf16 v[68:71], v[8:11], v[32:35], 0
	v_mfma_f32_16x16x32_bf16 v[72:75], v[0:3], v[40:43], 0
	v_mfma_f32_16x16x32_bf16 v[76:79], v[8:11], v[40:43], 0
	v_mfma_f32_16x16x32_bf16 v[80:83], v[0:3], v[48:51], 0
	v_mfma_f32_16x16x32_bf16 v[84:87], v[8:11], v[48:51], 0
	v_mfma_f32_16x16x32_bf16 v[88:91], v[0:3], v[56:59], 0
	v_mfma_f32_16x16x32_bf16 v[92:95], v[8:11], v[56:59], 0
	v_mfma_f32_16x16x32_bf16 v[64:67], v[4:7], v[36:39], v[64:67]
	v_mfma_f32_16x16x32_bf16 v[68:71], v[12:15], v[36:39], v[68:71]
	v_mfma_f32_16x16x32_bf16 v[72:75], v[4:7], v[44:47], v[72:75]
	v_mfma_f32_16x16x32_bf16 v[76:79], v[12:15], v[44:47], v[76:79]
	v_mfma_f32_16x16x32_bf16 v[80:83], v[4:7], v[52:55], v[80:83]
	v_mfma_f32_16x16x32_bf16 v[84:87], v[12:15], v[52:55], v[84:87]
	v_mfma_f32_16x16x32_bf16 v[88:91], v[4:7], v[60:63], v[88:91]
	v_mfma_f32_16x16x32_bf16 v[92:95], v[12:15], v[60:63], v[92:95]
	v_mfma_f32_16x16x32_bf16 v[96:99], v[16:19], v[32:35], 0
	v_mfma_f32_16x16x32_bf16 v[32:35], v[24:27], v[32:35], 0
	v_mfma_f32_16x16x32_bf16 v[96:99], v[20:23], v[36:39], v[96:99]
	v_mfma_f32_16x16x32_bf16 v[32:35], v[28:31], v[36:39], v[32:35]
	v_mfma_f32_16x16x32_bf16 v[36:39], v[16:19], v[40:43], 0
	v_mfma_f32_16x16x32_bf16 v[40:43], v[24:27], v[40:43], 0
	v_mfma_f32_16x16x32_bf16 v[36:39], v[20:23], v[44:47], v[36:39]
	v_mfma_f32_16x16x32_bf16 v[40:43], v[28:31], v[44:47], v[40:43]
	v_mfma_f32_16x16x32_bf16 v[44:47], v[16:19], v[48:51], 0
	v_mfma_f32_16x16x32_bf16 v[48:51], v[24:27], v[48:51], 0
	v_mfma_f32_16x16x32_bf16 v[44:47], v[20:23], v[52:55], v[44:47]
	v_mfma_f32_16x16x32_bf16 v[48:51], v[28:31], v[52:55], v[48:51]
	v_mfma_f32_16x16x32_bf16 v[52:55], v[16:19], v[56:59], 0
	v_mfma_f32_16x16x32_bf16 v[56:59], v[24:27], v[56:59], 0
	v_mfma_f32_16x16x32_bf16 v[52:55], v[20:23], v[60:63], v[52:55]
	v_mfma_f32_16x16x32_bf16 v[56:59], v[28:31], v[60:63], v[56:59]
	s_setprio 0
	s_barrier
	v_mov_b32_e32 v128, v135
	ds_read_b128 v[60:63], v143 offset:16384
	ds_read_b128 v[100:103], v143 offset:17408
	ds_read_b128 v[104:107], v143 offset:18432
	ds_read_b128 v[108:111], v143 offset:19456
	ds_read_b128 v[112:115], v143 offset:20480
	ds_read_b128 v[116:119], v143 offset:21504
	ds_read_b128 v[120:123], v143 offset:22528
	ds_read_b128 v[124:127], v143 offset:23552
	s_add_i32 s85, s75, s3
	v_lshl_add_u64 v[144:145], s[64:65], 0, v[128:129]
	v_lshl_add_u64 v[144:145], v[144:145], 0, s[40:41]
	s_mov_b32 m0, s85
	v_mov_b32_e32 v128, v137
	s_add_i32 s51, s85, 0x2000
	global_load_lds_dwordx4 v[144:145], off
	s_add_u32 s86, s64, 0x10100
	v_lshl_add_u64 v[144:145], s[64:65], 0, v[128:129]
	v_lshl_add_u64 v[144:145], v[144:145], 0, s[40:41]
	s_mov_b32 m0, s51
	s_addc_u32 s87, s65, 0
	s_add_i32 s53, s76, s3
	global_load_lds_dwordx4 v[144:145], off
	s_mov_b32 m0, s53
	s_add_i32 s84, s53, 0x2000
	global_load_lds_dwordx4 v135, s[86:87]
	s_mov_b32 m0, s84
	s_nop 0
	global_load_lds_dwordx4 v137, s[86:87]
	v_mov_b32_e32 v128, v134
	s_mov_b32 m0, s23
	v_lshl_add_u64 v[144:145], s[60:61], 0, v[128:129]
	v_lshl_add_u64 v[144:145], v[144:145], 0, s[40:41]
	v_mov_b32_e32 v128, v136
	global_load_lds_dwordx4 v[144:145], off
	s_mov_b32 m0, s33
	v_lshl_add_u64 v[144:145], s[60:61], 0, v[128:129]
	v_lshl_add_u64 v[144:145], v[144:145], 0, s[40:41]
	global_load_lds_dwordx4 v[144:145], off
	s_waitcnt vmcnt(8)
	s_waitcnt lgkmcnt(0)
	s_barrier
; #define PG8_STAGE(bufoff, gbase, voff) do { _Pragma("unroll") for (int _i = 0; _i < 2; ++_i) \
;         { unsigned _vo = (voff)[_i]; asm volatile("" : "+v"(_vo));     \
;         __builtin_amdgcn_global_load_lds((const unsigned*)((const char*)(gbase) + _vo), (PG8_LAS unsigned*)(lds + (bufoff) + ldsw + _i * 8192), 16, 0, 0); } } while (0)
; #define PG8_LDA(dst, b, h) do { _Pragma("unroll") for (int m = 0; m < 4; ++m) _Pragma("unroll") for (int k = 0; k < 2; ++k) dst[m][k] = *(const PG8_LAS bf16x8*)(lds + PG8_SA(b, h) + aoff + m * 2048 + k * 1024); } while (0)
; #define PG8_LDB(dst, b, h) do { _Pragma("unroll") for (int n = 0; n < 2; ++n) _Pragma("unroll") for (int k = 0; k < 2; ++k) dst[n][k] = *(const PG8_LAS bf16x8*)(lds + PG8_SB(b, h) + boff + n * 2048 + k * 1024); } while (0)
; #define PG8_WAIT_V(n) asm volatile("s_waitcnt vmcnt(" #n ")" ::: "memory")
; #define PG8_WAIT_L(n) asm volatile("s_waitcnt lgkmcnt(" #n ")" ::: "memory")
; #define PG8_BAR __builtin_amdgcn_s_barrier()
; #define PG8_SCHED __builtin_amdgcn_sched_barrier(0)
; template <class Epi, class Sched, bool ALIGN_EPI = false, bool SP2 = false, bool ABLK = false, bool F8 = false>
; __device__ __forceinline__ void gemm_phase(PG8_LAS unsigned char* lds, const Gemm g, const Sched& S, const Epi& E, const int wave_s) {
;     ...
;             PG8_WAIT_V(8); PG8_WAIT_L(0); PG8_BAR; PG8_MMA(1, 0, At, B0); PG8_MMA(1, 1, At, B1); PG8_BAR; PG8_SCHED;
;             PG8_LDB(B0, 1, 0); PG8_LDB(B1, 1, 1); PG8_SCHED; PG8_LDA(At, 1, 0); PG8_STAGE(PG8_SA(0, 1), a2 + hstepA, voffA);
;             PG8_WAIT_V(8); PG8_WAIT_L(0); PG8_BAR; PG8_MMA(0, 0, At, B0); PG8_MMA(0, 1, At, B1); PG8_BAR; PG8_SCHED;
	s_setprio 1
	s_waitcnt lgkmcnt(0)
	v_mfma_f32_16x16x32_bf16 v[144:147], v[0:3], v[60:63], 0
	v_mfma_f32_16x16x32_bf16 v[152:155], v[0:3], v[104:107], 0
	v_mfma_f32_16x16x32_bf16 v[160:163], v[0:3], v[112:115], 0
	v_mfma_f32_16x16x32_bf16 v[0:3], v[0:3], v[120:123], 0
	v_mfma_f32_16x16x32_bf16 v[144:147], v[4:7], v[100:103], v[144:147]
	v_mfma_f32_16x16x32_bf16 v[152:155], v[4:7], v[108:111], v[152:155]
	v_mfma_f32_16x16x32_bf16 v[160:163], v[4:7], v[116:119], v[160:163]
	v_mfma_f32_16x16x32_bf16 v[0:3], v[4:7], v[124:127], v[0:3]
	v_mfma_f32_16x16x32_bf16 v[4:7], v[8:11], v[120:123], 0
	v_mfma_f32_16x16x32_bf16 v[148:151], v[8:11], v[60:63], 0
	v_mfma_f32_16x16x32_bf16 v[156:159], v[8:11], v[104:107], 0
	v_mfma_f32_16x16x32_bf16 v[164:167], v[8:11], v[112:115], 0
	v_mfma_f32_16x16x32_bf16 v[4:7], v[12:15], v[124:127], v[4:7]
	v_mfma_f32_16x16x32_bf16 v[148:151], v[12:15], v[100:103], v[148:151]
	v_mfma_f32_16x16x32_bf16 v[156:159], v[12:15], v[108:111], v[156:159]
	v_mfma_f32_16x16x32_bf16 v[164:167], v[12:15], v[116:119], v[164:167]
	v_mfma_f32_16x16x32_bf16 v[8:11], v[16:19], v[60:63], 0
	v_mfma_f32_16x16x32_bf16 v[12:15], v[24:27], v[60:63], 0
	v_mfma_f32_16x16x32_bf16 v[8:11], v[20:23], v[100:103], v[8:11]
	v_mfma_f32_16x16x32_bf16 v[12:15], v[28:31], v[100:103], v[12:15]
	v_mfma_f32_16x16x32_bf16 v[60:63], v[16:19], v[104:107], 0
	v_mfma_f32_16x16x32_bf16 v[100:103], v[24:27], v[104:107], 0
	v_mfma_f32_16x16x32_bf16 v[104:107], v[16:19], v[112:115], 0
	v_mfma_f32_16x16x32_bf16 v[16:19], v[16:19], v[120:123], 0
	v_mfma_f32_16x16x32_bf16 v[60:63], v[20:23], v[108:111], v[60:63]
	v_mfma_f32_16x16x32_bf16 v[100:103], v[28:31], v[108:111], v[100:103]
	v_mfma_f32_16x16x32_bf16 v[104:107], v[20:23], v[116:119], v[104:107]
	v_mfma_f32_16x16x32_bf16 v[108:111], v[24:27], v[112:115], 0
	v_mfma_f32_16x16x32_bf16 v[16:19], v[20:23], v[124:127], v[16:19]
	v_mfma_f32_16x16x32_bf16 v[20:23], v[24:27], v[120:123], 0
	v_mfma_f32_16x16x32_bf16 v[108:111], v[28:31], v[116:119], v[108:111]
	v_mfma_f32_16x16x32_bf16 v[20:23], v[28:31], v[124:127], v[20:23]
	s_setprio 0
	s_barrier
	s_add_i32 s88, 0, 0x18000
	s_add_i32 s95, 0, 0x1c000
	v_add_u32_e32 v212, s88, v139
	v_add_u32_e32 v220, s95, v139
	ds_read_b128 v[24:27], v212
	ds_read_b128 v[28:31], v212 offset:1024
	ds_read_b128 v[112:115], v212 offset:2048
	ds_read_b128 v[116:119], v212 offset:3072
	ds_read_b128 v[120:123], v220
	ds_read_b128 v[124:127], v220 offset:1024
	ds_read_b128 v[168:171], v220 offset:2048
	ds_read_b128 v[172:175], v220 offset:3072
	s_add_u32 s86, s60, 0x10100
	s_mov_b32 m0, s59
	ds_read_b128 v[176:179], v143 offset:32768
	ds_read_b128 v[180:183], v143 offset:33792
	ds_read_b128 v[184:187], v143 offset:34816
	ds_read_b128 v[188:191], v143 offset:35840
	ds_read_b128 v[192:195], v143 offset:36864
	ds_read_b128 v[196:199], v143 offset:37888
	ds_read_b128 v[200:203], v143 offset:38912
	ds_read_b128 v[204:207], v143 offset:39936
	s_addc_u32 s87, s61, 0
	s_nop 0
	global_load_lds_dwordx4 v134, s[86:87]
	s_mov_b32 m0, s72
	s_nop 0
	global_load_lds_dwordx4 v136, s[86:87]
	s_waitcnt vmcnt(8)
	s_waitcnt lgkmcnt(0)
	s_barrier
	s_setprio 1
	s_waitcnt lgkmcnt(0)
	v_mfma_f32_16x16x32_bf16 v[64:67], v[24:27], v[176:179], v[64:67]
	v_mfma_f32_16x16x32_bf16 v[68:71], v[112:115], v[176:179], v[68:71]
	v_mfma_f32_16x16x32_bf16 v[72:75], v[24:27], v[184:187], v[72:75]
	v_mfma_f32_16x16x32_bf16 v[76:79], v[112:115], v[184:187], v[76:79]
	v_mfma_f32_16x16x32_bf16 v[80:83], v[24:27], v[192:195], v[80:83]
	v_mfma_f32_16x16x32_bf16 v[84:87], v[112:115], v[192:195], v[84:87]
	v_mfma_f32_16x16x32_bf16 v[88:91], v[24:27], v[200:203], v[88:91]
	v_mfma_f32_16x16x32_bf16 v[92:95], v[112:115], v[200:203], v[92:95]
	v_mfma_f32_16x16x32_bf16 v[64:67], v[28:31], v[180:183], v[64:67]
	v_mfma_f32_16x16x32_bf16 v[68:71], v[116:119], v[180:183], v[68:71]
	v_mfma_f32_16x16x32_bf16 v[72:75], v[28:31], v[188:191], v[72:75]
	v_mfma_f32_16x16x32_bf16 v[76:79], v[116:119], v[188:191], v[76:79]
	v_mfma_f32_16x16x32_bf16 v[80:83], v[28:31], v[196:199], v[80:83]
	v_mfma_f32_16x16x32_bf16 v[84:87], v[116:119], v[196:199], v[84:87]
	v_mfma_f32_16x16x32_bf16 v[88:91], v[28:31], v[204:207], v[88:91]
	v_mfma_f32_16x16x32_bf16 v[92:95], v[116:119], v[204:207], v[92:95]
	v_mfma_f32_16x16x32_bf16 v[96:99], v[120:123], v[176:179], v[96:99]
	v_mfma_f32_16x16x32_bf16 v[32:35], v[168:171], v[176:179], v[32:35]
	v_mfma_f32_16x16x32_bf16 v[36:39], v[120:123], v[184:187], v[36:39]
	v_mfma_f32_16x16x32_bf16 v[40:43], v[168:171], v[184:187], v[40:43]
	v_mfma_f32_16x16x32_bf16 v[44:47], v[120:123], v[192:195], v[44:47]
	v_mfma_f32_16x16x32_bf16 v[48:51], v[168:171], v[192:195], v[48:51]
	v_mfma_f32_16x16x32_bf16 v[52:55], v[120:123], v[200:203], v[52:55]
	v_mfma_f32_16x16x32_bf16 v[56:59], v[168:171], v[200:203], v[56:59]
	v_mfma_f32_16x16x32_bf16 v[96:99], v[124:127], v[180:183], v[96:99]
	v_mfma_f32_16x16x32_bf16 v[32:35], v[172:175], v[180:183], v[32:35]
	v_mfma_f32_16x16x32_bf16 v[36:39], v[124:127], v[188:191], v[36:39]
	v_mfma_f32_16x16x32_bf16 v[40:43], v[172:175], v[188:191], v[40:43]
	v_mfma_f32_16x16x32_bf16 v[44:47], v[124:127], v[196:199], v[44:47]
	v_mfma_f32_16x16x32_bf16 v[48:51], v[172:175], v[196:199], v[48:51]
	v_mfma_f32_16x16x32_bf16 v[52:55], v[124:127], v[204:207], v[52:55]
	v_mfma_f32_16x16x32_bf16 v[56:59], v[172:175], v[204:207], v[56:59]
	s_setprio 0
	s_barrier
; #define PG8_STAGE(bufoff, gbase, voff) do { _Pragma("unroll") for (int _i = 0; _i < 2; ++_i) \
;         { unsigned _vo = (voff)[_i]; asm volatile("" : "+v"(_vo));     \
;         __builtin_amdgcn_global_load_lds((const unsigned*)((const char*)(gbase) + _vo), (PG8_LAS unsigned*)(lds + (bufoff) + ldsw + _i * 8192), 16, 0, 0); } } while (0)
; #define PG8_LDA(dst, b, h) do { _Pragma("unroll") for (int m = 0; m < 4; ++m) _Pragma("unroll") for (int k = 0; k < 2; ++k) dst[m][k] = *(const PG8_LAS bf16x8*)(lds + PG8_SA(b, h) + aoff + m * 2048 + k * 1024); } while (0)
; #define PG8_LDB(dst, b, h) do { _Pragma("unroll") for (int n = 0; n < 2; ++n) _Pragma("unroll") for (int k = 0; k < 2; ++k) dst[n][k] = *(const PG8_LAS bf16x8*)(lds + PG8_SB(b, h) + boff + n * 2048 + k * 1024); } while (0)
; #define PG8_WAIT_V(n) asm volatile("s_waitcnt vmcnt(" #n ")" ::: "memory")
; #define PG8_WAIT_L(n) asm volatile("s_waitcnt lgkmcnt(" #n ")" ::: "memory")
; #define PG8_BAR __builtin_amdgcn_s_barrier()
; #define PG8_SCHED __builtin_amdgcn_sched_barrier(0)
; template <class Epi, class Sched, bool ALIGN_EPI = false, bool SP2 = false, bool ABLK = false, bool F8 = false>
; __device__ __forceinline__ void gemm_phase(PG8_LAS unsigned char* lds, const Gemm g, const Sched& S, const Epi& E, const int wave_s) {
;     ...
;             PG8_LDB(B0, 0, 0); PG8_LDB(B1, 0, 1); PG8_SCHED; PG8_LDA(At, 0, 0); PG8_STAGE(PG8_SA(1, 1), a1 + hstepA, voffA);
;             PG8_WAIT_V(8); PG8_WAIT_L(0); PG8_BAR; PG8_MMA(0, 0, At, B0); PG8_MMA(0, 1, At, B1); PG8_BAR; PG8_SCHED;
;             PG8_LDA(At, 0, 1); PG8_STAGE(PG8_SB(0, 0), b2, voffB); PG8_STAGE(PG8_SB(0, 1), b2 + hstep, voffB); PG8_STAGE(PG8_SA(0, 0), a2, voffA);
;             PG8_WAIT_V(8); PG8_WAIT_L(0); PG8_BAR; PG8_MMA(1, 0, At, B0); PG8_MMA(1, 1, At, B1); PG8_BAR; PG8_SCHED;
;             PG8_LDB(B0, 1, 0); PG8_LDB(B1, 1, 1); PG8_SCHED; PG8_LDA(At, 1, 0); PG8_STAGE(PG8_SA(0, 1), a2 + hstepA, voffA);
;             PG8_WAIT_V(8); PG8_WAIT_L(0); PG8_BAR; PG8_MMA(0, 0, At, B0); PG8_MMA(0, 1, At, B1); PG8_BAR; PG8_SCHED;
;             PG8_LDA(At, 1, 1); PG8_STAGE(PG8_SB(1, 0), b3, voffB); PG8_STAGE(PG8_SB(1, 1), b3 + hstep, voffB); PG8_STAGE(PG8_SA(1, 0), a3, voffA);
;             PG8_WAIT_V(8); PG8_WAIT_L(0); PG8_BAR; PG8_MMA(1, 0, At, B0); PG8_MMA(1, 1, At, B1); PG8_BAR; PG8_SCHED;
	v_mov_b32_e32 v128, v135
	ds_read_b128 v[176:179], v143 offset:49152
	ds_read_b128 v[180:183], v143 offset:50176
	ds_read_b128 v[184:187], v143 offset:51200
	ds_read_b128 v[188:191], v143 offset:52224
	ds_read_b128 v[192:195], v143 offset:53248
	ds_read_b128 v[196:199], v143 offset:54272
	ds_read_b128 v[200:203], v143 offset:55296
	ds_read_b128 v[204:207], v143 offset:56320
	s_add_i32 s87, s88, s3
	v_lshl_add_u64 v[208:209], s[64:65], 0, v[128:129]
	v_lshl_add_u64 v[208:209], v[208:209], 0, s[42:43]
	s_mov_b32 m0, s87
	v_mov_b32_e32 v128, v137
	s_add_i32 s86, s87, 0x2000
	global_load_lds_dwordx4 v[208:209], off
	s_add_u32 s88, s64, 0x10180
	v_lshl_add_u64 v[208:209], s[64:65], 0, v[128:129]
	v_lshl_add_u64 v[208:209], v[208:209], 0, s[42:43]
	s_mov_b32 m0, s86
	s_addc_u32 s89, s65, 0
	s_add_i32 s64, s95, s3
	global_load_lds_dwordx4 v[208:209], off
	s_mov_b32 m0, s64
	s_add_i32 s65, s64, 0x2000
	global_load_lds_dwordx4 v135, s[88:89]
	s_mov_b32 m0, s65
	s_nop 0
	global_load_lds_dwordx4 v137, s[88:89]
	v_mov_b32_e32 v128, v134
	s_mov_b32 m0, s73
	v_lshl_add_u64 v[208:209], s[60:61], 0, v[128:129]
	v_lshl_add_u64 v[208:209], v[208:209], 0, s[42:43]
	v_mov_b32_e32 v128, v136
	global_load_lds_dwordx4 v[208:209], off
	s_mov_b32 m0, s74
	v_lshl_add_u64 v[208:209], s[60:61], 0, v[128:129]
	v_lshl_add_u64 v[208:209], v[208:209], 0, s[42:43]
	global_load_lds_dwordx4 v[208:209], off
	s_waitcnt vmcnt(8)
	s_waitcnt lgkmcnt(0)
	s_barrier
	s_setprio 1
	s_waitcnt lgkmcnt(0)
	v_mfma_f32_16x16x32_bf16 v[0:3], v[24:27], v[200:203], v[0:3]
	v_mfma_f32_16x16x32_bf16 v[4:7], v[112:115], v[200:203], v[4:7]
	v_mfma_f32_16x16x32_bf16 v[144:147], v[24:27], v[176:179], v[144:147]
	v_mfma_f32_16x16x32_bf16 v[148:151], v[112:115], v[176:179], v[148:151]
	v_mfma_f32_16x16x32_bf16 v[152:155], v[24:27], v[184:187], v[152:155]
	v_mfma_f32_16x16x32_bf16 v[156:159], v[112:115], v[184:187], v[156:159]
	v_mfma_f32_16x16x32_bf16 v[160:163], v[24:27], v[192:195], v[160:163]
	v_mfma_f32_16x16x32_bf16 v[164:167], v[112:115], v[192:195], v[164:167]
	v_mfma_f32_16x16x32_bf16 v[0:3], v[28:31], v[204:207], v[0:3]
	v_mfma_f32_16x16x32_bf16 v[4:7], v[116:119], v[204:207], v[4:7]
	v_mfma_f32_16x16x32_bf16 v[144:147], v[28:31], v[180:183], v[144:147]
	v_mfma_f32_16x16x32_bf16 v[148:151], v[116:119], v[180:183], v[148:151]
	v_mfma_f32_16x16x32_bf16 v[152:155], v[28:31], v[188:191], v[152:155]
	v_mfma_f32_16x16x32_bf16 v[156:159], v[116:119], v[188:191], v[156:159]
	v_mfma_f32_16x16x32_bf16 v[160:163], v[28:31], v[196:199], v[160:163]
	v_mfma_f32_16x16x32_bf16 v[164:167], v[116:119], v[196:199], v[164:167]
	v_mfma_f32_16x16x32_bf16 v[8:11], v[120:123], v[176:179], v[8:11]
	v_mfma_f32_16x16x32_bf16 v[12:15], v[168:171], v[176:179], v[12:15]
	v_mfma_f32_16x16x32_bf16 v[24:27], v[120:123], v[184:187], v[60:63]
	v_mfma_f32_16x16x32_bf16 v[28:31], v[168:171], v[184:187], v[100:103]
	v_mfma_f32_16x16x32_bf16 v[60:63], v[120:123], v[192:195], v[104:107]
	v_mfma_f32_16x16x32_bf16 v[100:103], v[168:171], v[192:195], v[108:111]
	v_mfma_f32_16x16x32_bf16 v[16:19], v[120:123], v[200:203], v[16:19]
	v_mfma_f32_16x16x32_bf16 v[20:23], v[168:171], v[200:203], v[20:23]
	v_mfma_f32_16x16x32_bf16 v[8:11], v[124:127], v[180:183], v[8:11]
	v_mfma_f32_16x16x32_bf16 v[12:15], v[172:175], v[180:183], v[12:15]
	v_mfma_f32_16x16x32_bf16 v[24:27], v[124:127], v[188:191], v[24:27]
	v_mfma_f32_16x16x32_bf16 v[28:31], v[172:175], v[188:191], v[28:31]
	v_mfma_f32_16x16x32_bf16 v[60:63], v[124:127], v[196:199], v[60:63]
	v_mfma_f32_16x16x32_bf16 v[100:103], v[172:175], v[196:199], v[100:103]
	v_mfma_f32_16x16x32_bf16 v[16:19], v[124:127], v[204:207], v[16:19]
	v_mfma_f32_16x16x32_bf16 v[20:23], v[172:175], v[204:207], v[20:23]
	s_setprio 0
	s_barrier
	ds_read_b128 v[104:107], v141
	ds_read_b128 v[108:111], v141 offset:1024
	ds_read_b128 v[112:115], v141 offset:2048
	ds_read_b128 v[116:119], v141 offset:3072
	ds_read_b128 v[120:123], v142
	ds_read_b128 v[124:127], v142 offset:1024
	ds_read_b128 v[168:171], v142 offset:2048
	ds_read_b128 v[172:175], v142 offset:3072
	s_add_u32 s60, s60, 0x10180
	s_mov_b32 m0, s77
	ds_read_b128 v[176:179], v143
	ds_read_b128 v[180:183], v143 offset:1024
	ds_read_b128 v[184:187], v143 offset:2048
	ds_read_b128 v[188:191], v143 offset:3072
	ds_read_b128 v[192:195], v143 offset:4096
	ds_read_b128 v[196:199], v143 offset:5120
	ds_read_b128 v[200:203], v143 offset:6144
	ds_read_b128 v[204:207], v143 offset:7168
	s_addc_u32 s61, s61, 0
	s_nop 0
	global_load_lds_dwordx4 v134, s[60:61]
	s_mov_b32 m0, s78
	s_nop 0
	global_load_lds_dwordx4 v136, s[60:61]
	s_waitcnt vmcnt(8)
	s_waitcnt lgkmcnt(0)
	s_barrier
; #define PG8_STAGE(bufoff, gbase, voff) do { _Pragma("unroll") for (int _i = 0; _i < 2; ++_i) \
;         { unsigned _vo = (voff)[_i]; asm volatile("" : "+v"(_vo));     \
;         __builtin_amdgcn_global_load_lds((const unsigned*)((const char*)(gbase) + _vo), (PG8_LAS unsigned*)(lds + (bufoff) + ldsw + _i * 8192), 16, 0, 0); } } while (0)
; #define PG8_LDA(dst, b, h) do { _Pragma("unroll") for (int m = 0; m < 4; ++m) _Pragma("unroll") for (int k = 0; k < 2; ++k) dst[m][k] = *(const PG8_LAS bf16x8*)(lds + PG8_SA(b, h) + aoff + m * 2048 + k * 1024); } while (0)
; #define PG8_WAIT_V(n) asm volatile("s_waitcnt vmcnt(" #n ")" ::: "memory")
; #define PG8_WAIT_L(n) asm volatile("s_waitcnt lgkmcnt(" #n ")" ::: "memory")
; #define PG8_BAR __builtin_amdgcn_s_barrier()
; #define PG8_SCHED __builtin_amdgcn_sched_barrier(0)
; template <class Epi, class Sched, bool ALIGN_EPI = false, bool SP2 = false, bool ABLK = false, bool F8 = false>
; __device__ __forceinline__ void gemm_phase(PG8_LAS unsigned char* lds, const Gemm g, const Sched& S, const Epi& E, const int wave_s) {
;     ...
;             PG8_WAIT_V(8); PG8_WAIT_L(0); PG8_BAR; PG8_MMA(0, 0, At, B0); PG8_MMA(0, 1, At, B1); PG8_BAR; PG8_SCHED;
;             PG8_LDA(At, 0, 1); PG8_STAGE(PG8_SB(0, 0), b2, voffB); PG8_STAGE(PG8_SB(0, 1), b2 + hstep, voffB); PG8_STAGE(PG8_SA(0, 0), a2, voffA);
;             PG8_WAIT_V(8); PG8_WAIT_L(0); PG8_BAR; PG8_MMA(1, 0, At, B0); PG8_MMA(1, 1, At, B1); PG8_BAR; PG8_SCHED;
	s_setprio 1
	s_waitcnt lgkmcnt(0)
	v_mfma_f32_16x16x32_bf16 v[64:67], v[104:107], v[176:179], v[64:67]
	v_mfma_f32_16x16x32_bf16 v[68:71], v[112:115], v[176:179], v[68:71]
	v_mfma_f32_16x16x32_bf16 v[72:75], v[104:107], v[184:187], v[72:75]
	v_mfma_f32_16x16x32_bf16 v[76:79], v[112:115], v[184:187], v[76:79]
	v_mfma_f32_16x16x32_bf16 v[80:83], v[104:107], v[192:195], v[80:83]
	v_mfma_f32_16x16x32_bf16 v[84:87], v[112:115], v[192:195], v[84:87]
	v_mfma_f32_16x16x32_bf16 v[88:91], v[104:107], v[200:203], v[88:91]
	v_mfma_f32_16x16x32_bf16 v[92:95], v[112:115], v[200:203], v[92:95]
	v_mfma_f32_16x16x32_bf16 v[64:67], v[108:111], v[180:183], v[64:67]
	v_mfma_f32_16x16x32_bf16 v[68:71], v[116:119], v[180:183], v[68:71]
	v_mfma_f32_16x16x32_bf16 v[72:75], v[108:111], v[188:191], v[72:75]
	v_mfma_f32_16x16x32_bf16 v[76:79], v[116:119], v[188:191], v[76:79]
	v_mfma_f32_16x16x32_bf16 v[80:83], v[108:111], v[196:199], v[80:83]
	v_mfma_f32_16x16x32_bf16 v[84:87], v[116:119], v[196:199], v[84:87]
	v_mfma_f32_16x16x32_bf16 v[88:91], v[108:111], v[204:207], v[88:91]
	v_mfma_f32_16x16x32_bf16 v[92:95], v[116:119], v[204:207], v[92:95]
	v_mfma_f32_16x16x32_bf16 v[36:39], v[120:123], v[184:187], v[36:39]
	v_mfma_f32_16x16x32_bf16 v[96:99], v[120:123], v[176:179], v[96:99]
	v_mfma_f32_16x16x32_bf16 v[32:35], v[168:171], v[176:179], v[32:35]
	v_mfma_f32_16x16x32_bf16 v[176:179], v[124:127], v[188:191], v[36:39]
	v_mfma_f32_16x16x32_bf16 v[36:39], v[168:171], v[184:187], v[40:43]
	v_mfma_f32_16x16x32_bf16 v[40:43], v[172:175], v[188:191], v[36:39]
	v_mfma_f32_16x16x32_bf16 v[36:39], v[120:123], v[192:195], v[44:47]
	v_mfma_f32_16x16x32_bf16 v[96:99], v[124:127], v[180:183], v[96:99]
	v_mfma_f32_16x16x32_bf16 v[32:35], v[172:175], v[180:183], v[32:35]
	v_mfma_f32_16x16x32_bf16 v[180:183], v[124:127], v[196:199], v[36:39]
	v_mfma_f32_16x16x32_bf16 v[36:39], v[168:171], v[192:195], v[48:51]
	v_mfma_f32_16x16x32_bf16 v[48:51], v[172:175], v[196:199], v[36:39]
	v_mfma_f32_16x16x32_bf16 v[36:39], v[120:123], v[200:203], v[52:55]
	v_mfma_f32_16x16x32_bf16 v[52:55], v[124:127], v[204:207], v[36:39]
	v_mfma_f32_16x16x32_bf16 v[36:39], v[168:171], v[200:203], v[56:59]
	v_mfma_f32_16x16x32_bf16 v[56:59], v[172:175], v[204:207], v[36:39]
	s_setprio 0
	s_barrier
	s_mov_b32 m0, s85
	s_nop 2
	ds_read_b128 v[36:39], v143 offset:16384
	ds_read_b128 v[44:47], v143 offset:17408
	ds_read_b128 v[184:187], v143 offset:18432
	ds_read_b128 v[188:191], v143 offset:19456
	ds_read_b128 v[192:195], v143 offset:20480
	ds_read_b128 v[196:199], v143 offset:21504
	ds_read_b128 v[200:203], v143 offset:22528
	ds_read_b128 v[204:207], v143 offset:23552
	s_add_u32 s60, s66, 0x10000
	global_load_lds_dwordx4 v135, s[66:67]
	s_mov_b32 m0, s51
	s_addc_u32 s61, s67, 0
	global_load_lds_dwordx4 v137, s[66:67]
	s_mov_b32 m0, s53
	s_nop 0
	global_load_lds_dwordx4 v135, s[60:61]
	s_mov_b32 m0, s84
	s_nop 0
	global_load_lds_dwordx4 v137, s[60:61]
	s_mov_b32 m0, s23
	s_nop 0
	global_load_lds_dwordx4 v134, s[62:63]
	s_mov_b32 m0, s33
	s_nop 0
	global_load_lds_dwordx4 v136, s[62:63]
	s_waitcnt vmcnt(8)
	s_waitcnt lgkmcnt(0)
	s_barrier
	s_setprio 1
	s_waitcnt lgkmcnt(0)
	v_mfma_f32_16x16x32_bf16 v[0:3], v[104:107], v[200:203], v[0:3]
	v_mfma_f32_16x16x32_bf16 v[4:7], v[112:115], v[200:203], v[4:7]
	v_mfma_f32_16x16x32_bf16 v[144:147], v[104:107], v[36:39], v[144:147]
	v_mfma_f32_16x16x32_bf16 v[148:151], v[112:115], v[36:39], v[148:151]
	v_mfma_f32_16x16x32_bf16 v[152:155], v[104:107], v[184:187], v[152:155]
	v_mfma_f32_16x16x32_bf16 v[156:159], v[112:115], v[184:187], v[156:159]
	v_mfma_f32_16x16x32_bf16 v[160:163], v[104:107], v[192:195], v[160:163]
	v_mfma_f32_16x16x32_bf16 v[164:167], v[112:115], v[192:195], v[164:167]
	v_mfma_f32_16x16x32_bf16 v[0:3], v[108:111], v[204:207], v[0:3]
	v_mfma_f32_16x16x32_bf16 v[4:7], v[116:119], v[204:207], v[4:7]
	v_mfma_f32_16x16x32_bf16 v[144:147], v[108:111], v[44:47], v[144:147]
	v_mfma_f32_16x16x32_bf16 v[148:151], v[116:119], v[44:47], v[148:151]
	v_mfma_f32_16x16x32_bf16 v[152:155], v[108:111], v[188:191], v[152:155]
	v_mfma_f32_16x16x32_bf16 v[156:159], v[116:119], v[188:191], v[156:159]
	v_mfma_f32_16x16x32_bf16 v[160:163], v[108:111], v[196:199], v[160:163]
	v_mfma_f32_16x16x32_bf16 v[164:167], v[116:119], v[196:199], v[164:167]
	v_mfma_f32_16x16x32_bf16 v[12:15], v[168:171], v[36:39], v[12:15]
	v_mfma_f32_16x16x32_bf16 v[208:211], v[172:175], v[44:47], v[12:15]
	v_mfma_f32_16x16x32_bf16 v[12:15], v[120:123], v[184:187], v[24:27]
	v_mfma_f32_16x16x32_bf16 v[24:27], v[124:127], v[188:191], v[12:15]
	v_mfma_f32_16x16x32_bf16 v[12:15], v[168:171], v[184:187], v[28:31]
	v_mfma_f32_16x16x32_bf16 v[184:187], v[172:175], v[188:191], v[12:15]
	v_mfma_f32_16x16x32_bf16 v[12:15], v[120:123], v[192:195], v[60:63]
	v_mfma_f32_16x16x32_bf16 v[188:191], v[124:127], v[196:199], v[12:15]
	v_mfma_f32_16x16x32_bf16 v[12:15], v[168:171], v[192:195], v[100:103]
	v_mfma_f32_16x16x32_bf16 v[8:11], v[120:123], v[36:39], v[8:11]
	v_mfma_f32_16x16x32_bf16 v[192:195], v[172:175], v[196:199], v[12:15]
	v_mfma_f32_16x16x32_bf16 v[12:15], v[120:123], v[200:203], v[16:19]
	v_mfma_f32_16x16x32_bf16 v[8:11], v[124:127], v[44:47], v[8:11]
	v_mfma_f32_16x16x32_bf16 v[196:199], v[124:127], v[204:207], v[12:15]
	v_mfma_f32_16x16x32_bf16 v[12:15], v[168:171], v[200:203], v[20:23]
	v_mfma_f32_16x16x32_bf16 v[168:171], v[172:175], v[204:207], v[12:15]
	s_setprio 0
	s_barrier
; #define PG8_STAGE(bufoff, gbase, voff) do { _Pragma("unroll") for (int _i = 0; _i < 2; ++_i) \
;         { unsigned _vo = (voff)[_i]; asm volatile("" : "+v"(_vo));     \
;         __builtin_amdgcn_global_load_lds((const unsigned*)((const char*)(gbase) + _vo), (PG8_LAS unsigned*)(lds + (bufoff) + ldsw + _i * 8192), 16, 0, 0); } } while (0)
; #define PG8_LDA(dst, b, h) do { _Pragma("unroll") for (int m = 0; m < 4; ++m) _Pragma("unroll") for (int k = 0; k < 2; ++k) dst[m][k] = *(const PG8_LAS bf16x8*)(lds + PG8_SA(b, h) + aoff + m * 2048 + k * 1024); } while (0)
; #define PG8_LDB(dst, b, h) do { _Pragma("unroll") for (int n = 0; n < 2; ++n) _Pragma("unroll") for (int k = 0; k < 2; ++k) dst[n][k] = *(const PG8_LAS bf16x8*)(lds + PG8_SB(b, h) + boff + n * 2048 + k * 1024); } while (0)
; #define PG8_WAIT_V(n) asm volatile("s_waitcnt vmcnt(" #n ")" ::: "memory")
; #define PG8_WAIT_L(n) asm volatile("s_waitcnt lgkmcnt(" #n ")" ::: "memory")
; #define PG8_BAR __builtin_amdgcn_s_barrier()
; #define PG8_SCHED __builtin_amdgcn_sched_barrier(0)
; template <class Epi, class Sched, bool ALIGN_EPI = false, bool SP2 = false, bool ABLK = false, bool F8 = false>
; __device__ __forceinline__ void gemm_phase(PG8_LAS unsigned char* lds, const Gemm g, const Sched& S, const Epi& E, const int wave_s) {
;     ...
;             PG8_LDB(B0, 1, 0); PG8_LDB(B1, 1, 1); PG8_SCHED; PG8_LDA(At, 1, 0); PG8_STAGE(PG8_SA(0, 1), a2 + hstepA, voffA);
;             PG8_WAIT_V(8); PG8_WAIT_L(0); PG8_BAR; PG8_MMA(0, 0, At, B0); PG8_MMA(0, 1, At, B1); PG8_BAR; PG8_SCHED;
;             PG8_LDA(At, 1, 1); PG8_STAGE(PG8_SB(1, 0), b3, voffB); PG8_STAGE(PG8_SB(1, 1), b3 + hstep, voffB); PG8_STAGE(PG8_SA(1, 0), a3, voffA);
;             PG8_WAIT_V(8); PG8_WAIT_L(0); PG8_BAR; PG8_MMA(1, 0, At, B0); PG8_MMA(1, 1, At, B1); PG8_BAR; PG8_SCHED;
;     ...
;         if constexpr (ALIGN_EPI) { if (wr == 0) PG8_BAR; }
	s_nop 4
	ds_read_b128 v[12:15], v212
	ds_read_b128 v[16:19], v212 offset:1024
	ds_read_b128 v[172:175], v212 offset:2048
	ds_read_b128 v[200:203], v212 offset:3072
	ds_read_b128 v[204:207], v220
	ds_read_b128 v[212:215], v220 offset:1024
	ds_read_b128 v[216:219], v220 offset:2048
	ds_read_b128 v[220:223], v220 offset:3072
	s_add_u32 s60, s62, 0x10000
	s_mov_b32 m0, s59
	ds_read_b128 v[20:23], v143 offset:32768
	ds_read_b128 v[28:31], v143 offset:33792
	ds_read_b128 v[60:63], v143 offset:34816
	ds_read_b128 v[224:227], v143 offset:35840
	ds_read_b128 v[228:231], v143 offset:36864
	ds_read_b128 v[232:235], v143 offset:37888
	ds_read_b128 v[236:239], v143 offset:38912
	ds_read_b128 v[240:243], v143 offset:39936
	s_addc_u32 s61, s63, 0
	s_nop 0
	global_load_lds_dwordx4 v134, s[60:61]
	s_mov_b32 m0, s72
	s_nop 0
	global_load_lds_dwordx4 v136, s[60:61]
	s_waitcnt vmcnt(8)
	s_waitcnt lgkmcnt(0)
	s_barrier
	s_setprio 1
	s_waitcnt lgkmcnt(0)
	v_mfma_f32_16x16x32_bf16 v[36:39], v[12:15], v[20:23], v[64:67]
	v_mfma_f32_16x16x32_bf16 v[124:127], v[16:19], v[28:31], v[36:39]
	v_mfma_f32_16x16x32_bf16 v[36:39], v[172:175], v[20:23], v[68:71]
	v_mfma_f32_16x16x32_bf16 v[116:119], v[200:203], v[28:31], v[36:39]
	v_mfma_f32_16x16x32_bf16 v[36:39], v[12:15], v[60:63], v[72:75]
	v_mfma_f32_16x16x32_bf16 v[108:111], v[16:19], v[224:227], v[36:39]
	v_mfma_f32_16x16x32_bf16 v[36:39], v[172:175], v[60:63], v[76:79]
	v_mfma_f32_16x16x32_bf16 v[100:103], v[200:203], v[224:227], v[36:39]
	v_mfma_f32_16x16x32_bf16 v[36:39], v[12:15], v[228:231], v[80:83]
	v_mfma_f32_16x16x32_bf16 v[80:83], v[16:19], v[232:235], v[36:39]
	v_mfma_f32_16x16x32_bf16 v[36:39], v[172:175], v[228:231], v[84:87]
	v_mfma_f32_16x16x32_bf16 v[68:71], v[200:203], v[232:235], v[36:39]
	v_mfma_f32_16x16x32_bf16 v[36:39], v[12:15], v[236:239], v[88:91]
	v_mfma_f32_16x16x32_bf16 v[44:47], v[16:19], v[240:243], v[36:39]
	v_mfma_f32_16x16x32_bf16 v[36:39], v[172:175], v[236:239], v[92:95]
	v_mfma_f32_16x16x32_bf16 v[36:39], v[200:203], v[240:243], v[36:39]
	v_mfma_f32_16x16x32_bf16 v[64:67], v[204:207], v[20:23], v[96:99]
	v_mfma_f32_16x16x32_bf16 v[20:23], v[216:219], v[20:23], v[32:35]
	v_mfma_f32_16x16x32_bf16 v[112:115], v[220:223], v[28:31], v[20:23]
	v_mfma_f32_16x16x32_bf16 v[20:23], v[204:207], v[60:63], v[176:179]
	v_mfma_f32_16x16x32_bf16 v[104:107], v[212:215], v[224:227], v[20:23]
	v_mfma_f32_16x16x32_bf16 v[20:23], v[216:219], v[60:63], v[40:43]
	v_mfma_f32_16x16x32_bf16 v[96:99], v[220:223], v[224:227], v[20:23]
	v_mfma_f32_16x16x32_bf16 v[20:23], v[204:207], v[228:231], v[180:183]
	v_mfma_f32_16x16x32_bf16 v[72:75], v[212:215], v[232:235], v[20:23]
	v_mfma_f32_16x16x32_bf16 v[20:23], v[216:219], v[228:231], v[48:51]
	v_mfma_f32_16x16x32_bf16 v[120:123], v[212:215], v[28:31], v[64:67]
	v_mfma_f32_16x16x32_bf16 v[64:67], v[220:223], v[232:235], v[20:23]
	v_mfma_f32_16x16x32_bf16 v[20:23], v[204:207], v[236:239], v[52:55]
	v_mfma_f32_16x16x32_bf16 v[40:43], v[212:215], v[240:243], v[20:23]
	v_mfma_f32_16x16x32_bf16 v[20:23], v[216:219], v[236:239], v[56:59]
	v_mfma_f32_16x16x32_bf16 v[32:35], v[220:223], v[240:243], v[20:23]
	s_setprio 0
	s_barrier
	v_mov_b32_e32 v128, v135
	ds_read_b128 v[48:51], v143 offset:49152
	ds_read_b128 v[56:59], v143 offset:50176
	ds_read_b128 v[176:179], v143 offset:51200
	ds_read_b128 v[180:183], v143 offset:52224
	ds_read_b128 v[224:227], v143 offset:53248
	ds_read_b128 v[228:231], v143 offset:54272
	ds_read_b128 v[232:235], v143 offset:55296
	ds_read_b128 v[236:239], v143 offset:56320
	s_mov_b32 m0, s87
	v_lshl_add_u64 v[20:21], s[66:67], 0, v[128:129]
	v_lshl_add_u64 v[20:21], v[20:21], 0, s[10:11]
	v_mov_b32_e32 v128, v137
	global_load_lds_dwordx4 v[20:21], off
	s_mov_b32 m0, s86
	v_lshl_add_u64 v[20:21], s[66:67], 0, v[128:129]
	v_lshl_add_u64 v[20:21], v[20:21], 0, s[10:11]
	global_load_lds_dwordx4 v[20:21], off
	s_add_u32 s60, s66, 0x10080
	s_addc_u32 s61, s67, 0
	s_mov_b32 m0, s64
	v_mov_b32_e32 v128, v134
	global_load_lds_dwordx4 v135, s[60:61]
	s_mov_b32 m0, s65
	s_nop 0
	global_load_lds_dwordx4 v137, s[60:61]
	s_mov_b32 m0, s73
	v_lshl_add_u64 v[20:21], s[62:63], 0, v[128:129]
	v_lshl_add_u64 v[20:21], v[20:21], 0, s[10:11]
	v_mov_b32_e32 v128, v136
	global_load_lds_dwordx4 v[20:21], off
	s_mov_b32 m0, s74
	v_lshl_add_u64 v[20:21], s[62:63], 0, v[128:129]
	v_lshl_add_u64 v[20:21], v[20:21], 0, s[10:11]
	global_load_lds_dwordx4 v[20:21], off
	s_waitcnt vmcnt(8)
	s_waitcnt lgkmcnt(0)
	s_barrier
	s_setprio 1
	s_waitcnt lgkmcnt(0)
	v_mfma_f32_16x16x32_bf16 v[20:23], v[12:15], v[48:51], v[144:147]
	v_mfma_f32_16x16x32_bf16 v[92:95], v[16:19], v[56:59], v[20:23]
	v_mfma_f32_16x16x32_bf16 v[20:23], v[172:175], v[48:51], v[148:151]
	v_mfma_f32_16x16x32_bf16 v[88:91], v[200:203], v[56:59], v[20:23]
	v_mfma_f32_16x16x32_bf16 v[20:23], v[12:15], v[176:179], v[152:155]
	v_mfma_f32_16x16x32_bf16 v[60:63], v[16:19], v[180:183], v[20:23]
	v_mfma_f32_16x16x32_bf16 v[20:23], v[172:175], v[176:179], v[156:159]
	v_mfma_f32_16x16x32_bf16 v[52:55], v[200:203], v[180:183], v[20:23]
	v_mfma_f32_16x16x32_bf16 v[20:23], v[12:15], v[224:227], v[160:163]
	v_mfma_f32_16x16x32_bf16 v[0:3], v[12:15], v[232:235], v[0:3]
	v_mfma_f32_16x16x32_bf16 v[28:31], v[16:19], v[228:231], v[20:23]
	v_mfma_f32_16x16x32_bf16 v[20:23], v[172:175], v[224:227], v[164:167]
	v_mfma_f32_16x16x32_bf16 v[12:15], v[16:19], v[236:239], v[0:3]
	v_mfma_f32_16x16x32_bf16 v[0:3], v[172:175], v[232:235], v[4:7]
	v_mfma_f32_16x16x32_bf16 v[20:23], v[200:203], v[228:231], v[20:23]
	v_mfma_f32_16x16x32_bf16 v[4:7], v[200:203], v[236:239], v[0:3]
	v_mfma_f32_16x16x32_bf16 v[0:3], v[204:207], v[48:51], v[8:11]
	v_mfma_f32_16x16x32_bf16 v[84:87], v[212:215], v[56:59], v[0:3]
	v_mfma_f32_16x16x32_bf16 v[0:3], v[216:219], v[48:51], v[208:211]
	v_mfma_f32_16x16x32_bf16 v[76:79], v[220:223], v[56:59], v[0:3]
	v_mfma_f32_16x16x32_bf16 v[0:3], v[204:207], v[176:179], v[24:27]
	v_mfma_f32_16x16x32_bf16 v[56:59], v[212:215], v[180:183], v[0:3]
	v_mfma_f32_16x16x32_bf16 v[0:3], v[216:219], v[176:179], v[184:187]
	v_mfma_f32_16x16x32_bf16 v[48:51], v[220:223], v[180:183], v[0:3]
	v_mfma_f32_16x16x32_bf16 v[0:3], v[204:207], v[224:227], v[188:191]
	v_mfma_f32_16x16x32_bf16 v[24:27], v[212:215], v[228:231], v[0:3]
	v_mfma_f32_16x16x32_bf16 v[0:3], v[216:219], v[224:227], v[192:195]
	v_mfma_f32_16x16x32_bf16 v[16:19], v[220:223], v[228:231], v[0:3]
	v_mfma_f32_16x16x32_bf16 v[0:3], v[204:207], v[232:235], v[196:199]
	v_mfma_f32_16x16x32_bf16 v[8:11], v[212:215], v[236:239], v[0:3]
	v_mfma_f32_16x16x32_bf16 v[0:3], v[216:219], v[232:235], v[168:171]
	v_mfma_f32_16x16x32_bf16 v[0:3], v[220:223], v[236:239], v[0:3]
	s_setprio 0
	s_barrier
	s_and_b64 vcc, exec, s[4:5]
	s_cbranch_vccnz .LBB0_987
	s_barrier

; #define PG8_STAGE(bufoff, gbase, voff) do { _Pragma("unroll") for (int _i = 0; _i < 2; ++_i) \
;         { unsigned _vo = (voff)[_i]; asm volatile("" : "+v"(_vo));     \
;         __builtin_amdgcn_global_load_lds((const unsigned*)((const char*)(gbase) + _vo), (PG8_LAS unsigned*)(lds + (bufoff) + ldsw + _i * 8192), 16, 0, 0); } } while (0)
; #define PG8_LDA(dst, b, h) do { _Pragma("unroll") for (int m = 0; m < 4; ++m) _Pragma("unroll") for (int k = 0; k < 2; ++k) dst[m][k] = *(const PG8_LAS bf16x8*)(lds + PG8_SA(b, h) + aoff + m * 2048 + k * 1024); } while (0)
; #define PG8_LDB(dst, b, h) do { _Pragma("unroll") for (int n = 0; n < 2; ++n) _Pragma("unroll") for (int k = 0; k < 2; ++k) dst[n][k] = *(const PG8_LAS bf16x8*)(lds + PG8_SB(b, h) + boff + n * 2048 + k * 1024); } while (0)
; #define PG8_WAIT_V(n) asm volatile("s_waitcnt vmcnt(" #n ")" ::: "memory")
; #define PG8_WAIT_L(n) asm volatile("s_waitcnt lgkmcnt(" #n ")" ::: "memory")
; #define PG8_BAR __builtin_amdgcn_s_barrier()
; #define PG8_SCHED __builtin_amdgcn_sched_barrier(0)
; template <class Epi, class Sched, bool ALIGN_EPI = false, bool SP2 = false, bool ABLK = false, bool F8 = false>
; __device__ __forceinline__ void gemm_phase(PG8_LAS unsigned char* lds, const Gemm g, const Sched& S, const Epi& E, const int wave_s) {
;     ...
;             PG8_LDB(B0, 0, 0); PG8_LDB(B1, 0, 1); PG8_SCHED; PG8_LDA(At, 0, 0); PG8_STAGE(PG8_SA(1, 1), a1 + hstepA, voffA);
;             PG8_WAIT_V(8); PG8_WAIT_L(0); PG8_BAR; PG8_MMA(0, 0, At, B0); PG8_MMA(0, 1, At, B1); PG8_BAR; PG8_SCHED;
;             PG8_LDA(At, 0, 1); PG8_STAGE(PG8_SB(0, 0), b2, voffB); PG8_STAGE(PG8_SB(0, 1), b2 + hstep, voffB); PG8_STAGE(PG8_SA(0, 0), a2, voffA);
;             PG8_WAIT_V(8); PG8_WAIT_L(0); PG8_BAR; PG8_MMA(1, 0, At, B0); PG8_MMA(1, 1, At, B1); PG8_BAR; PG8_SCHED;
.LBB0_1010:
	ds_read_b128 v[64:67], v236
	ds_read_b128 v[68:71], v236 offset:1024
	ds_read_b128 v[88:91], v236 offset:2048
	ds_read_b128 v[92:95], v236 offset:3072
	ds_read_b128 v[112:115], v237
	ds_read_b128 v[116:119], v237 offset:1024
	ds_read_b128 v[136:139], v237 offset:2048
	ds_read_b128 v[140:143], v237 offset:3072
	s_add_u32 s52, s50, 0xfff80080
	s_addc_u32 s53, s51, -1
	s_cmp_eq_u32 s62, 28
	s_cselect_b32 s53, s41, s53
	s_cselect_b32 s52, s47, s52
	s_cselect_b32 s55, s13, s61
	s_cselect_b32 s54, s59, s60
	ds_read_b128 v[152:155], v238
	ds_read_b128 v[164:167], v238 offset:1024
	ds_read_b128 v[168:171], v238 offset:2048
	ds_read_b128 v[172:175], v238 offset:3072
	ds_read_b128 v[176:179], v238 offset:4096
	ds_read_b128 v[180:183], v238 offset:5120
	ds_read_b128 v[190:193], v238 offset:6144
	ds_read_b128 v[194:197], v238 offset:7168
	s_add_i32 m0, s20, 0xc000
	s_nop 0
	global_load_lds_dwordx4 v229, s[50:51]
	s_add_i32 m0, s20, 0xe000
	s_nop 0
	global_load_lds_dwordx4 v231, s[50:51]
	s_waitcnt vmcnt(8)
	s_waitcnt lgkmcnt(0)
	s_barrier
	s_setprio 1
	s_waitcnt lgkmcnt(0)
	v_mfma_f32_16x16x32_bf16 v[160:163], v[64:67], v[152:155], v[160:163]
	v_mfma_f32_16x16x32_bf16 v[156:159], v[88:91], v[152:155], v[156:159]
	v_mfma_f32_16x16x32_bf16 v[132:135], v[64:67], v[168:171], v[132:135]
	v_mfma_f32_16x16x32_bf16 v[128:131], v[88:91], v[168:171], v[128:131]
	v_mfma_f32_16x16x32_bf16 v[108:111], v[64:67], v[176:179], v[108:111]
	v_mfma_f32_16x16x32_bf16 v[104:107], v[88:91], v[176:179], v[104:107]
	v_mfma_f32_16x16x32_bf16 v[84:87], v[64:67], v[190:193], v[84:87]
	v_mfma_f32_16x16x32_bf16 v[80:83], v[88:91], v[190:193], v[80:83]
	v_mfma_f32_16x16x32_bf16 v[160:163], v[68:71], v[164:167], v[160:163]
	v_mfma_f32_16x16x32_bf16 v[156:159], v[92:95], v[164:167], v[156:159]
	v_mfma_f32_16x16x32_bf16 v[132:135], v[68:71], v[172:175], v[132:135]
	v_mfma_f32_16x16x32_bf16 v[128:131], v[92:95], v[172:175], v[128:131]
	v_mfma_f32_16x16x32_bf16 v[108:111], v[68:71], v[180:183], v[108:111]
	v_mfma_f32_16x16x32_bf16 v[104:107], v[92:95], v[180:183], v[104:107]
	v_mfma_f32_16x16x32_bf16 v[84:87], v[68:71], v[194:197], v[84:87]
	v_mfma_f32_16x16x32_bf16 v[80:83], v[92:95], v[194:197], v[80:83]
	v_mfma_f32_16x16x32_bf16 v[148:151], v[112:115], v[152:155], v[148:151]
	v_mfma_f32_16x16x32_bf16 v[144:147], v[136:139], v[152:155], v[144:147]
	v_mfma_f32_16x16x32_bf16 v[124:127], v[112:115], v[168:171], v[124:127]
	v_mfma_f32_16x16x32_bf16 v[120:123], v[136:139], v[168:171], v[120:123]
	v_mfma_f32_16x16x32_bf16 v[100:103], v[112:115], v[176:179], v[100:103]
	v_mfma_f32_16x16x32_bf16 v[96:99], v[136:139], v[176:179], v[96:99]
	v_mfma_f32_16x16x32_bf16 v[76:79], v[112:115], v[190:193], v[76:79]
	v_mfma_f32_16x16x32_bf16 v[72:75], v[136:139], v[190:193], v[72:75]
	v_mfma_f32_16x16x32_bf16 v[148:151], v[116:119], v[164:167], v[148:151]
	v_mfma_f32_16x16x32_bf16 v[144:147], v[140:143], v[164:167], v[144:147]
	v_mfma_f32_16x16x32_bf16 v[124:127], v[116:119], v[172:175], v[124:127]
	v_mfma_f32_16x16x32_bf16 v[120:123], v[140:143], v[172:175], v[120:123]
	v_mfma_f32_16x16x32_bf16 v[100:103], v[116:119], v[180:183], v[100:103]
	v_mfma_f32_16x16x32_bf16 v[96:99], v[140:143], v[180:183], v[96:99]
	v_mfma_f32_16x16x32_bf16 v[76:79], v[116:119], v[194:197], v[76:79]
	v_mfma_f32_16x16x32_bf16 v[72:75], v[140:143], v[194:197], v[72:75]
	s_setprio 0
	s_barrier
	s_add_i32 s63, s57, s3
	ds_read_b128 v[152:155], v238 offset:16384
	ds_read_b128 v[164:167], v238 offset:17408
	ds_read_b128 v[168:171], v238 offset:18432
	ds_read_b128 v[172:175], v238 offset:19456
	ds_read_b128 v[176:179], v238 offset:20480
	ds_read_b128 v[180:183], v238 offset:21504
	ds_read_b128 v[190:193], v238 offset:22528
	ds_read_b128 v[194:197], v238 offset:23552
	s_mov_b32 m0, s63
	s_nop 0
	global_load_lds_dwordx4 v230, s[54:55]
	s_add_i32 m0, s63, 0x2000
	s_add_u32 s64, s54, 0x80000
	global_load_lds_dwordx4 v232, s[54:55]
	s_addc_u32 s65, s55, 0
	s_add_i32 s63, s58, s3
	s_mov_b32 m0, s63
	s_nop 0
	global_load_lds_dwordx4 v230, s[64:65]
	s_add_i32 m0, s63, 0x2000
	s_nop 0
	global_load_lds_dwordx4 v232, s[64:65]
	s_mov_b32 m0, s20
	s_nop 0
	global_load_lds_dwordx4 v229, s[52:53]
	s_mov_b32 m0, s21
	s_nop 0
	global_load_lds_dwordx4 v231, s[52:53]
	s_waitcnt vmcnt(8)
	s_waitcnt lgkmcnt(0)
	s_barrier
	s_setprio 1
	s_waitcnt lgkmcnt(0)
	v_mfma_f32_16x16x32_bf16 v[60:63], v[64:67], v[152:155], v[60:63]
	v_mfma_f32_16x16x32_bf16 v[56:59], v[88:91], v[152:155], v[56:59]
	v_mfma_f32_16x16x32_bf16 v[44:47], v[64:67], v[168:171], v[44:47]
	v_mfma_f32_16x16x32_bf16 v[40:43], v[88:91], v[168:171], v[40:43]
	v_mfma_f32_16x16x32_bf16 v[28:31], v[64:67], v[176:179], v[28:31]
	v_mfma_f32_16x16x32_bf16 v[24:27], v[88:91], v[176:179], v[24:27]
	v_mfma_f32_16x16x32_bf16 v[12:15], v[64:67], v[190:193], v[12:15]
	v_mfma_f32_16x16x32_bf16 v[8:11], v[88:91], v[190:193], v[8:11]
	v_mfma_f32_16x16x32_bf16 v[60:63], v[68:71], v[164:167], v[60:63]
	v_mfma_f32_16x16x32_bf16 v[56:59], v[92:95], v[164:167], v[56:59]
	v_mfma_f32_16x16x32_bf16 v[44:47], v[68:71], v[172:175], v[44:47]
	v_mfma_f32_16x16x32_bf16 v[40:43], v[92:95], v[172:175], v[40:43]
	v_mfma_f32_16x16x32_bf16 v[28:31], v[68:71], v[180:183], v[28:31]
	v_mfma_f32_16x16x32_bf16 v[24:27], v[92:95], v[180:183], v[24:27]
	v_mfma_f32_16x16x32_bf16 v[12:15], v[68:71], v[194:197], v[12:15]
	v_mfma_f32_16x16x32_bf16 v[8:11], v[92:95], v[194:197], v[8:11]
	v_mfma_f32_16x16x32_bf16 v[52:55], v[112:115], v[152:155], v[52:55]
	v_mfma_f32_16x16x32_bf16 v[48:51], v[136:139], v[152:155], v[48:51]
	v_mfma_f32_16x16x32_bf16 v[36:39], v[112:115], v[168:171], v[36:39]
	v_mfma_f32_16x16x32_bf16 v[32:35], v[136:139], v[168:171], v[32:35]
	v_mfma_f32_16x16x32_bf16 v[20:23], v[112:115], v[176:179], v[20:23]
	v_mfma_f32_16x16x32_bf16 v[16:19], v[136:139], v[176:179], v[16:19]
	v_mfma_f32_16x16x32_bf16 v[4:7], v[112:115], v[190:193], v[4:7]
	v_mfma_f32_16x16x32_bf16 v[0:3], v[136:139], v[190:193], v[0:3]
	v_mfma_f32_16x16x32_bf16 v[52:55], v[116:119], v[164:167], v[52:55]
	v_mfma_f32_16x16x32_bf16 v[48:51], v[140:143], v[164:167], v[48:51]
	v_mfma_f32_16x16x32_bf16 v[36:39], v[116:119], v[172:175], v[36:39]
	v_mfma_f32_16x16x32_bf16 v[32:35], v[140:143], v[172:175], v[32:35]
	v_mfma_f32_16x16x32_bf16 v[20:23], v[116:119], v[180:183], v[20:23]
	v_mfma_f32_16x16x32_bf16 v[16:19], v[140:143], v[180:183], v[16:19]
	v_mfma_f32_16x16x32_bf16 v[4:7], v[116:119], v[194:197], v[4:7]
	v_mfma_f32_16x16x32_bf16 v[0:3], v[140:143], v[194:197], v[0:3]
	s_setprio 0
	s_barrier
; #define PG8_STAGE(bufoff, gbase, voff) do { _Pragma("unroll") for (int _i = 0; _i < 2; ++_i) \
;         { unsigned _vo = (voff)[_i]; asm volatile("" : "+v"(_vo));     \
;         __builtin_amdgcn_global_load_lds((const unsigned*)((const char*)(gbase) + _vo), (PG8_LAS unsigned*)(lds + (bufoff) + ldsw + _i * 8192), 16, 0, 0); } } while (0)
; #define PG8_LDA(dst, b, h) do { _Pragma("unroll") for (int m = 0; m < 4; ++m) _Pragma("unroll") for (int k = 0; k < 2; ++k) dst[m][k] = *(const PG8_LAS bf16x8*)(lds + PG8_SA(b, h) + aoff + m * 2048 + k * 1024); } while (0)
; #define PG8_LDB(dst, b, h) do { _Pragma("unroll") for (int n = 0; n < 2; ++n) _Pragma("unroll") for (int k = 0; k < 2; ++k) dst[n][k] = *(const PG8_LAS bf16x8*)(lds + PG8_SB(b, h) + boff + n * 2048 + k * 1024); } while (0)
; #define PG8_WAIT_V(n) asm volatile("s_waitcnt vmcnt(" #n ")" ::: "memory")
; #define PG8_WAIT_L(n) asm volatile("s_waitcnt lgkmcnt(" #n ")" ::: "memory")
; #define PG8_BAR __builtin_amdgcn_s_barrier()
; #define PG8_SCHED __builtin_amdgcn_sched_barrier(0)
; template <class Epi, class Sched, bool ALIGN_EPI = false, bool SP2 = false, bool ABLK = false, bool F8 = false>
; __device__ __forceinline__ void gemm_phase(PG8_LAS unsigned char* lds, const Gemm g, const Sched& S, const Epi& E, const int wave_s) {
;     ...
;             PG8_LDB(B0, 1, 0); PG8_LDB(B1, 1, 1); PG8_SCHED; PG8_LDA(At, 1, 0); PG8_STAGE(PG8_SA(0, 1), a2 + hstepA, voffA);
;             PG8_WAIT_V(8); PG8_WAIT_L(0); PG8_BAR; PG8_MMA(0, 0, At, B0); PG8_MMA(0, 1, At, B1); PG8_BAR; PG8_SCHED;
;             PG8_LDA(At, 1, 1); PG8_STAGE(PG8_SB(1, 0), b3, voffB); PG8_STAGE(PG8_SB(1, 1), b3 + hstep, voffB); PG8_STAGE(PG8_SA(1, 0), a3, voffA);
;             PG8_WAIT_V(8); PG8_WAIT_L(0); PG8_BAR; PG8_MMA(1, 0, At, B0); PG8_MMA(1, 1, At, B1); PG8_BAR; PG8_SCHED;
;     ...
;         if constexpr (ALIGN_EPI) { if (wr == 0) PG8_BAR; }
	s_add_i32 s63, 0, 0x18000
	s_add_i32 s66, 0, 0x1c000
	v_add_u32_e32 v92, s63, v234
	v_add_u32_e32 v140, s66, v234
	ds_read_b128 v[64:67], v92
	ds_read_b128 v[68:71], v92 offset:1024
	ds_read_b128 v[88:91], v92 offset:2048
	ds_read_b128 v[92:95], v92 offset:3072
	ds_read_b128 v[112:115], v140
	ds_read_b128 v[116:119], v140 offset:1024
	ds_read_b128 v[136:139], v140 offset:2048
	ds_read_b128 v[140:143], v140 offset:3072
	s_add_u32 s64, s52, 0x80000
	s_mov_b32 m0, s22
	ds_read_b128 v[152:155], v238 offset:32768
	ds_read_b128 v[164:167], v238 offset:33792
	ds_read_b128 v[168:171], v238 offset:34816
	ds_read_b128 v[172:175], v238 offset:35840
	ds_read_b128 v[176:179], v238 offset:36864
	ds_read_b128 v[180:183], v238 offset:37888
	ds_read_b128 v[190:193], v238 offset:38912
	ds_read_b128 v[194:197], v238 offset:39936
	s_addc_u32 s65, s53, 0
	s_nop 0
	global_load_lds_dwordx4 v229, s[64:65]
	s_mov_b32 m0, s23
	s_nop 0
	global_load_lds_dwordx4 v231, s[64:65]
	s_waitcnt vmcnt(8)
	s_waitcnt lgkmcnt(0)
	s_barrier
	s_setprio 1
	s_waitcnt lgkmcnt(0)
	v_mfma_f32_16x16x32_bf16 v[160:163], v[64:67], v[152:155], v[160:163]
	v_mfma_f32_16x16x32_bf16 v[156:159], v[88:91], v[152:155], v[156:159]
	v_mfma_f32_16x16x32_bf16 v[132:135], v[64:67], v[168:171], v[132:135]
	v_mfma_f32_16x16x32_bf16 v[128:131], v[88:91], v[168:171], v[128:131]
	v_mfma_f32_16x16x32_bf16 v[108:111], v[64:67], v[176:179], v[108:111]
	v_mfma_f32_16x16x32_bf16 v[104:107], v[88:91], v[176:179], v[104:107]
	v_mfma_f32_16x16x32_bf16 v[84:87], v[64:67], v[190:193], v[84:87]
	v_mfma_f32_16x16x32_bf16 v[80:83], v[88:91], v[190:193], v[80:83]
	v_mfma_f32_16x16x32_bf16 v[160:163], v[68:71], v[164:167], v[160:163]
	v_mfma_f32_16x16x32_bf16 v[156:159], v[92:95], v[164:167], v[156:159]
	v_mfma_f32_16x16x32_bf16 v[132:135], v[68:71], v[172:175], v[132:135]
	v_mfma_f32_16x16x32_bf16 v[128:131], v[92:95], v[172:175], v[128:131]
	v_mfma_f32_16x16x32_bf16 v[108:111], v[68:71], v[180:183], v[108:111]
	v_mfma_f32_16x16x32_bf16 v[104:107], v[92:95], v[180:183], v[104:107]
	v_mfma_f32_16x16x32_bf16 v[84:87], v[68:71], v[194:197], v[84:87]
	v_mfma_f32_16x16x32_bf16 v[80:83], v[92:95], v[194:197], v[80:83]
	v_mfma_f32_16x16x32_bf16 v[148:151], v[112:115], v[152:155], v[148:151]
	v_mfma_f32_16x16x32_bf16 v[144:147], v[136:139], v[152:155], v[144:147]
	v_mfma_f32_16x16x32_bf16 v[124:127], v[112:115], v[168:171], v[124:127]
	v_mfma_f32_16x16x32_bf16 v[120:123], v[136:139], v[168:171], v[120:123]
	v_mfma_f32_16x16x32_bf16 v[100:103], v[112:115], v[176:179], v[100:103]
	v_mfma_f32_16x16x32_bf16 v[96:99], v[136:139], v[176:179], v[96:99]
	v_mfma_f32_16x16x32_bf16 v[76:79], v[112:115], v[190:193], v[76:79]
	v_mfma_f32_16x16x32_bf16 v[72:75], v[136:139], v[190:193], v[72:75]
	v_mfma_f32_16x16x32_bf16 v[148:151], v[116:119], v[164:167], v[148:151]
	v_mfma_f32_16x16x32_bf16 v[144:147], v[140:143], v[164:167], v[144:147]
	v_mfma_f32_16x16x32_bf16 v[124:127], v[116:119], v[172:175], v[124:127]
	v_mfma_f32_16x16x32_bf16 v[120:123], v[140:143], v[172:175], v[120:123]
	v_mfma_f32_16x16x32_bf16 v[100:103], v[116:119], v[180:183], v[100:103]
	v_mfma_f32_16x16x32_bf16 v[96:99], v[140:143], v[180:183], v[96:99]
	v_mfma_f32_16x16x32_bf16 v[76:79], v[116:119], v[194:197], v[76:79]
	v_mfma_f32_16x16x32_bf16 v[72:75], v[140:143], v[194:197], v[72:75]
	s_setprio 0
	s_barrier
	ds_read_b128 v[152:155], v238 offset:49152
	ds_read_b128 v[164:167], v238 offset:50176
	ds_read_b128 v[168:171], v238 offset:51200
	ds_read_b128 v[172:175], v238 offset:52224
	ds_read_b128 v[176:179], v238 offset:53248
	ds_read_b128 v[180:183], v238 offset:54272
	ds_read_b128 v[190:193], v238 offset:55296
	ds_read_b128 v[194:197], v238 offset:56320
	s_add_i32 s63, s63, s3
	s_add_u32 vcc_lo, s54, s10
	s_addc_u32 vcc_hi, s55, s11
	s_mov_b32 m0, s63
	s_nop 0
	global_load_lds_dwordx4 v230, vcc
	s_add_i32 m0, s63, 0x2000
	s_nop 0
	s_add_u32 vcc_lo, s54, s10
	s_addc_u32 vcc_hi, s55, s11
	s_add_u32 s54, s54, 0x80080
	s_addc_u32 s55, s55, 0
	s_add_i32 s63, s66, s3
	global_load_lds_dwordx4 v232, vcc
	s_mov_b32 m0, s63
	s_nop 0
	global_load_lds_dwordx4 v230, s[54:55]
	s_add_i32 m0, s63, 0x2000
	s_nop 0
	global_load_lds_dwordx4 v232, s[54:55]
	s_mov_b32 m0, s49
	s_add_u32 vcc_lo, s52, s10
	s_addc_u32 vcc_hi, s53, s11
	v_mov_b32_e32 v184, v231
	global_load_lds_dwordx4 v229, vcc
	s_mov_b32 m0, s56
	s_add_u32 vcc_lo, s52, s10
	s_addc_u32 vcc_hi, s53, s11
	global_load_lds_dwordx4 v231, vcc
	s_waitcnt vmcnt(8)
	s_waitcnt lgkmcnt(0)
	s_barrier
	s_setprio 1
	s_waitcnt lgkmcnt(0)
	v_mfma_f32_16x16x32_bf16 v[60:63], v[64:67], v[152:155], v[60:63]
	v_mfma_f32_16x16x32_bf16 v[56:59], v[88:91], v[152:155], v[56:59]
	v_mfma_f32_16x16x32_bf16 v[44:47], v[64:67], v[168:171], v[44:47]
	v_mfma_f32_16x16x32_bf16 v[40:43], v[88:91], v[168:171], v[40:43]
	v_mfma_f32_16x16x32_bf16 v[28:31], v[64:67], v[176:179], v[28:31]
	v_mfma_f32_16x16x32_bf16 v[24:27], v[88:91], v[176:179], v[24:27]
	v_mfma_f32_16x16x32_bf16 v[12:15], v[64:67], v[190:193], v[12:15]
	v_mfma_f32_16x16x32_bf16 v[8:11], v[88:91], v[190:193], v[8:11]
	v_mfma_f32_16x16x32_bf16 v[60:63], v[68:71], v[164:167], v[60:63]
	v_mfma_f32_16x16x32_bf16 v[56:59], v[92:95], v[164:167], v[56:59]
	v_mfma_f32_16x16x32_bf16 v[44:47], v[68:71], v[172:175], v[44:47]
	v_mfma_f32_16x16x32_bf16 v[40:43], v[92:95], v[172:175], v[40:43]
	v_mfma_f32_16x16x32_bf16 v[28:31], v[68:71], v[180:183], v[28:31]
	v_mfma_f32_16x16x32_bf16 v[24:27], v[92:95], v[180:183], v[24:27]
	v_mfma_f32_16x16x32_bf16 v[12:15], v[68:71], v[194:197], v[12:15]
	v_mfma_f32_16x16x32_bf16 v[8:11], v[92:95], v[194:197], v[8:11]
	v_mfma_f32_16x16x32_bf16 v[52:55], v[112:115], v[152:155], v[52:55]
	v_mfma_f32_16x16x32_bf16 v[48:51], v[136:139], v[152:155], v[48:51]
	v_mfma_f32_16x16x32_bf16 v[36:39], v[112:115], v[168:171], v[36:39]
	v_mfma_f32_16x16x32_bf16 v[32:35], v[136:139], v[168:171], v[32:35]
	v_mfma_f32_16x16x32_bf16 v[20:23], v[112:115], v[176:179], v[20:23]
	v_mfma_f32_16x16x32_bf16 v[16:19], v[136:139], v[176:179], v[16:19]
	v_mfma_f32_16x16x32_bf16 v[4:7], v[112:115], v[190:193], v[4:7]
	v_mfma_f32_16x16x32_bf16 v[0:3], v[136:139], v[190:193], v[0:3]
	v_mfma_f32_16x16x32_bf16 v[52:55], v[116:119], v[164:167], v[52:55]
	v_mfma_f32_16x16x32_bf16 v[48:51], v[140:143], v[164:167], v[48:51]
	v_mfma_f32_16x16x32_bf16 v[36:39], v[116:119], v[172:175], v[36:39]
	v_mfma_f32_16x16x32_bf16 v[32:35], v[140:143], v[172:175], v[32:35]
	v_mfma_f32_16x16x32_bf16 v[20:23], v[116:119], v[180:183], v[20:23]
	v_mfma_f32_16x16x32_bf16 v[16:19], v[140:143], v[180:183], v[16:19]
	v_mfma_f32_16x16x32_bf16 v[4:7], v[116:119], v[194:197], v[4:7]
	v_mfma_f32_16x16x32_bf16 v[0:3], v[140:143], v[194:197], v[0:3]
	s_setprio 0
	s_barrier
	s_add_i32 s62, s62, 2
	s_add_u32 s50, s50, 0x100
	s_addc_u32 s51, s51, 0
	s_add_u32 s60, s60, 0x100
	s_addc_u32 s61, s61, 0
	s_cmp_gt_u32 s62, 29
	s_cbranch_scc0 .LBB0_1010
	s_and_b64 vcc, exec, s[36:37]
	s_cbranch_vccz .LBB0_1013
	s_barrier
